# score R-merge (exact, med3 fast path + check + compare-exchange fallback): row-0 tie pass without moves
# speedup vs baseline: 1.0028x; 1.0014x over previous
; DEV f32x4 mfma16(bf16x8 a, bf16x8 b, f32x4 c) { return __builtin_amdgcn_mfma_f32_16x16x32_bf16(a, b, c, 0, 0, 0); }
; DEV void peer_top16(const bf16_t* __restrict__ pq, const bf16_t* sk  , float (&l)[16]) {
;     ...
; #pragma unroll 1
;   for (int ks = 0; ks < 4; ks++) {
;     const bf16x8 bqk = *(const bf16x8*)(pq + ks * 32 + quad * 8);
; #pragma unroll
;     for (int nt = 0; nt < 8; nt++) {
;       bf16x8 ak = *(const bf16x8*)(sk + (nt * 16 + l15) * 144 + ks * 32 + quad * 8);
;       acc[nt] = mfma16(ak, bqk, acc[nt]);
;     }
;   }
.LBB0_170:
	v_add_u32_e32 v139, 0x10e00, v122
	ds_read_b128 v[164:167], v122 offset:36864
	ds_read_b128 v[168:171], v122 offset:41472
	ds_read_b128 v[172:175], v122 offset:46080
	ds_read_b128 v[176:179], v122 offset:50688
	ds_read_b128 v[180:183], v122 offset:55296
	ds_read_b128 v[184:187], v122 offset:59904
	ds_read_b128 v[188:191], v122 offset:64512
	ds_read_b128 v[128:131], v139
	s_waitcnt vmcnt(3) lgkmcnt(7)
	v_mfma_f32_16x16x32_bf16 v[30:33], v[164:167], v[148:151], v[30:33]
	ds_read_b128 v[164:167], v122 offset:36928
	s_waitcnt lgkmcnt(7)
	v_mfma_f32_16x16x32_bf16 v[22:25], v[168:171], v[148:151], v[22:25]
	ds_read_b128 v[168:171], v122 offset:41536
	s_waitcnt lgkmcnt(7)
	v_mfma_f32_16x16x32_bf16 v[14:17], v[172:175], v[148:151], v[14:17]
	ds_read_b128 v[172:175], v122 offset:46144
	s_waitcnt lgkmcnt(7)
	v_mfma_f32_16x16x32_bf16 v[6:9], v[176:179], v[148:151], v[6:9]
	ds_read_b128 v[176:179], v122 offset:50752
	s_waitcnt lgkmcnt(7)
	v_mfma_f32_16x16x32_bf16 v[26:29], v[180:183], v[148:151], v[26:29]
	ds_read_b128 v[180:183], v122 offset:55360
	s_waitcnt lgkmcnt(7)
	v_mfma_f32_16x16x32_bf16 v[18:21], v[184:187], v[148:151], v[18:21]
	ds_read_b128 v[184:187], v122 offset:59968
	s_waitcnt lgkmcnt(7)
	v_mfma_f32_16x16x32_bf16 v[10:13], v[188:191], v[148:151], v[10:13]
	ds_read_b128 v[188:191], v122 offset:64576
	s_waitcnt lgkmcnt(7)
	v_mfma_f32_16x16x32_bf16 v[2:5], v[128:131], v[148:151], v[2:5]
	ds_read_b128 v[128:131], v139 offset:64
	s_waitcnt vmcnt(2) lgkmcnt(7)
	v_mfma_f32_16x16x32_bf16 v[30:33], v[164:167], v[152:155], v[30:33]
	ds_read_b128 v[164:167], v122 offset:36992
	s_waitcnt lgkmcnt(7)
	v_mfma_f32_16x16x32_bf16 v[22:25], v[168:171], v[152:155], v[22:25]
	ds_read_b128 v[168:171], v122 offset:41600
	s_waitcnt lgkmcnt(7)
	v_mfma_f32_16x16x32_bf16 v[14:17], v[172:175], v[152:155], v[14:17]
	ds_read_b128 v[172:175], v122 offset:46208
	s_waitcnt lgkmcnt(7)
	v_mfma_f32_16x16x32_bf16 v[6:9], v[176:179], v[152:155], v[6:9]
	ds_read_b128 v[176:179], v122 offset:50816
	s_waitcnt lgkmcnt(7)
	v_mfma_f32_16x16x32_bf16 v[26:29], v[180:183], v[152:155], v[26:29]
	ds_read_b128 v[180:183], v122 offset:55424
	s_waitcnt lgkmcnt(7)
	v_mfma_f32_16x16x32_bf16 v[18:21], v[184:187], v[152:155], v[18:21]
	ds_read_b128 v[184:187], v122 offset:60032
	s_waitcnt lgkmcnt(7)
	v_mfma_f32_16x16x32_bf16 v[10:13], v[188:191], v[152:155], v[10:13]
	ds_read_b128 v[188:191], v122 offset:64640
	s_waitcnt lgkmcnt(7)
	v_mfma_f32_16x16x32_bf16 v[2:5], v[128:131], v[152:155], v[2:5]
	ds_read_b128 v[128:131], v139 offset:128
	s_waitcnt vmcnt(1) lgkmcnt(7)
	v_mfma_f32_16x16x32_bf16 v[30:33], v[164:167], v[156:159], v[30:33]
	ds_read_b128 v[164:167], v122 offset:37056
	s_waitcnt lgkmcnt(7)
	v_mfma_f32_16x16x32_bf16 v[22:25], v[168:171], v[156:159], v[22:25]
	ds_read_b128 v[168:171], v122 offset:41664
	s_waitcnt lgkmcnt(7)
	v_mfma_f32_16x16x32_bf16 v[14:17], v[172:175], v[156:159], v[14:17]
	ds_read_b128 v[172:175], v122 offset:46272
	s_waitcnt lgkmcnt(7)
	v_mfma_f32_16x16x32_bf16 v[6:9], v[176:179], v[156:159], v[6:9]
	ds_read_b128 v[176:179], v122 offset:50880
	s_waitcnt lgkmcnt(7)
	v_mfma_f32_16x16x32_bf16 v[26:29], v[180:183], v[156:159], v[26:29]
	ds_read_b128 v[180:183], v122 offset:55488
	s_waitcnt lgkmcnt(7)
	v_mfma_f32_16x16x32_bf16 v[18:21], v[184:187], v[156:159], v[18:21]
	ds_read_b128 v[184:187], v122 offset:60096
	s_waitcnt lgkmcnt(7)
	v_mfma_f32_16x16x32_bf16 v[10:13], v[188:191], v[156:159], v[10:13]
	ds_read_b128 v[188:191], v122 offset:64704
	s_waitcnt lgkmcnt(7)
	v_mfma_f32_16x16x32_bf16 v[2:5], v[128:131], v[156:159], v[2:5]
	ds_read_b128 v[128:131], v139 offset:192
	s_waitcnt vmcnt(0) lgkmcnt(7)
	v_mfma_f32_16x16x32_bf16 v[30:33], v[164:167], v[160:163], v[30:33]
	s_waitcnt lgkmcnt(6)
	v_mfma_f32_16x16x32_bf16 v[22:25], v[168:171], v[160:163], v[22:25]
	s_waitcnt lgkmcnt(5)
	v_mfma_f32_16x16x32_bf16 v[14:17], v[172:175], v[160:163], v[14:17]
	s_waitcnt lgkmcnt(4)
	v_mfma_f32_16x16x32_bf16 v[6:9], v[176:179], v[160:163], v[6:9]
	s_waitcnt lgkmcnt(3)
	v_mfma_f32_16x16x32_bf16 v[26:29], v[180:183], v[160:163], v[26:29]
	s_waitcnt lgkmcnt(2)
	v_mfma_f32_16x16x32_bf16 v[18:21], v[184:187], v[160:163], v[18:21]
	s_waitcnt lgkmcnt(1)
	v_mfma_f32_16x16x32_bf16 v[10:13], v[188:191], v[160:163], v[10:13]
	s_waitcnt lgkmcnt(0)
; DEV void ce(float& a, float& b) { float hi = fmaxf(a, b), lo = fminf(a, b); a = hi; b = lo; }
; DEV void bitonic16(float (&l)[16]) {
; #pragma unroll
;   for (int s = 8; s > 0; s >>= 1)
; #pragma unroll
;     for (int i = 0; i < 16; i++)
;       if (!(i & s)) ce(l[i], l[i + s]);
; }
; DEV void peer_top16(const bf16_t* __restrict__ pq, const bf16_t* sk  , float (&l)[16]) {
;     ...
;   float hi[16];
; #pragma unroll
;   for (int nt = 0; nt < 4; nt++)
; #pragma unroll
;     for (int r = 0; r < 4; r++) {
;       l[nt * 4 + r] = __uint_as_float((__float_as_uint(acc[nt][r]) & ~127u) | (unsigned)(nt * 16 + quad * 4 + r));
;       hi[nt * 4 + r] = __uint_as_float((__float_as_uint(acc[nt + 4][r]) & ~127u) | (unsigned)((nt + 4) * 16 + quad * 4 + r));
;     }
;   sort16_desc(l);
;   sort16_desc(hi);
; #pragma unroll
;   for (int i = 0; i < 16; i++) l[i] = fmaxf(l[i], hi[15 - i]);
;   bitonic16(l);
;   merge_xor(l, 16);
;   merge_xor(l, 32);
	v_mfma_f32_16x16x32_bf16 v[2:5], v[128:131], v[160:163], v[2:5]
	s_movk_i32 s0, 0x100
	v_max_f32_e32 v0, v109, v121
	v_max_f32_e32 v100, v107, v120
	v_max_f32_e32 v101, v105, v119
	v_max_f32_e32 v103, v103, v118
	v_max_f32_e32 v87, v87, v116
	v_max_f32_e32 v79, v79, v115
	v_max_f32_e32 v75, v75, v114
	v_max_f32_e32 v71, v71, v113
	v_max_f32_e32 v67, v67, v112
	v_max_f32_e32 v63, v63, v111
	v_max_f32_e32 v59, v59, v110
	v_max_f32_e32 v55, v55, v108
	v_max_f32_e32 v51, v51, v106
	v_max_f32_e32 v47, v47, v104
	v_max_f32_e32 v43, v43, v91
	v_max_f32_e32 v39, v39, v83
	v_max_f32_e32 v83, v0, v67
	v_min_f32_e32 v0, v0, v67
	v_max_f32_e32 v67, v100, v63
	v_min_f32_e32 v63, v100, v63
	v_max_f32_e32 v91, v101, v59
	v_min_f32_e32 v59, v101, v59
	v_max_f32_e32 v100, v103, v55
	v_min_f32_e32 v55, v103, v55
	v_max_f32_e32 v101, v87, v51
	v_min_f32_e32 v51, v87, v51
	v_max_f32_e32 v87, v79, v47
	v_min_f32_e32 v47, v79, v47
	v_max_f32_e32 v79, v75, v43
	v_min_f32_e32 v43, v75, v43
	v_max_f32_e32 v75, v71, v39
	v_min_f32_e32 v39, v71, v39
	v_max_f32_e32 v71, v83, v101
	v_min_f32_e32 v101, v83, v101
	v_max_f32_e32 v103, v67, v87
	v_min_f32_e32 v67, v67, v87
	v_max_f32_e32 v87, v91, v79
	v_min_f32_e32 v79, v91, v79
	v_max_f32_e32 v91, v100, v75
	v_min_f32_e32 v75, v100, v75
	v_max_f32_e32 v100, v0, v51
	v_min_f32_e32 v0, v0, v51
	v_max_f32_e32 v51, v63, v47
	v_max_f32_e32 v105, v59, v43
	v_min_f32_e32 v43, v59, v43
	v_max_f32_e32 v59, v55, v39
	v_min_f32_e32 v107, v101, v79
	v_min_f32_e32 v108, v67, v75
	v_min_f32_e32 v110, v51, v59
	v_max_f32_e32 v79, v101, v79
	v_max_f32_e32 v67, v67, v75
	v_max_f32_e32 v101, v100, v105
	v_max_f32_e32 v51, v51, v59
	v_min_f32_e32 v75, v79, v67
	v_min_f32_e32 v59, v101, v51
	v_max_f32_e32 v79, v79, v67
	v_max_f32_e32 v67, v101, v51
	v_lshlrev_b32_e32 v101, 2, v102
	s_movk_i32 s0, 0xff80
	v_and_or_b32 v30, v30, s0, v101
	v_and_b32_e32 v27, 0xffffff80, v27
	s_movk_i32 s0, 0x41
	v_or3_b32 v27, v101, v27, s0
	v_and_b32_e32 v28, 0xffffff80, v28
	s_movk_i32 s0, 0x42
	v_or3_b32 v28, v101, v28, s0
	v_and_b32_e32 v29, 0xffffff80, v29
	s_movk_i32 s0, 0x43
	v_or3_b32 v29, v101, v29, s0
	v_and_b32_e32 v18, 0xffffff80, v18
	s_movk_i32 s0, 0x50
	v_or3_b32 v18, v101, v18, s0
	v_and_b32_e32 v19, 0xffffff80, v19
	s_movk_i32 s0, 0x51
	v_or3_b32 v19, v101, v19, s0
	v_and_b32_e32 v20, 0xffffff80, v20
	s_movk_i32 s0, 0x52
	v_or3_b32 v20, v101, v20, s0
	v_and_b32_e32 v21, 0xffffff80, v21
	s_movk_i32 s0, 0x53
	v_or3_b32 v21, v101, v21, s0
	v_and_b32_e32 v10, 0xffffff80, v10
	s_movk_i32 s0, 0x60
	v_or3_b32 v10, v101, v10, s0
	v_and_b32_e32 v11, 0xffffff80, v11
	s_movk_i32 s0, 0x61
	v_or3_b32 v11, v101, v11, s0
	v_and_b32_e32 v12, 0xffffff80, v12
	s_movk_i32 s0, 0x62
	v_or3_b32 v12, v101, v12, s0
	v_and_b32_e32 v13, 0xffffff80, v13
	s_movk_i32 s0, 0x63
	v_or3_b32 v13, v101, v13, s0
	v_and_b32_e32 v2, 0xffffff80, v2
	s_movk_i32 s0, 0x70
	v_and_b32_e32 v26, 0xffffff80, v26
	v_and_b32_e32 v31, 0xffffff80, v31
	v_or3_b32 v2, v101, v2, s0
	v_and_b32_e32 v3, 0xffffff80, v3
	s_movk_i32 s0, 0x71
	v_or3_b32 v26, v101, v26, 64
	v_or3_b32 v31, v101, v31, 1
	v_and_b32_e32 v32, 0xffffff80, v32
	v_and_b32_e32 v33, 0xffffff80, v33
	v_and_b32_e32 v22, 0xffffff80, v22
	v_and_b32_e32 v23, 0xffffff80, v23
	v_or3_b32 v3, v101, v3, s0
	v_and_b32_e32 v4, 0xffffff80, v4
	s_movk_i32 s0, 0x72
	v_min_f32_e32 v39, v55, v39
	v_min_f32_e32 v55, v71, v87
	v_min_f32_e32 v106, v103, v91
	v_min_f32_e32 v109, v100, v105
	v_max_f32_e32 v71, v71, v87
	v_max_f32_e32 v87, v103, v91
	v_or3_b32 v32, v101, v32, 2
	v_or3_b32 v33, v101, v33, 3
	v_or3_b32 v22, v101, v22, 16
	v_or3_b32 v23, v101, v23, 17
	v_and_b32_e32 v24, 0xffffff80, v24
	v_and_b32_e32 v25, 0xffffff80, v25
	v_and_b32_e32 v14, 0xffffff80, v14
	v_and_b32_e32 v15, 0xffffff80, v15
	v_and_b32_e32 v16, 0xffffff80, v16
	v_and_b32_e32 v17, 0xffffff80, v17
	v_and_b32_e32 v6, 0xffffff80, v6
	v_and_b32_e32 v7, 0xffffff80, v7
	v_and_b32_e32 v8, 0xffffff80, v8
	v_or3_b32 v4, v101, v4, s0
	v_and_b32_e32 v9, 0xffffff80, v9
	v_and_b32_e32 v5, 0xffffff80, v5
	s_movk_i32 s0, 0x73
	v_min_f32_e32 v104, v63, v47
	v_min_f32_e32 v83, v55, v106
	v_min_f32_e32 v47, v109, v110
	v_min_f32_e32 v91, v71, v87
	v_max_f32_e32 v100, v71, v87
	v_max_f32_e32 v87, v55, v106
	v_max_f32_e32 v55, v109, v110
	v_or3_b32 v24, v101, v24, 18
	v_or3_b32 v25, v101, v25, 19
	v_or3_b32 v14, v101, v14, 32
	v_or3_b32 v15, v101, v15, 33
	v_or3_b32 v16, v101, v16, 34
	v_or3_b32 v17, v101, v17, 35
	v_or3_b32 v6, v101, v6, 48
	v_or3_b32 v7, v101, v7, 49
	v_or3_b32 v8, v101, v8, 50
	v_or3_b32 v9, v101, v9, 51
	v_or3_b32 v5, v101, v5, s0
	v_max_f32_e32 v101, v30, v31
	v_min_f32_e32 v30, v30, v31
	v_max_f32_e32 v31, v32, v32
	v_max_f32_e32 v32, v33, v33
	v_max_f32_e32 v109, v26, v27
	v_min_f32_e32 v26, v26, v27
	v_max_f32_e32 v27, v28, v28
	v_max_f32_e32 v28, v29, v29
	v_max_f32_e32 v33, v32, v31
	v_min_f32_e32 v31, v32, v31
	v_max_f32_e32 v32, v22, v23
	v_min_f32_e32 v22, v22, v23
	v_max_f32_e32 v23, v24, v24
	v_max_f32_e32 v24, v25, v25
	v_max_f32_e32 v29, v28, v27
	v_min_f32_e32 v27, v28, v27
	v_max_f32_e32 v28, v18, v19
	v_min_f32_e32 v18, v18, v19
	v_max_f32_e32 v19, v20, v20
	v_max_f32_e32 v20, v21, v21
	v_max_f32_e32 v25, v24, v23
	v_min_f32_e32 v23, v24, v23
	v_max_f32_e32 v24, v14, v15
	v_min_f32_e32 v14, v14, v15
	v_max_f32_e32 v15, v16, v16
	v_max_f32_e32 v16, v17, v17
	v_max_f32_e32 v21, v20, v19
	v_min_f32_e32 v19, v20, v19
	v_max_f32_e32 v20, v10, v11
	v_min_f32_e32 v10, v10, v11
	v_max_f32_e32 v11, v12, v12
	v_max_f32_e32 v12, v13, v13
	v_max_f32_e32 v17, v16, v15
	v_min_f32_e32 v15, v16, v15
	v_max_f32_e32 v16, v6, v7
	v_min_f32_e32 v6, v6, v7
; DEV void ce(float& a, float& b) { float hi = fmaxf(a, b), lo = fminf(a, b); a = hi; b = lo; }
; DEV void sort16_desc(float (&a)[16]) {
; #pragma unroll
;   for (int k = 2; k <= 16; k <<= 1)
; #pragma unroll
;     for (int j = k >> 1; j > 0; j >>= 1)
; #pragma unroll
;       for (int i = 0; i < 16; i++) {
;         const int p = i ^ j;
;         if (p > i) { if ((i & k) == 0) ce(a[i], a[p]); else ce(a[p], a[i]); }
;       }
; }
	v_max_f32_e32 v7, v8, v8
	v_max_f32_e32 v8, v9, v9
	v_max_f32_e32 v13, v12, v11
	v_min_f32_e32 v11, v12, v11
	v_max_f32_e32 v12, v2, v3
	v_min_f32_e32 v2, v2, v3
	v_max_f32_e32 v3, v4, v4
	v_max_f32_e32 v4, v5, v5
	v_max_f32_e32 v9, v8, v7
	v_min_f32_e32 v7, v8, v7
	v_max_f32_e32 v5, v4, v3
	v_min_f32_e32 v3, v4, v3
	v_max_f32_e32 v8, v101, v31
	v_min_f32_e32 v31, v101, v31
	v_max_f32_e32 v101, v30, v33
	v_min_f32_e32 v30, v30, v33
	v_max_f32_e32 v33, v23, v32
	v_min_f32_e32 v23, v23, v32
	v_max_f32_e32 v32, v25, v22
	v_min_f32_e32 v22, v25, v22
	v_max_f32_e32 v25, v24, v15
	v_min_f32_e32 v15, v24, v15
	v_max_f32_e32 v24, v14, v17
	v_min_f32_e32 v14, v14, v17
	v_max_f32_e32 v17, v7, v16
	v_min_f32_e32 v7, v7, v16
	v_max_f32_e32 v16, v9, v6
	v_min_f32_e32 v6, v9, v6
	v_max_f32_e32 v4, v109, v27
	v_min_f32_e32 v27, v109, v27
	v_max_f32_e32 v109, v26, v29
	v_min_f32_e32 v26, v26, v29
	v_max_f32_e32 v29, v19, v28
	v_min_f32_e32 v19, v19, v28
	v_max_f32_e32 v28, v21, v18
	v_min_f32_e32 v18, v21, v18
	v_max_f32_e32 v21, v20, v11
	v_min_f32_e32 v11, v20, v11
	v_max_f32_e32 v20, v10, v13
	v_min_f32_e32 v10, v10, v13
	v_max_f32_e32 v13, v3, v12
	v_min_f32_e32 v3, v3, v12
	v_max_f32_e32 v12, v5, v2
	v_min_f32_e32 v2, v5, v2
	v_max_f32_e32 v9, v8, v101
	v_min_f32_e32 v8, v8, v101
	v_max_f32_e32 v101, v31, v30
	v_min_f32_e32 v30, v31, v30
	v_max_f32_e32 v31, v22, v23
	v_min_f32_e32 v22, v22, v23
	v_max_f32_e32 v23, v32, v33
	v_min_f32_e32 v32, v32, v33
	v_max_f32_e32 v33, v25, v24
	v_min_f32_e32 v24, v25, v24
	v_max_f32_e32 v25, v15, v14
	v_min_f32_e32 v14, v15, v14
	v_max_f32_e32 v15, v6, v7
	v_min_f32_e32 v6, v6, v7
	v_max_f32_e32 v7, v16, v17
	v_min_f32_e32 v16, v16, v17
	v_max_f32_e32 v5, v4, v109
	v_min_f32_e32 v4, v4, v109
	v_max_f32_e32 v109, v27, v26
	v_min_f32_e32 v26, v27, v26
	v_max_f32_e32 v27, v18, v19
	v_min_f32_e32 v18, v18, v19
	v_max_f32_e32 v19, v28, v29
	v_min_f32_e32 v28, v28, v29
	v_max_f32_e32 v29, v21, v20
	v_min_f32_e32 v20, v21, v20
	v_max_f32_e32 v21, v11, v10
	v_min_f32_e32 v10, v11, v10
	v_max_f32_e32 v11, v2, v3
	v_min_f32_e32 v2, v2, v3
	v_max_f32_e32 v3, v12, v13
	v_min_f32_e32 v12, v12, v13
	v_max_f32_e32 v17, v9, v22
	v_min_f32_e32 v9, v9, v22
	v_max_f32_e32 v22, v8, v31
	v_min_f32_e32 v8, v8, v31
	v_max_f32_e32 v31, v101, v32
	v_min_f32_e32 v32, v101, v32
	v_max_f32_e32 v101, v30, v23
	v_min_f32_e32 v23, v30, v23
	v_max_f32_e32 v30, v6, v33
	v_min_f32_e32 v6, v6, v33
	v_max_f32_e32 v33, v15, v24
	v_min_f32_e32 v15, v15, v24
	v_max_f32_e32 v24, v16, v25
	v_min_f32_e32 v16, v16, v25
	v_max_f32_e32 v25, v7, v14
	v_min_f32_e32 v7, v7, v14
	v_max_f32_e32 v13, v5, v18
	v_min_f32_e32 v5, v5, v18
	v_max_f32_e32 v18, v4, v27
	v_min_f32_e32 v4, v4, v27
	v_max_f32_e32 v27, v109, v28
	v_min_f32_e32 v28, v109, v28
	v_max_f32_e32 v109, v26, v19
	v_min_f32_e32 v19, v26, v19
	v_max_f32_e32 v26, v2, v29
	v_min_f32_e32 v2, v2, v29
	v_max_f32_e32 v29, v11, v20
	v_min_f32_e32 v11, v11, v20
	v_max_f32_e32 v20, v12, v21
	v_min_f32_e32 v12, v12, v21
	v_max_f32_e32 v21, v3, v10
	v_min_f32_e32 v3, v3, v10
	v_max_f32_e32 v14, v17, v31
	v_min_f32_e32 v17, v17, v31
	v_max_f32_e32 v31, v22, v101
	v_min_f32_e32 v22, v22, v101
	v_max_f32_e32 v101, v9, v32
	v_min_f32_e32 v9, v9, v32
	v_max_f32_e32 v32, v8, v23
	v_min_f32_e32 v8, v8, v23
	v_max_f32_e32 v23, v16, v6
	v_min_f32_e32 v6, v16, v6
	v_max_f32_e32 v16, v7, v15
	v_min_f32_e32 v7, v7, v15
	v_max_f32_e32 v15, v24, v30
	v_min_f32_e32 v24, v24, v30
	v_max_f32_e32 v30, v25, v33
	v_min_f32_e32 v25, v25, v33
	v_max_f32_e32 v10, v13, v27
	v_min_f32_e32 v13, v13, v27
	v_max_f32_e32 v27, v18, v109
	v_min_f32_e32 v18, v18, v109
	v_max_f32_e32 v109, v5, v28
	v_min_f32_e32 v5, v5, v28
	v_max_f32_e32 v28, v4, v19
	v_min_f32_e32 v4, v4, v19
	v_max_f32_e32 v19, v12, v2
	v_min_f32_e32 v2, v12, v2
	v_max_f32_e32 v12, v3, v11
	v_min_f32_e32 v3, v3, v11
	v_max_f32_e32 v11, v20, v26
	v_min_f32_e32 v20, v20, v26
	v_max_f32_e32 v26, v21, v29
	v_min_f32_e32 v21, v21, v29
	v_max_f32_e32 v33, v14, v31
	v_min_f32_e32 v14, v14, v31
	v_max_f32_e32 v31, v17, v22
	v_min_f32_e32 v17, v17, v22
	v_max_f32_e32 v22, v101, v32
	v_min_f32_e32 v32, v101, v32
	v_max_f32_e32 v101, v9, v8
	v_min_f32_e32 v8, v9, v8
	v_max_f32_e32 v9, v7, v6
	v_min_f32_e32 v6, v7, v6
	v_max_f32_e32 v7, v16, v23
	v_min_f32_e32 v16, v16, v23
	v_max_f32_e32 v23, v25, v24
	v_min_f32_e32 v24, v25, v24
	v_max_f32_e32 v25, v30, v15
	v_min_f32_e32 v15, v30, v15
	v_max_f32_e32 v29, v10, v27
	v_min_f32_e32 v10, v10, v27
	v_max_f32_e32 v27, v13, v18
	v_min_f32_e32 v13, v13, v18
	v_max_f32_e32 v18, v109, v28
	v_min_f32_e32 v28, v109, v28
	v_max_f32_e32 v109, v5, v4
	v_min_f32_e32 v4, v5, v4
	v_max_f32_e32 v5, v3, v2
	v_min_f32_e32 v2, v3, v2
	v_max_f32_e32 v3, v12, v19
	v_min_f32_e32 v12, v12, v19
	v_max_f32_e32 v19, v21, v20
	v_min_f32_e32 v20, v21, v20
	v_max_f32_e32 v21, v26, v11
	v_min_f32_e32 v11, v26, v11
	v_max_f32_e32 v30, v33, v6
	v_min_f32_e32 v6, v33, v6
	v_max_f32_e32 v33, v14, v9
	v_min_f32_e32 v9, v14, v9
	v_max_f32_e32 v14, v31, v16
	v_min_f32_e32 v16, v31, v16
	v_max_f32_e32 v31, v17, v7
	v_min_f32_e32 v7, v17, v7
	v_max_f32_e32 v17, v22, v24
	v_min_f32_e32 v22, v22, v24
	v_max_f32_e32 v24, v32, v23
	v_min_f32_e32 v23, v32, v23
	v_max_f32_e32 v32, v101, v15
	v_min_f32_e32 v15, v101, v15
	v_max_f32_e32 v101, v8, v25
	v_min_f32_e32 v8, v8, v25
	v_max_f32_e32 v26, v29, v2
	v_min_f32_e32 v2, v29, v2
	v_max_f32_e32 v29, v10, v5
	v_min_f32_e32 v5, v10, v5
	v_max_f32_e32 v10, v27, v12
	v_min_f32_e32 v12, v27, v12
	v_max_f32_e32 v27, v13, v3
	v_min_f32_e32 v3, v13, v3
	v_max_f32_e32 v13, v18, v20
	v_min_f32_e32 v18, v18, v20
	v_max_f32_e32 v20, v28, v19
; DEV void ce(float& a, float& b) { float hi = fmaxf(a, b), lo = fminf(a, b); a = hi; b = lo; }
; DEV void sort16_desc(float (&a)[16]) {
; #pragma unroll
;   for (int k = 2; k <= 16; k <<= 1)
; #pragma unroll
;     for (int j = k >> 1; j > 0; j >>= 1)
; #pragma unroll
;       for (int i = 0; i < 16; i++) {
;         const int p = i ^ j;
;         if (p > i) { if ((i & k) == 0) ce(a[i], a[p]); else ce(a[p], a[i]); }
;       }
; }
; DEV void merge_xor(float (&l)[16], int mask) {
;   float t[16];
; #pragma unroll
;   for (int i = 0; i < 16; i++) t[i] = __shfl_xor(l[15 - i], mask);
; #pragma unroll
;   for (int i = 0; i < 16; i++) l[i] = fmaxf(l[i], t[i]);
;   bitonic16(l);
; }
; DEV void peer_top16(const bf16_t* __restrict__ pq, const bf16_t* sk  , float (&l)[16]) {
;     ...
;   sort16_desc(l);
;   sort16_desc(hi);
; #pragma unroll
;   for (int i = 0; i < 16; i++) l[i] = fmaxf(l[i], hi[15 - i]);
;   bitonic16(l);
;   merge_xor(l, 16);
	v_min_f32_e32 v19, v28, v19
	v_max_f32_e32 v28, v109, v11
	v_min_f32_e32 v11, v109, v11
	v_max_f32_e32 v109, v4, v21
	v_min_f32_e32 v4, v4, v21
	v_max_f32_e32 v25, v30, v17
	v_min_f32_e32 v17, v30, v17
	v_max_f32_e32 v30, v33, v24
	v_min_f32_e32 v24, v33, v24
	v_max_f32_e32 v33, v14, v32
	v_min_f32_e32 v14, v14, v32
	v_max_f32_e32 v32, v31, v101
	v_min_f32_e32 v31, v31, v101
	v_max_f32_e32 v101, v6, v22
	v_min_f32_e32 v6, v6, v22
	v_max_f32_e32 v22, v9, v23
	v_min_f32_e32 v9, v9, v23
	v_max_f32_e32 v23, v16, v15
	v_min_f32_e32 v15, v16, v15
	v_max_f32_e32 v16, v7, v8
	v_min_f32_e32 v7, v7, v8
	v_max_f32_e32 v21, v26, v13
	v_min_f32_e32 v13, v26, v13
	v_max_f32_e32 v26, v29, v20
	v_min_f32_e32 v20, v29, v20
	v_max_f32_e32 v29, v10, v28
	v_min_f32_e32 v10, v10, v28
	v_max_f32_e32 v28, v27, v109
	v_min_f32_e32 v27, v27, v109
	v_max_f32_e32 v109, v2, v18
	v_min_f32_e32 v2, v2, v18
	v_max_f32_e32 v18, v5, v19
	v_min_f32_e32 v5, v5, v19
	v_max_f32_e32 v19, v12, v11
	v_min_f32_e32 v11, v12, v11
	v_max_f32_e32 v12, v3, v4
	v_min_f32_e32 v3, v3, v4
	v_max_f32_e32 v111, v0, v43
	v_min_f32_e32 v112, v104, v39
	v_max_f32_e32 v103, v104, v39
	v_min_f32_e32 v0, v0, v43
	v_max_f32_e32 v8, v25, v33
	v_min_f32_e32 v25, v25, v33
	v_max_f32_e32 v33, v30, v32
	v_min_f32_e32 v30, v30, v32
	v_max_f32_e32 v32, v17, v14
	v_min_f32_e32 v14, v17, v14
	v_max_f32_e32 v17, v24, v31
	v_min_f32_e32 v24, v24, v31
	v_max_f32_e32 v31, v101, v23
	v_min_f32_e32 v23, v101, v23
	v_max_f32_e32 v101, v22, v16
	v_min_f32_e32 v16, v22, v16
	v_max_f32_e32 v22, v6, v15
	v_min_f32_e32 v6, v6, v15
	v_max_f32_e32 v15, v9, v7
	v_min_f32_e32 v7, v9, v7
	v_max_f32_e32 v4, v21, v29
	v_min_f32_e32 v21, v21, v29
	v_max_f32_e32 v29, v26, v28
	v_min_f32_e32 v26, v26, v28
	v_max_f32_e32 v28, v13, v10
	v_min_f32_e32 v10, v13, v10
	v_max_f32_e32 v13, v20, v27
	v_min_f32_e32 v20, v20, v27
	v_max_f32_e32 v27, v109, v19
	v_min_f32_e32 v19, v109, v19
	v_max_f32_e32 v109, v18, v12
	v_min_f32_e32 v12, v18, v12
	v_max_f32_e32 v18, v2, v11
	v_min_f32_e32 v2, v2, v11
	v_max_f32_e32 v11, v5, v3
	v_min_f32_e32 v3, v5, v3
	v_min_f32_e32 v63, v107, v108
	v_min_f32_e32 v39, v111, v103
	v_max_f32_e32 v71, v107, v108
	v_max_f32_e32 v51, v111, v103
	v_max_f32_e32 v43, v0, v112
	v_min_f32_e32 v0, v0, v112
	v_min_f32_e32 v9, v8, v33
	v_min_f32_e32 v102, v25, v30
	v_min_f32_e32 v103, v32, v17
	v_min_f32_e32 v104, v14, v24
	v_min_f32_e32 v105, v31, v101
	v_min_f32_e32 v106, v23, v16
	v_min_f32_e32 v107, v22, v15
	v_min_f32_e32 v108, v6, v7
	v_min_f32_e32 v5, v4, v29
	v_min_f32_e32 v110, v21, v26
	v_min_f32_e32 v111, v28, v13
	v_min_f32_e32 v112, v10, v20
	v_min_f32_e32 v113, v27, v109
	v_min_f32_e32 v114, v19, v12
	v_min_f32_e32 v115, v18, v11
	v_min_f32_e32 v116, v2, v3
	v_max3_f32 v8, v8, v33, v116
	v_max3_f32 v2, v9, v2, v3
	v_max3_f32 v3, v25, v30, v115
	v_max3_f32 v9, v102, v18, v11
	v_max3_f32 v11, v32, v17, v114
	v_max3_f32 v12, v103, v19, v12
	v_max3_f32 v14, v14, v24, v113
	v_max3_f32 v17, v104, v27, v109
	v_max3_f32 v18, v31, v101, v112
	v_max3_f32 v10, v105, v10, v20
	v_max3_f32 v16, v23, v16, v111
	v_max3_f32 v13, v106, v28, v13
	v_max3_f32 v15, v22, v15, v110
	v_max3_f32 v19, v107, v21, v26
	v_max3_f32 v5, v6, v7, v5
	v_max3_f32 v4, v108, v4, v29
	v_max_f32_e32 v6, v8, v18
	v_min_f32_e32 v7, v8, v18
	v_max_f32_e32 v8, v2, v10
	v_min_f32_e32 v2, v2, v10
	v_max_f32_e32 v10, v3, v16
	v_min_f32_e32 v3, v3, v16
	v_max_f32_e32 v16, v9, v13
	v_min_f32_e32 v9, v9, v13
	v_max_f32_e32 v13, v11, v15
	v_min_f32_e32 v11, v11, v15
	v_max_f32_e32 v15, v12, v19
	v_min_f32_e32 v12, v12, v19
	v_max_f32_e32 v18, v14, v5
	v_min_f32_e32 v5, v14, v5
	v_max_f32_e32 v14, v17, v4
	v_min_f32_e32 v4, v17, v4
	v_max_f32_e32 v17, v6, v13
	v_min_f32_e32 v6, v6, v13
	v_max_f32_e32 v13, v8, v15
	v_min_f32_e32 v8, v8, v15
	v_max_f32_e32 v15, v10, v18
	v_min_f32_e32 v10, v10, v18
	v_max_f32_e32 v18, v16, v14
	v_min_f32_e32 v14, v16, v14
	v_max_f32_e32 v16, v7, v11
	v_min_f32_e32 v7, v7, v11
	v_max_f32_e32 v11, v2, v12
	v_min_f32_e32 v2, v2, v12
	v_max_f32_e32 v12, v3, v5
	v_min_f32_e32 v3, v3, v5
	v_max_f32_e32 v5, v9, v4
	v_min_f32_e32 v4, v9, v4
	v_max_f32_e32 v9, v17, v15
	v_min_f32_e32 v15, v17, v15
	v_max_f32_e32 v17, v13, v18
	v_min_f32_e32 v13, v13, v18
	v_max_f32_e32 v18, v6, v10
	v_min_f32_e32 v6, v6, v10
	v_max_f32_e32 v10, v8, v14
	v_min_f32_e32 v8, v8, v14
	v_max_f32_e32 v14, v16, v12
	v_min_f32_e32 v12, v16, v12
	v_max_f32_e32 v16, v11, v5
	v_min_f32_e32 v5, v11, v5
	v_max_f32_e32 v11, v7, v3
	v_min_f32_e32 v3, v7, v3
	v_max_f32_e32 v7, v2, v4
	v_min_f32_e32 v2, v2, v4
	v_max_f32_e32 v4, v9, v17
	v_min_f32_e32 v9, v9, v17
	v_max_f32_e32 v17, v15, v13
	v_min_f32_e32 v13, v15, v13
	v_max_f32_e32 v15, v18, v10
	v_min_f32_e32 v10, v18, v10
	v_max_f32_e32 v18, v6, v8
	v_min_f32_e32 v6, v6, v8
	v_max_f32_e32 v8, v14, v16
	v_min_f32_e32 v14, v14, v16
	v_max_f32_e32 v16, v12, v5
	v_min_f32_e32 v5, v12, v5
	v_max_f32_e32 v12, v11, v7
	v_min_f32_e32 v7, v11, v7
	v_max_f32_e32 v11, v3, v2
	v_min_f32_e32 v2, v3, v2
	ds_bpermute_b32 v3, v95, v2
	ds_bpermute_b32 v19, v95, v11
	ds_bpermute_b32 v20, v95, v7
	ds_bpermute_b32 v21, v95, v12
	ds_bpermute_b32 v22, v95, v5
	ds_bpermute_b32 v23, v95, v16
	s_waitcnt lgkmcnt(5)
	ds_bpermute_b32 v24, v95, v14
	ds_bpermute_b32 v33, v95, v4
	v_max_f32_e32 v3, v4, v3
	s_waitcnt lgkmcnt(6)
	ds_bpermute_b32 v25, v95, v8
	ds_bpermute_b32 v32, v95, v9
	v_max_f32_e32 v4, v9, v19
	s_waitcnt lgkmcnt(7)
	ds_bpermute_b32 v26, v95, v6
	ds_bpermute_b32 v31, v95, v17
	v_max_f32_e32 v9, v17, v20
	s_waitcnt lgkmcnt(8)
	ds_bpermute_b32 v27, v95, v18
	ds_bpermute_b32 v30, v95, v13
	v_max_f32_e32 v13, v13, v21
	s_waitcnt lgkmcnt(9)
; DEV void merge_xor(float (&l)[16], int mask) {
;   float t[16];
; #pragma unroll
;   for (int i = 0; i < 16; i++) t[i] = __shfl_xor(l[15 - i], mask);
; #pragma unroll
;   for (int i = 0; i < 16; i++) l[i] = fmaxf(l[i], t[i]);
;   bitonic16(l);
; }
; DEV void phase_peer_score(const Params& p, int layer, int M, char* smem) {
;     ...
;     unsigned char* tab = (unsigned char*)smem + 73728 + (w * 16 + l15) * 32;
; #pragma unroll
;     for (int i = 0; i < 16; i++) { tab[i] = (unsigned char)(__float_as_uint(L0[i]) & 127u); tab[16 + i] = (unsigned char)(__float_as_uint(L1[i]) & 127u); }
	ds_bpermute_b32 v28, v95, v10
	ds_bpermute_b32 v29, v95, v15
	v_max_f32_e32 v15, v15, v22
	s_waitcnt lgkmcnt(10)
	v_max_f32_e32 v10, v10, v23
	s_waitcnt lgkmcnt(9)
	v_max_f32_e32 v17, v18, v24
	s_waitcnt lgkmcnt(7)
	v_max_f32_e32 v6, v6, v25
	s_waitcnt lgkmcnt(5)
	v_max_f32_e32 v8, v8, v26
	s_waitcnt lgkmcnt(3)
	v_max_f32_e32 v14, v14, v27
	s_waitcnt lgkmcnt(1)
	v_max_f32_e32 v16, v16, v28
	s_waitcnt lgkmcnt(0)
	v_max_f32_e32 v5, v5, v29
	v_max_f32_e32 v12, v12, v30
	v_max_f32_e32 v7, v7, v31
	v_max_f32_e32 v11, v11, v32
	v_max_f32_e32 v2, v2, v33
	v_max_f32_e32 v18, v3, v8
	v_min_f32_e32 v3, v3, v8
	v_max_f32_e32 v8, v4, v14
	v_min_f32_e32 v4, v4, v14
	v_max_f32_e32 v14, v9, v16
	v_min_f32_e32 v9, v9, v16
	v_max_f32_e32 v16, v13, v5
	v_min_f32_e32 v5, v13, v5
	v_max_f32_e32 v13, v15, v12
	v_min_f32_e32 v12, v15, v12
	v_max_f32_e32 v15, v10, v7
	v_min_f32_e32 v7, v10, v7
	v_max_f32_e32 v10, v17, v11
	v_min_f32_e32 v11, v17, v11
	v_max_f32_e32 v17, v6, v2
	v_min_f32_e32 v2, v6, v2
	v_max_f32_e32 v6, v18, v13
	v_min_f32_e32 v13, v18, v13
	v_max_f32_e32 v18, v8, v15
	v_min_f32_e32 v8, v8, v15
	v_max_f32_e32 v15, v14, v10
	v_min_f32_e32 v10, v14, v10
	v_max_f32_e32 v14, v16, v17
	v_min_f32_e32 v16, v16, v17
	v_max_f32_e32 v17, v3, v12
	v_min_f32_e32 v3, v3, v12
	v_max_f32_e32 v12, v4, v7
	v_min_f32_e32 v4, v4, v7
	v_max_f32_e32 v7, v9, v11
	v_min_f32_e32 v9, v9, v11
	v_max_f32_e32 v11, v5, v2
	v_min_f32_e32 v2, v5, v2
	v_max_f32_e32 v5, v6, v15
	v_min_f32_e32 v6, v6, v15
	v_max_f32_e32 v15, v18, v14
	v_min_f32_e32 v14, v18, v14
	v_max_f32_e32 v18, v13, v10
	v_min_f32_e32 v10, v13, v10
	v_max_f32_e32 v13, v8, v16
	v_min_f32_e32 v8, v8, v16
	v_max_f32_e32 v16, v17, v7
	v_min_f32_e32 v7, v17, v7
	v_max_f32_e32 v17, v12, v11
	v_min_f32_e32 v11, v12, v11
	v_max_f32_e32 v12, v3, v9
	v_min_f32_e32 v3, v3, v9
	v_max_f32_e32 v9, v4, v2
	v_min_f32_e32 v2, v4, v2
	v_max_f32_e32 v4, v5, v15
	v_min_f32_e32 v5, v5, v15
	v_max_f32_e32 v15, v6, v14
	v_min_f32_e32 v6, v6, v14
	v_max_f32_e32 v14, v18, v13
	v_min_f32_e32 v13, v18, v13
	v_max_f32_e32 v18, v10, v8
	v_min_f32_e32 v8, v10, v8
	v_max_f32_e32 v10, v16, v17
	v_min_f32_e32 v16, v16, v17
	v_max_f32_e32 v17, v7, v11
	v_min_f32_e32 v7, v7, v11
	v_max_f32_e32 v11, v12, v9
	v_min_f32_e32 v9, v12, v9
	v_max_f32_e32 v12, v3, v2
	v_min_f32_e32 v2, v3, v2
	ds_bpermute_b32 v3, v99, v2
	ds_bpermute_b32 v19, v99, v12
	ds_bpermute_b32 v20, v99, v9
	ds_bpermute_b32 v21, v99, v11
	ds_bpermute_b32 v22, v99, v7
	ds_bpermute_b32 v23, v99, v17
	s_waitcnt lgkmcnt(5)
	ds_bpermute_b32 v24, v99, v16
	ds_bpermute_b32 v33, v99, v4
	v_max_f32_e32 v3, v4, v3
	s_waitcnt lgkmcnt(6)
	ds_bpermute_b32 v25, v99, v10
	ds_bpermute_b32 v32, v99, v5
	v_max_f32_e32 v4, v5, v19
	s_waitcnt lgkmcnt(7)
	ds_bpermute_b32 v26, v99, v8
	ds_bpermute_b32 v31, v99, v15
	v_max_f32_e32 v5, v15, v20
	s_waitcnt lgkmcnt(8)
	ds_bpermute_b32 v27, v99, v18
	ds_bpermute_b32 v30, v99, v6
	v_max_f32_e32 v6, v6, v21
	s_waitcnt lgkmcnt(9)
	ds_bpermute_b32 v28, v99, v13
	ds_bpermute_b32 v29, v99, v14
	v_max_f32_e32 v14, v14, v22
	s_waitcnt lgkmcnt(10)
	v_max_f32_e32 v13, v13, v23
	s_waitcnt lgkmcnt(9)
	v_max_f32_e32 v15, v18, v24
	s_waitcnt lgkmcnt(7)
	v_max_f32_e32 v8, v8, v25
	s_waitcnt lgkmcnt(5)
	v_max_f32_e32 v10, v10, v26
	s_waitcnt lgkmcnt(3)
	v_max_f32_e32 v16, v16, v27
	s_waitcnt lgkmcnt(1)
	v_max_f32_e32 v17, v17, v28
	s_waitcnt lgkmcnt(0)
	v_max_f32_e32 v7, v7, v29
	v_max_f32_e32 v11, v11, v30
	v_max_f32_e32 v9, v9, v31
	v_max_f32_e32 v12, v12, v32
	v_max_f32_e32 v2, v2, v33
	v_max_f32_e32 v18, v3, v10
	v_min_f32_e32 v3, v3, v10
	v_max_f32_e32 v10, v4, v16
	v_min_f32_e32 v4, v4, v16
	v_max_f32_e32 v16, v5, v17
	v_min_f32_e32 v5, v5, v17
	v_max_f32_e32 v17, v6, v7
	v_min_f32_e32 v6, v6, v7
	v_max_f32_e32 v7, v14, v11
	v_min_f32_e32 v11, v14, v11
	v_max_f32_e32 v14, v13, v9
	v_min_f32_e32 v9, v13, v9
	v_max_f32_e32 v13, v15, v12
	v_min_f32_e32 v12, v15, v12
	v_max_f32_e32 v15, v8, v2
	v_min_f32_e32 v2, v8, v2
	v_max_f32_e32 v8, v18, v7
	v_min_f32_e32 v7, v18, v7
	v_max_f32_e32 v18, v10, v14
	v_min_f32_e32 v10, v10, v14
	v_max_f32_e32 v14, v16, v13
	v_min_f32_e32 v13, v16, v13
	v_max_f32_e32 v16, v17, v15
	v_min_f32_e32 v15, v17, v15
	v_max_f32_e32 v17, v3, v11
	v_min_f32_e32 v3, v3, v11
	v_max_f32_e32 v11, v4, v9
	v_min_f32_e32 v4, v4, v9
	v_max_f32_e32 v9, v5, v12
	v_min_f32_e32 v5, v5, v12
	v_max_f32_e32 v12, v6, v2
	v_min_f32_e32 v2, v6, v2
	v_max_f32_e32 v6, v8, v14
	v_min_f32_e32 v8, v8, v14
	v_max_f32_e32 v14, v18, v16
	v_min_f32_e32 v16, v18, v16
	v_max_f32_e32 v18, v7, v13
	v_max_f32_e32 v19, v10, v15
	s_movk_i32 s0, 0x7f
	v_min_f32_e32 v13, v7, v13
	v_min_f32_e32 v10, v10, v15
	v_max_f32_e32 v15, v17, v9
	v_min_f32_e32 v21, v17, v9
	v_max_f32_e32 v17, v11, v12
	v_min_f32_e32 v22, v11, v12
	v_max_f32_e32 v23, v3, v5
	v_min_f32_e32 v3, v3, v5
	v_max_f32_e32 v5, v4, v2
	v_min_f32_e32 v24, v4, v2
	v_max_f32_e32 v9, v18, v19
	v_min_f32_e32 v12, v18, v19
	v_and_b32_sdwa v18, v63, s0 dst_sel:BYTE_1 dst_unused:UNUSED_PAD src0_sel:DWORD src1_sel:DWORD
	v_max_f32_e32 v2, v6, v14
	v_min_f32_e32 v4, v6, v14
	v_max_f32_e32 v11, v13, v10
	v_min_f32_e32 v10, v13, v10
	v_max_f32_e32 v14, v23, v5
	v_min_f32_e32 v13, v23, v5
	v_max_f32_e32 v6, v3, v24
	v_min_f32_e32 v5, v3, v24
	v_and_b32_sdwa v3, v75, s0 dst_sel:BYTE_1 dst_unused:UNUSED_PAD src0_sel:DWORD src1_sel:DWORD
	v_bitop3_b16 v18, v71, v18, s0 bitop3:0xec
	v_bitop3_b16 v3, v79, v3, s0 bitop3:0xec
	v_lshlrev_b32_e32 v18, 16, v18
	v_or_b32_sdwa v23, v3, v18 dst_sel:DWORD dst_unused:UNUSED_PAD src0_sel:WORD_0 src1_sel:DWORD
	v_and_b32_sdwa v18, v83, s0 dst_sel:BYTE_1 dst_unused:UNUSED_PAD src0_sel:DWORD src1_sel:DWORD
; DEV void ce(float& a, float& b) { float hi = fmaxf(a, b), lo = fminf(a, b); a = hi; b = lo; }
; DEV void phase_peer_score(const Params& p, int layer, int M, char* smem) {
;     ...
; #pragma unroll
;     for (int i = 0; i < 16; i++) R[i] = -3.0e38f;
; #pragma unroll
;     for (int i = 0; i < 16; i++)
; #pragma unroll
;       for (int j = 0; j < 16; j++)
;         if ((i + 1) * (j + 1) <= 16) {
;           float v = L0[i] + L1[j];
;           v = __uint_as_float((__float_as_uint(v) & ~255u) | (unsigned)(i * 16 + j));
; #pragma unroll
;           for (int t = 0; t < 16; t++)
;             if (t >= (i + 1) * (j + 1) - 1) ce(R[t], v);
;         }
;     unsigned char* tab = (unsigned char*)smem + 73728 + (w * 16 + l15) * 32;
; #pragma unroll
;     for (int i = 0; i < 16; i++) { tab[i] = (unsigned char)(__float_as_uint(L0[i]) & 127u); tab[16 + i] = (unsigned char)(__float_as_uint(L1[i]) & 127u); }
	v_and_b32_sdwa v3, v91, s0 dst_sel:BYTE_1 dst_unused:UNUSED_PAD src0_sel:DWORD src1_sel:DWORD
	v_bitop3_b16 v18, v87, v18, s0 bitop3:0xec
	v_bitop3_b16 v3, v100, v3, s0 bitop3:0xec
	v_lshlrev_b32_e32 v18, 16, v18
	v_max_f32_e32 v7, v8, v16
	v_min_f32_e32 v8, v8, v16
	v_max_f32_e32 v20, v15, v17
	v_min_f32_e32 v17, v15, v17
	v_max_f32_e32 v16, v21, v22
	v_min_f32_e32 v15, v21, v22
	v_or_b32_sdwa v22, v3, v18 dst_sel:DWORD dst_unused:UNUSED_PAD src0_sel:WORD_0 src1_sel:DWORD
	v_and_b32_sdwa v18, v10, s0 dst_sel:BYTE_1 dst_unused:UNUSED_PAD src0_sel:DWORD src1_sel:DWORD
	v_and_b32_sdwa v3, v12, s0 dst_sel:BYTE_1 dst_unused:UNUSED_PAD src0_sel:DWORD src1_sel:DWORD
	v_bitop3_b16 v18, v11, v18, s0 bitop3:0xec
	v_bitop3_b16 v3, v9, v3, s0 bitop3:0xec
	v_lshlrev_b32_e32 v18, 16, v18
	v_or_b32_sdwa v27, v3, v18 dst_sel:DWORD dst_unused:UNUSED_PAD src0_sel:WORD_0 src1_sel:DWORD
	v_and_b32_sdwa v18, v8, s0 dst_sel:BYTE_1 dst_unused:UNUSED_PAD src0_sel:DWORD src1_sel:DWORD
	v_and_b32_sdwa v3, v4, s0 dst_sel:BYTE_1 dst_unused:UNUSED_PAD src0_sel:DWORD src1_sel:DWORD
	v_bitop3_b16 v18, v7, v18, s0 bitop3:0xec
	v_bitop3_b16 v3, v2, v3, s0 bitop3:0xec
	v_lshlrev_b32_e32 v18, 16, v18
	v_or_b32_sdwa v26, v3, v18 dst_sel:DWORD dst_unused:UNUSED_PAD src0_sel:WORD_0 src1_sel:DWORD
	v_and_b32_sdwa v18, v0, s0 dst_sel:BYTE_1 dst_unused:UNUSED_PAD src0_sel:DWORD src1_sel:DWORD
	v_and_b32_sdwa v3, v39, s0 dst_sel:BYTE_1 dst_unused:UNUSED_PAD src0_sel:DWORD src1_sel:DWORD
	v_bitop3_b16 v18, v43, v18, s0 bitop3:0xec
	v_bitop3_b16 v3, v51, v3, s0 bitop3:0xec
	v_lshlrev_b32_e32 v18, 16, v18
	v_or_b32_sdwa v25, v3, v18 dst_sel:DWORD dst_unused:UNUSED_PAD src0_sel:WORD_0 src1_sel:DWORD
	v_and_b32_sdwa v18, v47, s0 dst_sel:BYTE_1 dst_unused:UNUSED_PAD src0_sel:DWORD src1_sel:DWORD
	v_and_b32_sdwa v3, v59, s0 dst_sel:BYTE_1 dst_unused:UNUSED_PAD src0_sel:DWORD src1_sel:DWORD
	v_bitop3_b16 v18, v55, v18, s0 bitop3:0xec
	v_bitop3_b16 v3, v67, v3, s0 bitop3:0xec
	v_lshlrev_b32_e32 v18, 16, v18
	v_or_b32_sdwa v24, v3, v18 dst_sel:DWORD dst_unused:UNUSED_PAD src0_sel:WORD_0 src1_sel:DWORD
	v_and_b32_sdwa v18, v5, s0 dst_sel:BYTE_1 dst_unused:UNUSED_PAD src0_sel:DWORD src1_sel:DWORD
	v_and_b32_sdwa v3, v13, s0 dst_sel:BYTE_1 dst_unused:UNUSED_PAD src0_sel:DWORD src1_sel:DWORD
	v_bitop3_b16 v18, v6, v18, s0 bitop3:0xec
	v_bitop3_b16 v3, v14, v3, s0 bitop3:0xec
	v_lshlrev_b32_e32 v18, 16, v18
	v_or_b32_sdwa v29, v3, v18 dst_sel:DWORD dst_unused:UNUSED_PAD src0_sel:WORD_0 src1_sel:DWORD
	v_and_b32_sdwa v18, v15, s0 dst_sel:BYTE_1 dst_unused:UNUSED_PAD src0_sel:DWORD src1_sel:DWORD
	v_and_b32_sdwa v3, v17, s0 dst_sel:BYTE_1 dst_unused:UNUSED_PAD src0_sel:DWORD src1_sel:DWORD
	v_bitop3_b16 v18, v16, v18, s0 bitop3:0xec
	v_bitop3_b16 v3, v20, v3, s0 bitop3:0xec
	v_lshlrev_b32_e32 v18, 16, v18
	v_or_b32_sdwa v28, v3, v18 dst_sel:DWORD dst_unused:UNUSED_PAD src0_sel:WORD_0 src1_sel:DWORD
	ds_write_b128 v138, v[22:25]
	ds_write_b128 v138, v[26:29] offset:16
	s_and_saveexec_b64 s[14:15], s[38:39]
	s_cbranch_execz .LBB0_162
	s_movk_i32 s0, 0xff00
	v_add_f32_e32 v164, v100, v2
	v_and_or_b32 v164, v164, s0, 0
	v_max_f32_e32 v148, 0xff61b1e6, v164
	v_add_f32_e32 v164, v100, v4
	v_and_or_b32 v164, v164, s0, 1
	v_max_f32_e32 v149, 0xff61b1e6, v164
	v_add_f32_e32 v164, v100, v7
	v_and_or_b32 v164, v164, s0, 2
	v_max_f32_e32 v150, 0xff61b1e6, v164
	v_add_f32_e32 v164, v100, v8
	v_and_or_b32 v164, v164, s0, 3
	v_max_f32_e32 v151, 0xff61b1e6, v164
	v_add_f32_e32 v164, v100, v9
	v_and_or_b32 v164, v164, s0, 4
	v_max_f32_e32 v152, 0xff61b1e6, v164
	v_add_f32_e32 v164, v100, v12
	v_and_or_b32 v164, v164, s0, 5
	v_max_f32_e32 v153, 0xff61b1e6, v164
	v_add_f32_e32 v164, v100, v11
	v_and_or_b32 v164, v164, s0, 6
	v_max_f32_e32 v154, 0xff61b1e6, v164
	v_add_f32_e32 v164, v100, v10
	v_and_or_b32 v164, v164, s0, 7
	v_max_f32_e32 v155, 0xff61b1e6, v164
	v_add_f32_e32 v164, v100, v20
	v_and_or_b32 v164, v164, s0, 8
	v_max_f32_e32 v156, 0xff61b1e6, v164
	v_add_f32_e32 v164, v100, v17
	v_and_or_b32 v164, v164, s0, 9
	v_max_f32_e32 v157, 0xff61b1e6, v164
	v_add_f32_e32 v164, v100, v16
	v_and_or_b32 v164, v164, s0, 10
	v_max_f32_e32 v158, 0xff61b1e6, v164
	v_add_f32_e32 v164, v100, v15
	v_and_or_b32 v164, v164, s0, 11
	v_max_f32_e32 v159, 0xff61b1e6, v164
	v_add_f32_e32 v164, v100, v14
	v_and_or_b32 v164, v164, s0, 12
	v_max_f32_e32 v160, 0xff61b1e6, v164
	v_add_f32_e32 v164, v100, v13
	v_and_or_b32 v164, v164, s0, 13
	v_max_f32_e32 v161, 0xff61b1e6, v164
	v_add_f32_e32 v164, v100, v6
	v_and_or_b32 v164, v164, s0, 14
	v_max_f32_e32 v162, 0xff61b1e6, v164
	v_add_f32_e32 v164, v100, v5
	v_and_or_b32 v164, v164, s0, 15
	v_max_f32_e32 v163, 0xff61b1e6, v164
	v_min_f32_e32 v164, v148, v149
	v_max_f32_e32 v148, v148, v149
	v_min_f32_e32 v149, v164, v150
	v_max_f32_e32 v164, v164, v150
	v_min_f32_e32 v150, v149, v151
	v_max_f32_e32 v149, v149, v151
	v_min_f32_e32 v151, v150, v152
	v_max_f32_e32 v150, v150, v152
	v_min_f32_e32 v152, v151, v153
	v_max_f32_e32 v151, v151, v153
	v_min_f32_e32 v153, v152, v154
	v_max_f32_e32 v152, v152, v154
	v_min_f32_e32 v154, v153, v155
	v_max_f32_e32 v153, v153, v155
	v_min_f32_e32 v155, v154, v156
	v_max_f32_e32 v154, v154, v156
	v_min_f32_e32 v156, v155, v157
	v_max_f32_e32 v155, v155, v157
	v_min_f32_e32 v157, v156, v158
	v_max_f32_e32 v156, v156, v158
	v_min_f32_e32 v158, v157, v159
	v_max_f32_e32 v157, v157, v159
	v_min_f32_e32 v159, v158, v160
	v_max_f32_e32 v158, v158, v160
	v_min_f32_e32 v160, v159, v161
	v_max_f32_e32 v159, v159, v161
	v_min_f32_e32 v161, v160, v162
	v_max_f32_e32 v160, v160, v162
	v_min_f32_e32 v162, v161, v163
	v_max_f32_e32 v161, v161, v163
; DEV void ce(float& a, float& b) { float hi = fmaxf(a, b), lo = fminf(a, b); a = hi; b = lo; }
; DEV void phase_peer_score(const Params& p, int layer, int M, char* smem) {
;     ...
;     for (int i = 0; i < 16; i++)
; #pragma unroll
;       for (int j = 0; j < 16; j++)
;         if ((i + 1) * (j + 1) <= 16) {
;           float v = L0[i] + L1[j];
;           v = __uint_as_float((__float_as_uint(v) & ~255u) | (unsigned)(i * 16 + j));
; #pragma unroll
;           for (int t = 0; t < 16; t++)
;             if (t >= (i + 1) * (j + 1) - 1) ce(R[t], v);
;         }
	v_add_f32_e32 v163, v91, v2
	v_and_or_b32 v163, v163, s0, 16
	v_med3_f32 v162, v161, v162, v163
	v_med3_f32 v161, v160, v161, v163
	v_med3_f32 v160, v159, v160, v163
	v_med3_f32 v159, v158, v159, v163
	v_med3_f32 v158, v157, v158, v163
	v_med3_f32 v157, v156, v157, v163
	v_med3_f32 v156, v155, v156, v163
	v_med3_f32 v155, v154, v155, v163
	v_med3_f32 v154, v153, v154, v163
	v_med3_f32 v153, v152, v153, v163
	v_med3_f32 v152, v151, v152, v163
	v_med3_f32 v151, v150, v151, v163
	v_med3_f32 v150, v149, v150, v163
	v_med3_f32 v149, v164, v149, v163
	v_med3_f32 v164, v148, v164, v163
	v_max_f32_e32 v148, v148, v163
	v_add_f32_e32 v163, v91, v4
	v_and_or_b32 v163, v163, s0, 17
	v_med3_f32 v162, v161, v162, v163
	v_med3_f32 v161, v160, v161, v163
	v_med3_f32 v160, v159, v160, v163
	v_med3_f32 v159, v158, v159, v163
	v_med3_f32 v158, v157, v158, v163
	v_med3_f32 v157, v156, v157, v163
	v_med3_f32 v156, v155, v156, v163
	v_med3_f32 v155, v154, v155, v163
	v_med3_f32 v154, v153, v154, v163
	v_med3_f32 v153, v152, v153, v163
	v_med3_f32 v152, v151, v152, v163
	v_med3_f32 v151, v150, v151, v163
	v_med3_f32 v150, v149, v150, v163
	v_max_f32_e32 v149, v149, v163
	v_add_f32_e32 v163, v91, v7
	v_and_or_b32 v163, v163, s0, 18
	v_med3_f32 v162, v161, v162, v163
	v_med3_f32 v161, v160, v161, v163
	v_med3_f32 v160, v159, v160, v163
	v_med3_f32 v159, v158, v159, v163
	v_med3_f32 v158, v157, v158, v163
	v_med3_f32 v157, v156, v157, v163
	v_med3_f32 v156, v155, v156, v163
	v_med3_f32 v155, v154, v155, v163
	v_med3_f32 v154, v153, v154, v163
	v_med3_f32 v153, v152, v153, v163
	v_med3_f32 v152, v151, v152, v163
	v_max_f32_e32 v151, v151, v163
	v_add_f32_e32 v163, v91, v8
	v_and_or_b32 v163, v163, s0, 19
	v_med3_f32 v162, v161, v162, v163
	v_med3_f32 v161, v160, v161, v163
	v_med3_f32 v160, v159, v160, v163
	v_med3_f32 v159, v158, v159, v163
	v_med3_f32 v158, v157, v158, v163
	v_med3_f32 v157, v156, v157, v163
	v_med3_f32 v156, v155, v156, v163
	v_med3_f32 v155, v154, v155, v163
	v_med3_f32 v154, v153, v154, v163
	v_max_f32_e32 v153, v153, v163
	v_add_f32_e32 v163, v91, v9
	v_and_or_b32 v163, v163, s0, 20
	v_med3_f32 v162, v161, v162, v163
	v_med3_f32 v161, v160, v161, v163
	v_med3_f32 v160, v159, v160, v163
	v_med3_f32 v159, v158, v159, v163
	v_med3_f32 v158, v157, v158, v163
	v_med3_f32 v157, v156, v157, v163
	v_med3_f32 v156, v155, v156, v163
	v_max_f32_e32 v155, v155, v163
	v_add_f32_e32 v163, v91, v12
	v_and_or_b32 v163, v163, s0, 21
	v_med3_f32 v162, v161, v162, v163
	v_med3_f32 v161, v160, v161, v163
	v_med3_f32 v160, v159, v160, v163
	v_med3_f32 v159, v158, v159, v163
	v_med3_f32 v158, v157, v158, v163
	v_max_f32_e32 v157, v157, v163
	v_add_f32_e32 v163, v91, v11
	v_and_or_b32 v163, v163, s0, 22
	v_med3_f32 v162, v161, v162, v163
	v_med3_f32 v161, v160, v161, v163
	v_med3_f32 v160, v159, v160, v163
	v_max_f32_e32 v159, v159, v163
	v_add_f32_e32 v163, v91, v10
	v_and_or_b32 v163, v163, s0, 23
	v_med3_f32 v162, v161, v162, v163
	v_max_f32_e32 v161, v161, v163
	v_add_f32_e32 v163, v87, v2
	v_and_or_b32 v163, v163, s0, 32
	v_med3_f32 v162, v161, v162, v163
	v_med3_f32 v161, v160, v161, v163
	v_med3_f32 v160, v159, v160, v163
	v_med3_f32 v159, v158, v159, v163
	v_med3_f32 v158, v157, v158, v163
	v_med3_f32 v157, v156, v157, v163
	v_med3_f32 v156, v155, v156, v163
	v_med3_f32 v155, v154, v155, v163
	v_med3_f32 v154, v153, v154, v163
	v_med3_f32 v153, v152, v153, v163
	v_med3_f32 v152, v151, v152, v163
	v_med3_f32 v151, v150, v151, v163
	v_med3_f32 v150, v149, v150, v163
	v_med3_f32 v149, v164, v149, v163
	v_max_f32_e32 v164, v164, v163
	v_add_f32_e32 v163, v87, v4
	v_and_or_b32 v163, v163, s0, 33
	v_med3_f32 v162, v161, v162, v163
	v_med3_f32 v161, v160, v161, v163
	v_med3_f32 v160, v159, v160, v163
	v_med3_f32 v159, v158, v159, v163
	v_med3_f32 v158, v157, v158, v163
	v_med3_f32 v157, v156, v157, v163
	v_med3_f32 v156, v155, v156, v163
	v_med3_f32 v155, v154, v155, v163
	v_med3_f32 v154, v153, v154, v163
	v_med3_f32 v153, v152, v153, v163
	v_med3_f32 v152, v151, v152, v163
	v_max_f32_e32 v151, v151, v163
	v_add_f32_e32 v163, v87, v7
	v_and_or_b32 v163, v163, s0, 34
	v_med3_f32 v162, v161, v162, v163
	v_med3_f32 v161, v160, v161, v163
	v_med3_f32 v160, v159, v160, v163
	v_med3_f32 v159, v158, v159, v163
	v_med3_f32 v158, v157, v158, v163
	v_med3_f32 v157, v156, v157, v163
	v_med3_f32 v156, v155, v156, v163
	v_med3_f32 v155, v154, v155, v163
	v_max_f32_e32 v154, v154, v163
	v_add_f32_e32 v163, v87, v8
	v_and_or_b32 v163, v163, s0, 35
	v_med3_f32 v162, v161, v162, v163
	v_med3_f32 v161, v160, v161, v163
	v_med3_f32 v160, v159, v160, v163
	v_med3_f32 v159, v158, v159, v163
	v_med3_f32 v158, v157, v158, v163
	v_max_f32_e32 v157, v157, v163
	v_add_f32_e32 v163, v87, v9
	v_and_or_b32 v163, v163, s0, 36
	v_med3_f32 v162, v161, v162, v163
	v_med3_f32 v161, v160, v161, v163
	v_max_f32_e32 v160, v160, v163
	v_add_f32_e32 v163, v83, v2
	v_and_or_b32 v163, v163, s0, 48
	v_med3_f32 v162, v161, v162, v163
	v_med3_f32 v161, v160, v161, v163
	v_med3_f32 v160, v159, v160, v163
	v_med3_f32 v159, v158, v159, v163
	v_med3_f32 v158, v157, v158, v163
	v_med3_f32 v157, v156, v157, v163
	v_med3_f32 v156, v155, v156, v163
	v_med3_f32 v155, v154, v155, v163
	v_med3_f32 v154, v153, v154, v163
	v_med3_f32 v153, v152, v153, v163
	v_med3_f32 v152, v151, v152, v163
	v_med3_f32 v151, v150, v151, v163
	v_med3_f32 v150, v149, v150, v163
	v_max_f32_e32 v149, v149, v163
	v_add_f32_e32 v163, v83, v4
	v_and_or_b32 v163, v163, s0, 49
	v_med3_f32 v162, v161, v162, v163
	v_med3_f32 v161, v160, v161, v163
	v_med3_f32 v160, v159, v160, v163
	v_med3_f32 v159, v158, v159, v163
	v_med3_f32 v158, v157, v158, v163
; DEV void ce(float& a, float& b) { float hi = fmaxf(a, b), lo = fminf(a, b); a = hi; b = lo; }
; DEV void phase_peer_score(const Params& p, int layer, int M, char* smem) {
;     ...
;     for (int i = 0; i < 16; i++)
; #pragma unroll
;       for (int j = 0; j < 16; j++)
;         if ((i + 1) * (j + 1) <= 16) {
;           float v = L0[i] + L1[j];
;           v = __uint_as_float((__float_as_uint(v) & ~255u) | (unsigned)(i * 16 + j));
; #pragma unroll
;           for (int t = 0; t < 16; t++)
;             if (t >= (i + 1) * (j + 1) - 1) ce(R[t], v);
;         }
	v_med3_f32 v157, v156, v157, v163
	v_med3_f32 v156, v155, v156, v163
	v_med3_f32 v155, v154, v155, v163
	v_med3_f32 v154, v153, v154, v163
	v_max_f32_e32 v153, v153, v163
	v_add_f32_e32 v163, v83, v7
	v_and_or_b32 v163, v163, s0, 50
	v_med3_f32 v162, v161, v162, v163
	v_med3_f32 v161, v160, v161, v163
	v_med3_f32 v160, v159, v160, v163
	v_med3_f32 v159, v158, v159, v163
	v_med3_f32 v158, v157, v158, v163
	v_max_f32_e32 v157, v157, v163
	v_add_f32_e32 v163, v83, v8
	v_and_or_b32 v163, v163, s0, 51
	v_med3_f32 v162, v161, v162, v163
	v_max_f32_e32 v161, v161, v163
	v_add_f32_e32 v163, v79, v2
	v_and_or_b32 v163, v163, s0, 64
	v_med3_f32 v162, v161, v162, v163
	v_med3_f32 v161, v160, v161, v163
	v_med3_f32 v160, v159, v160, v163
	v_med3_f32 v159, v158, v159, v163
	v_med3_f32 v158, v157, v158, v163
	v_med3_f32 v157, v156, v157, v163
	v_med3_f32 v156, v155, v156, v163
	v_med3_f32 v155, v154, v155, v163
	v_med3_f32 v154, v153, v154, v163
	v_med3_f32 v153, v152, v153, v163
	v_med3_f32 v152, v151, v152, v163
	v_med3_f32 v151, v150, v151, v163
	v_max_f32_e32 v150, v150, v163
	v_add_f32_e32 v163, v79, v4
	v_and_b32_e32 v163, 0xffffff00, v163
	v_or_b32_e32 v163, 0x41, v163
	v_med3_f32 v162, v161, v162, v163
	v_med3_f32 v161, v160, v161, v163
	v_med3_f32 v160, v159, v160, v163
	v_med3_f32 v159, v158, v159, v163
	v_med3_f32 v158, v157, v158, v163
	v_med3_f32 v157, v156, v157, v163
	v_med3_f32 v156, v155, v156, v163
	v_max_f32_e32 v155, v155, v163
	v_add_f32_e32 v163, v79, v7
	v_and_b32_e32 v163, 0xffffff00, v163
	v_or_b32_e32 v163, 0x42, v163
	v_med3_f32 v162, v161, v162, v163
	v_med3_f32 v161, v160, v161, v163
	v_max_f32_e32 v160, v160, v163
	v_add_f32_e32 v163, v75, v2
	v_and_b32_e32 v163, 0xffffff00, v163
	v_or_b32_e32 v163, 0x50, v163
	v_med3_f32 v162, v161, v162, v163
	v_med3_f32 v161, v160, v161, v163
	v_med3_f32 v160, v159, v160, v163
	v_med3_f32 v159, v158, v159, v163
	v_med3_f32 v158, v157, v158, v163
	v_med3_f32 v157, v156, v157, v163
	v_med3_f32 v156, v155, v156, v163
	v_med3_f32 v155, v154, v155, v163
	v_med3_f32 v154, v153, v154, v163
	v_med3_f32 v153, v152, v153, v163
	v_med3_f32 v152, v151, v152, v163
	v_max_f32_e32 v151, v151, v163
	v_add_f32_e32 v163, v75, v4
	v_and_b32_e32 v163, 0xffffff00, v163
	v_or_b32_e32 v163, 0x51, v163
	v_med3_f32 v162, v161, v162, v163
	v_med3_f32 v161, v160, v161, v163
	v_med3_f32 v160, v159, v160, v163
	v_med3_f32 v159, v158, v159, v163
	v_med3_f32 v158, v157, v158, v163
	v_max_f32_e32 v157, v157, v163
	v_add_f32_e32 v163, v71, v2
	v_and_b32_e32 v163, 0xffffff00, v163
	v_or_b32_e32 v163, 0x60, v163
	v_med3_f32 v162, v161, v162, v163
	v_med3_f32 v161, v160, v161, v163
	v_med3_f32 v160, v159, v160, v163
	v_med3_f32 v159, v158, v159, v163
	v_med3_f32 v158, v157, v158, v163
	v_med3_f32 v157, v156, v157, v163
	v_med3_f32 v156, v155, v156, v163
	v_med3_f32 v155, v154, v155, v163
	v_med3_f32 v154, v153, v154, v163
	v_med3_f32 v153, v152, v153, v163
	v_max_f32_e32 v152, v152, v163
	v_add_f32_e32 v163, v71, v4
	v_and_b32_e32 v163, 0xffffff00, v163
	v_or_b32_e32 v163, 0x61, v163
	v_med3_f32 v162, v161, v162, v163
	v_med3_f32 v161, v160, v161, v163
	v_med3_f32 v160, v159, v160, v163
	v_max_f32_e32 v159, v159, v163
	v_add_f32_e32 v163, v63, v2
	v_and_b32_e32 v163, 0xffffff00, v163
	v_or_b32_e32 v163, 0x70, v163
	v_med3_f32 v162, v161, v162, v163
	v_med3_f32 v161, v160, v161, v163
	v_med3_f32 v160, v159, v160, v163
	v_med3_f32 v159, v158, v159, v163
	v_med3_f32 v158, v157, v158, v163
	v_med3_f32 v157, v156, v157, v163
	v_med3_f32 v156, v155, v156, v163
	v_med3_f32 v155, v154, v155, v163
	v_med3_f32 v154, v153, v154, v163
	v_max_f32_e32 v153, v153, v163
	v_add_f32_e32 v163, v63, v4
	v_and_b32_e32 v163, 0xffffff00, v163
	v_or_b32_e32 v163, 0x71, v163
	v_med3_f32 v162, v161, v162, v163
	v_max_f32_e32 v161, v161, v163
	v_add_f32_e32 v163, v67, v2
	v_and_b32_e32 v163, 0xffffff00, v163
	v_or_b32_e32 v163, 0x80, v163
	v_med3_f32 v162, v161, v162, v163
	v_med3_f32 v161, v160, v161, v163
	v_med3_f32 v160, v159, v160, v163
	v_med3_f32 v159, v158, v159, v163
	v_med3_f32 v158, v157, v158, v163
	v_med3_f32 v157, v156, v157, v163
	v_med3_f32 v156, v155, v156, v163
	v_med3_f32 v155, v154, v155, v163
	v_max_f32_e32 v154, v154, v163
	v_add_f32_e32 v163, v59, v2
	v_and_b32_e32 v163, 0xffffff00, v163
	v_or_b32_e32 v163, 0x90, v163
	v_med3_f32 v162, v161, v162, v163
	v_med3_f32 v161, v160, v161, v163
	v_med3_f32 v160, v159, v160, v163
	v_med3_f32 v159, v158, v159, v163
	v_med3_f32 v158, v157, v158, v163
	v_med3_f32 v157, v156, v157, v163
	v_med3_f32 v156, v155, v156, v163
	v_max_f32_e32 v155, v155, v163
	v_add_f32_e32 v163, v55, v2
	v_and_b32_e32 v163, 0xffffff00, v163
	v_or_b32_e32 v163, 0xa0, v163
	v_med3_f32 v162, v161, v162, v163
	v_med3_f32 v161, v160, v161, v163
	v_med3_f32 v160, v159, v160, v163
	v_med3_f32 v159, v158, v159, v163
	v_med3_f32 v158, v157, v158, v163
	v_med3_f32 v157, v156, v157, v163
	v_max_f32_e32 v156, v156, v163
	v_add_f32_e32 v163, v47, v2
	v_and_b32_e32 v163, 0xffffff00, v163
	v_or_b32_e32 v163, 0xb0, v163
	v_med3_f32 v162, v161, v162, v163
	v_med3_f32 v161, v160, v161, v163
	v_med3_f32 v160, v159, v160, v163
	v_med3_f32 v159, v158, v159, v163
	v_med3_f32 v158, v157, v158, v163
	v_max_f32_e32 v157, v157, v163
	v_add_f32_e32 v163, v51, v2
	v_and_b32_e32 v163, 0xffffff00, v163
	v_or_b32_e32 v163, 0xc0, v163
	v_med3_f32 v162, v161, v162, v163
	v_med3_f32 v161, v160, v161, v163
	v_med3_f32 v160, v159, v160, v163
	v_med3_f32 v159, v158, v159, v163
	v_max_f32_e32 v158, v158, v163
	v_add_f32_e32 v163, v39, v2
	v_and_b32_e32 v163, 0xffffff00, v163
	v_or_b32_e32 v163, 0xd0, v163
	v_med3_f32 v162, v161, v162, v163
; DEV void ce(float& a, float& b) { float hi = fmaxf(a, b), lo = fminf(a, b); a = hi; b = lo; }
; DEV void phase_peer_score(const Params& p, int layer, int M, char* smem) {
;     ...
;     for (int i = 0; i < 16; i++)
; #pragma unroll
;       for (int j = 0; j < 16; j++)
;         if ((i + 1) * (j + 1) <= 16) {
;           float v = L0[i] + L1[j];
;           v = __uint_as_float((__float_as_uint(v) & ~255u) | (unsigned)(i * 16 + j));
; #pragma unroll
;           for (int t = 0; t < 16; t++)
;             if (t >= (i + 1) * (j + 1) - 1) ce(R[t], v);
;         }
	v_med3_f32 v161, v160, v161, v163
	v_med3_f32 v160, v159, v160, v163
	v_max_f32_e32 v159, v159, v163
	v_add_f32_e32 v163, v43, v2
	v_and_b32_e32 v163, 0xffffff00, v163
	v_or_b32_e32 v163, 0xe0, v163
	v_med3_f32 v162, v161, v162, v163
	v_med3_f32 v161, v160, v161, v163
	v_max_f32_e32 v160, v160, v163
	v_add_f32_e32 v163, v0, v2
	v_and_b32_e32 v163, 0xffffff00, v163
	v_or_b32_e32 v163, 0xf0, v163
	v_med3_f32 v162, v161, v162, v163
	v_max_f32_e32 v161, v161, v163
	v_cmp_le_f32_e64 s[40:41], v148, v164
	v_cmp_le_f32_e32 vcc, v164, v149
	s_or_b64 s[40:41], s[40:41], vcc
	v_cmp_le_f32_e32 vcc, v149, v150
	s_or_b64 s[40:41], s[40:41], vcc
	v_cmp_le_f32_e32 vcc, v150, v151
	s_or_b64 s[40:41], s[40:41], vcc
	v_cmp_le_f32_e32 vcc, v151, v152
	s_or_b64 s[40:41], s[40:41], vcc
	v_cmp_le_f32_e32 vcc, v152, v153
	s_or_b64 s[40:41], s[40:41], vcc
	v_cmp_le_f32_e32 vcc, v153, v154
	s_or_b64 s[40:41], s[40:41], vcc
	v_cmp_le_f32_e32 vcc, v154, v155
	s_or_b64 s[40:41], s[40:41], vcc
	v_cmp_le_f32_e32 vcc, v155, v156
	s_or_b64 s[40:41], s[40:41], vcc
	v_cmp_le_f32_e32 vcc, v156, v157
	s_or_b64 s[40:41], s[40:41], vcc
	v_cmp_le_f32_e32 vcc, v157, v158
	s_or_b64 s[40:41], s[40:41], vcc
	v_cmp_le_f32_e32 vcc, v158, v159
	s_or_b64 s[40:41], s[40:41], vcc
	v_cmp_le_f32_e32 vcc, v159, v160
	s_or_b64 s[40:41], s[40:41], vcc
	v_cmp_le_f32_e32 vcc, v160, v161
	s_or_b64 s[40:41], s[40:41], vcc
	v_cmp_le_f32_e32 vcc, v161, v162
	s_or_b64 s[40:41], s[40:41], vcc
	s_and_b64 s[40:41], s[40:41], exec
	s_cbranch_scc0 .Lmed3_ok_bb_172
	v_mov_b32_e32 v148, 0xff61b1e6
	v_mov_b32_e32 v164, 0xff61b1e6
	v_mov_b32_e32 v149, 0xff61b1e6
	v_mov_b32_e32 v150, 0xff61b1e6
	v_mov_b32_e32 v151, 0xff61b1e6
	v_mov_b32_e32 v152, 0xff61b1e6
	v_mov_b32_e32 v153, 0xff61b1e6
	v_mov_b32_e32 v154, 0xff61b1e6
	v_mov_b32_e32 v155, 0xff61b1e6
	v_mov_b32_e32 v156, 0xff61b1e6
	v_mov_b32_e32 v157, 0xff61b1e6
	v_mov_b32_e32 v158, 0xff61b1e6
	v_mov_b32_e32 v159, 0xff61b1e6
	v_mov_b32_e32 v160, 0xff61b1e6
	v_mov_b32_e32 v161, 0xff61b1e6
	v_mov_b32_e32 v162, 0xff61b1e6
	v_add_f32_e32 v163, v100, v2
	v_and_or_b32 v163, v163, s0, 0
	v_min_f32_e32 v165, v148, v163
	v_max_f32_e32 v148, v148, v163
	v_min_f32_e32 v163, v164, v165
	v_max_f32_e32 v164, v164, v165
	v_min_f32_e32 v165, v149, v163
	v_max_f32_e32 v149, v149, v163
	v_min_f32_e32 v163, v150, v165
	v_max_f32_e32 v150, v150, v165
	v_min_f32_e32 v165, v151, v163
	v_max_f32_e32 v151, v151, v163
	v_min_f32_e32 v163, v152, v165
	v_max_f32_e32 v152, v152, v165
	v_min_f32_e32 v165, v153, v163
	v_max_f32_e32 v153, v153, v163
	v_min_f32_e32 v163, v154, v165
	v_max_f32_e32 v154, v154, v165
	v_min_f32_e32 v165, v155, v163
	v_max_f32_e32 v155, v155, v163
	v_min_f32_e32 v163, v156, v165
	v_max_f32_e32 v156, v156, v165
	v_min_f32_e32 v165, v157, v163
	v_max_f32_e32 v157, v157, v163
	v_min_f32_e32 v163, v158, v165
	v_max_f32_e32 v158, v158, v165
	v_min_f32_e32 v165, v159, v163
	v_max_f32_e32 v159, v159, v163
	v_min_f32_e32 v163, v160, v165
	v_max_f32_e32 v160, v160, v165
	v_min_f32_e32 v165, v161, v163
	v_max_f32_e32 v161, v161, v163
	v_max_f32_e32 v162, v162, v165
	v_add_f32_e32 v163, v100, v4
	v_and_or_b32 v163, v163, s0, 1
	v_min_f32_e32 v165, v164, v163
	v_max_f32_e32 v164, v164, v163
	v_min_f32_e32 v163, v149, v165
	v_max_f32_e32 v149, v149, v165
	v_min_f32_e32 v165, v150, v163
	v_max_f32_e32 v150, v150, v163
	v_min_f32_e32 v163, v151, v165
	v_max_f32_e32 v151, v151, v165
	v_min_f32_e32 v165, v152, v163
	v_max_f32_e32 v152, v152, v163
	v_min_f32_e32 v163, v153, v165
	v_max_f32_e32 v153, v153, v165
	v_min_f32_e32 v165, v154, v163
	v_max_f32_e32 v154, v154, v163
	v_min_f32_e32 v163, v155, v165
	v_max_f32_e32 v155, v155, v165
	v_min_f32_e32 v165, v156, v163
	v_max_f32_e32 v156, v156, v163
	v_min_f32_e32 v163, v157, v165
	v_max_f32_e32 v157, v157, v165
	v_min_f32_e32 v165, v158, v163
	v_max_f32_e32 v158, v158, v163
	v_min_f32_e32 v163, v159, v165
	v_max_f32_e32 v159, v159, v165
	v_min_f32_e32 v165, v160, v163
	v_max_f32_e32 v160, v160, v163
	v_min_f32_e32 v163, v161, v165
	v_max_f32_e32 v161, v161, v165
	v_max_f32_e32 v162, v162, v163
	v_add_f32_e32 v163, v100, v7
	v_and_or_b32 v163, v163, s0, 2
	v_min_f32_e32 v165, v149, v163
	v_max_f32_e32 v149, v149, v163
	v_min_f32_e32 v163, v150, v165
	v_max_f32_e32 v150, v150, v165
	v_min_f32_e32 v165, v151, v163
	v_max_f32_e32 v151, v151, v163
	v_min_f32_e32 v163, v152, v165
	v_max_f32_e32 v152, v152, v165
	v_min_f32_e32 v165, v153, v163
	v_max_f32_e32 v153, v153, v163
	v_min_f32_e32 v163, v154, v165
	v_max_f32_e32 v154, v154, v165
	v_min_f32_e32 v165, v155, v163
	v_max_f32_e32 v155, v155, v163
	v_min_f32_e32 v163, v156, v165
	v_max_f32_e32 v156, v156, v165
	v_min_f32_e32 v165, v157, v163
	v_max_f32_e32 v157, v157, v163
	v_min_f32_e32 v163, v158, v165
	v_max_f32_e32 v158, v158, v165
	v_min_f32_e32 v165, v159, v163
	v_max_f32_e32 v159, v159, v163
	v_min_f32_e32 v163, v160, v165
	v_max_f32_e32 v160, v160, v165
	v_min_f32_e32 v165, v161, v163
	v_max_f32_e32 v161, v161, v163
	v_max_f32_e32 v162, v162, v165
	v_add_f32_e32 v163, v100, v8
	v_and_or_b32 v163, v163, s0, 3
	v_min_f32_e32 v165, v150, v163
	v_max_f32_e32 v150, v150, v163
	v_min_f32_e32 v163, v151, v165
	v_max_f32_e32 v151, v151, v165
	v_min_f32_e32 v165, v152, v163
	v_max_f32_e32 v152, v152, v163
	v_min_f32_e32 v163, v153, v165
	v_max_f32_e32 v153, v153, v165
	v_min_f32_e32 v165, v154, v163
	v_max_f32_e32 v154, v154, v163
	v_min_f32_e32 v163, v155, v165
	v_max_f32_e32 v155, v155, v165
	v_min_f32_e32 v165, v156, v163
	v_max_f32_e32 v156, v156, v163
	v_min_f32_e32 v163, v157, v165
	v_max_f32_e32 v157, v157, v165
	v_min_f32_e32 v165, v158, v163
	v_max_f32_e32 v158, v158, v163
; DEV void ce(float& a, float& b) { float hi = fmaxf(a, b), lo = fminf(a, b); a = hi; b = lo; }
; DEV void phase_peer_score(const Params& p, int layer, int M, char* smem) {
;     ...
;     for (int i = 0; i < 16; i++)
; #pragma unroll
;       for (int j = 0; j < 16; j++)
;         if ((i + 1) * (j + 1) <= 16) {
;           float v = L0[i] + L1[j];
;           v = __uint_as_float((__float_as_uint(v) & ~255u) | (unsigned)(i * 16 + j));
; #pragma unroll
;           for (int t = 0; t < 16; t++)
;             if (t >= (i + 1) * (j + 1) - 1) ce(R[t], v);
;         }
	v_min_f32_e32 v163, v159, v165
	v_max_f32_e32 v159, v159, v165
	v_min_f32_e32 v165, v160, v163
	v_max_f32_e32 v160, v160, v163
	v_min_f32_e32 v163, v161, v165
	v_max_f32_e32 v161, v161, v165
	v_max_f32_e32 v162, v162, v163
	v_add_f32_e32 v163, v100, v9
	v_and_or_b32 v163, v163, s0, 4
	v_min_f32_e32 v165, v151, v163
	v_max_f32_e32 v151, v151, v163
	v_min_f32_e32 v163, v152, v165
	v_max_f32_e32 v152, v152, v165
	v_min_f32_e32 v165, v153, v163
	v_max_f32_e32 v153, v153, v163
	v_min_f32_e32 v163, v154, v165
	v_max_f32_e32 v154, v154, v165
	v_min_f32_e32 v165, v155, v163
	v_max_f32_e32 v155, v155, v163
	v_min_f32_e32 v163, v156, v165
	v_max_f32_e32 v156, v156, v165
	v_min_f32_e32 v165, v157, v163
	v_max_f32_e32 v157, v157, v163
	v_min_f32_e32 v163, v158, v165
	v_max_f32_e32 v158, v158, v165
	v_min_f32_e32 v165, v159, v163
	v_max_f32_e32 v159, v159, v163
	v_min_f32_e32 v163, v160, v165
	v_max_f32_e32 v160, v160, v165
	v_min_f32_e32 v165, v161, v163
	v_max_f32_e32 v161, v161, v163
	v_max_f32_e32 v162, v162, v165
	v_add_f32_e32 v163, v100, v12
	v_and_or_b32 v163, v163, s0, 5
	v_min_f32_e32 v165, v152, v163
	v_max_f32_e32 v152, v152, v163
	v_min_f32_e32 v163, v153, v165
	v_max_f32_e32 v153, v153, v165
	v_min_f32_e32 v165, v154, v163
	v_max_f32_e32 v154, v154, v163
	v_min_f32_e32 v163, v155, v165
	v_max_f32_e32 v155, v155, v165
	v_min_f32_e32 v165, v156, v163
	v_max_f32_e32 v156, v156, v163
	v_min_f32_e32 v163, v157, v165
	v_max_f32_e32 v157, v157, v165
	v_min_f32_e32 v165, v158, v163
	v_max_f32_e32 v158, v158, v163
	v_min_f32_e32 v163, v159, v165
	v_max_f32_e32 v159, v159, v165
	v_min_f32_e32 v165, v160, v163
	v_max_f32_e32 v160, v160, v163
	v_min_f32_e32 v163, v161, v165
	v_max_f32_e32 v161, v161, v165
	v_max_f32_e32 v162, v162, v163
	v_add_f32_e32 v163, v100, v11
	v_and_or_b32 v163, v163, s0, 6
	v_min_f32_e32 v165, v153, v163
	v_max_f32_e32 v153, v153, v163
	v_min_f32_e32 v163, v154, v165
	v_max_f32_e32 v154, v154, v165
	v_min_f32_e32 v165, v155, v163
	v_max_f32_e32 v155, v155, v163
	v_min_f32_e32 v163, v156, v165
	v_max_f32_e32 v156, v156, v165
	v_min_f32_e32 v165, v157, v163
	v_max_f32_e32 v157, v157, v163
	v_min_f32_e32 v163, v158, v165
	v_max_f32_e32 v158, v158, v165
	v_min_f32_e32 v165, v159, v163
	v_max_f32_e32 v159, v159, v163
	v_min_f32_e32 v163, v160, v165
	v_max_f32_e32 v160, v160, v165
	v_min_f32_e32 v165, v161, v163
	v_max_f32_e32 v161, v161, v163
	v_max_f32_e32 v162, v162, v165
	v_add_f32_e32 v163, v100, v10
	v_and_or_b32 v163, v163, s0, 7
	v_min_f32_e32 v165, v154, v163
	v_max_f32_e32 v154, v154, v163
	v_min_f32_e32 v163, v155, v165
	v_max_f32_e32 v155, v155, v165
	v_min_f32_e32 v165, v156, v163
	v_max_f32_e32 v156, v156, v163
	v_min_f32_e32 v163, v157, v165
	v_max_f32_e32 v157, v157, v165
	v_min_f32_e32 v165, v158, v163
	v_max_f32_e32 v158, v158, v163
	v_min_f32_e32 v163, v159, v165
	v_max_f32_e32 v159, v159, v165
	v_min_f32_e32 v165, v160, v163
	v_max_f32_e32 v160, v160, v163
	v_min_f32_e32 v163, v161, v165
	v_max_f32_e32 v161, v161, v165
	v_max_f32_e32 v162, v162, v163
	v_add_f32_e32 v163, v100, v20
	v_and_or_b32 v163, v163, s0, 8
	v_min_f32_e32 v165, v155, v163
	v_max_f32_e32 v155, v155, v163
	v_min_f32_e32 v163, v156, v165
	v_max_f32_e32 v156, v156, v165
	v_min_f32_e32 v165, v157, v163
	v_max_f32_e32 v157, v157, v163
	v_min_f32_e32 v163, v158, v165
	v_max_f32_e32 v158, v158, v165
	v_min_f32_e32 v165, v159, v163
	v_max_f32_e32 v159, v159, v163
	v_min_f32_e32 v163, v160, v165
	v_max_f32_e32 v160, v160, v165
	v_min_f32_e32 v165, v161, v163
	v_max_f32_e32 v161, v161, v163
	v_max_f32_e32 v162, v162, v165
	v_add_f32_e32 v163, v100, v17
	v_and_or_b32 v163, v163, s0, 9
	v_min_f32_e32 v165, v156, v163
	v_max_f32_e32 v156, v156, v163
	v_min_f32_e32 v163, v157, v165
	v_max_f32_e32 v157, v157, v165
	v_min_f32_e32 v165, v158, v163
	v_max_f32_e32 v158, v158, v163
	v_min_f32_e32 v163, v159, v165
	v_max_f32_e32 v159, v159, v165
	v_min_f32_e32 v165, v160, v163
	v_max_f32_e32 v160, v160, v163
	v_min_f32_e32 v163, v161, v165
	v_max_f32_e32 v161, v161, v165
	v_max_f32_e32 v162, v162, v163
	v_add_f32_e32 v163, v100, v16
	v_and_or_b32 v163, v163, s0, 10
	v_min_f32_e32 v165, v157, v163
	v_max_f32_e32 v157, v157, v163
	v_min_f32_e32 v163, v158, v165
	v_max_f32_e32 v158, v158, v165
	v_min_f32_e32 v165, v159, v163
	v_max_f32_e32 v159, v159, v163
	v_min_f32_e32 v163, v160, v165
	v_max_f32_e32 v160, v160, v165
	v_min_f32_e32 v165, v161, v163
	v_max_f32_e32 v161, v161, v163
	v_max_f32_e32 v162, v162, v165
	v_add_f32_e32 v163, v100, v15
	v_and_or_b32 v163, v163, s0, 11
	v_min_f32_e32 v165, v158, v163
	v_max_f32_e32 v158, v158, v163
	v_min_f32_e32 v163, v159, v165
	v_max_f32_e32 v159, v159, v165
	v_min_f32_e32 v165, v160, v163
	v_max_f32_e32 v160, v160, v163
	v_min_f32_e32 v163, v161, v165
	v_max_f32_e32 v161, v161, v165
	v_max_f32_e32 v162, v162, v163
	v_add_f32_e32 v163, v100, v14
	v_and_or_b32 v163, v163, s0, 12
	v_min_f32_e32 v165, v159, v163
	v_max_f32_e32 v159, v159, v163
	v_min_f32_e32 v163, v160, v165
	v_max_f32_e32 v160, v160, v165
	v_min_f32_e32 v165, v161, v163
	v_max_f32_e32 v161, v161, v163
	v_max_f32_e32 v162, v162, v165
	v_add_f32_e32 v163, v100, v13
	v_and_or_b32 v163, v163, s0, 13
	v_min_f32_e32 v165, v160, v163
	v_max_f32_e32 v160, v160, v163
	v_min_f32_e32 v163, v161, v165
	v_max_f32_e32 v161, v161, v165
	v_max_f32_e32 v162, v162, v163
	v_add_f32_e32 v163, v100, v6
	v_and_or_b32 v163, v163, s0, 14
	v_min_f32_e32 v165, v161, v163
	v_max_f32_e32 v161, v161, v163
	v_max_f32_e32 v162, v162, v165
	v_add_f32_e32 v163, v100, v5
	v_and_or_b32 v163, v163, s0, 15
	v_max_f32_e32 v162, v162, v163
	v_add_f32_e32 v163, v91, v2
	v_and_or_b32 v163, v163, s0, 16
; DEV void ce(float& a, float& b) { float hi = fmaxf(a, b), lo = fminf(a, b); a = hi; b = lo; }
; DEV void phase_peer_score(const Params& p, int layer, int M, char* smem) {
;     ...
;     for (int i = 0; i < 16; i++)
; #pragma unroll
;       for (int j = 0; j < 16; j++)
;         if ((i + 1) * (j + 1) <= 16) {
;           float v = L0[i] + L1[j];
;           v = __uint_as_float((__float_as_uint(v) & ~255u) | (unsigned)(i * 16 + j));
; #pragma unroll
;           for (int t = 0; t < 16; t++)
;             if (t >= (i + 1) * (j + 1) - 1) ce(R[t], v);
;         }
	v_min_f32_e32 v165, v164, v163
	v_max_f32_e32 v164, v164, v163
	v_min_f32_e32 v163, v149, v165
	v_max_f32_e32 v149, v149, v165
	v_min_f32_e32 v165, v150, v163
	v_max_f32_e32 v150, v150, v163
	v_min_f32_e32 v163, v151, v165
	v_max_f32_e32 v151, v151, v165
	v_min_f32_e32 v165, v152, v163
	v_max_f32_e32 v152, v152, v163
	v_min_f32_e32 v163, v153, v165
	v_max_f32_e32 v153, v153, v165
	v_min_f32_e32 v165, v154, v163
	v_max_f32_e32 v154, v154, v163
	v_min_f32_e32 v163, v155, v165
	v_max_f32_e32 v155, v155, v165
	v_min_f32_e32 v165, v156, v163
	v_max_f32_e32 v156, v156, v163
	v_min_f32_e32 v163, v157, v165
	v_max_f32_e32 v157, v157, v165
	v_min_f32_e32 v165, v158, v163
	v_max_f32_e32 v158, v158, v163
	v_min_f32_e32 v163, v159, v165
	v_max_f32_e32 v159, v159, v165
	v_min_f32_e32 v165, v160, v163
	v_max_f32_e32 v160, v160, v163
	v_min_f32_e32 v163, v161, v165
	v_max_f32_e32 v161, v161, v165
	v_max_f32_e32 v162, v162, v163
	v_add_f32_e32 v163, v91, v4
	v_and_or_b32 v163, v163, s0, 17
	v_min_f32_e32 v165, v150, v163
	v_max_f32_e32 v150, v150, v163
	v_min_f32_e32 v163, v151, v165
	v_max_f32_e32 v151, v151, v165
	v_min_f32_e32 v165, v152, v163
	v_max_f32_e32 v152, v152, v163
	v_min_f32_e32 v163, v153, v165
	v_max_f32_e32 v153, v153, v165
	v_min_f32_e32 v165, v154, v163
	v_max_f32_e32 v154, v154, v163
	v_min_f32_e32 v163, v155, v165
	v_max_f32_e32 v155, v155, v165
	v_min_f32_e32 v165, v156, v163
	v_max_f32_e32 v156, v156, v163
	v_min_f32_e32 v163, v157, v165
	v_max_f32_e32 v157, v157, v165
	v_min_f32_e32 v165, v158, v163
	v_max_f32_e32 v158, v158, v163
	v_min_f32_e32 v163, v159, v165
	v_max_f32_e32 v159, v159, v165
	v_min_f32_e32 v165, v160, v163
	v_max_f32_e32 v160, v160, v163
	v_min_f32_e32 v163, v161, v165
	v_max_f32_e32 v161, v161, v165
	v_max_f32_e32 v162, v162, v163
	v_add_f32_e32 v163, v91, v7
	v_and_or_b32 v163, v163, s0, 18
	v_min_f32_e32 v165, v152, v163
	v_max_f32_e32 v152, v152, v163
	v_min_f32_e32 v163, v153, v165
	v_max_f32_e32 v153, v153, v165
	v_min_f32_e32 v165, v154, v163
	v_max_f32_e32 v154, v154, v163
	v_min_f32_e32 v163, v155, v165
	v_max_f32_e32 v155, v155, v165
	v_min_f32_e32 v165, v156, v163
	v_max_f32_e32 v156, v156, v163
	v_min_f32_e32 v163, v157, v165
	v_max_f32_e32 v157, v157, v165
	v_min_f32_e32 v165, v158, v163
	v_max_f32_e32 v158, v158, v163
	v_min_f32_e32 v163, v159, v165
	v_max_f32_e32 v159, v159, v165
	v_min_f32_e32 v165, v160, v163
	v_max_f32_e32 v160, v160, v163
	v_min_f32_e32 v163, v161, v165
	v_max_f32_e32 v161, v161, v165
	v_max_f32_e32 v162, v162, v163
	v_add_f32_e32 v163, v91, v8
	v_and_or_b32 v163, v163, s0, 19
	v_min_f32_e32 v165, v154, v163
	v_max_f32_e32 v154, v154, v163
	v_min_f32_e32 v163, v155, v165
	v_max_f32_e32 v155, v155, v165
	v_min_f32_e32 v165, v156, v163
	v_max_f32_e32 v156, v156, v163
	v_min_f32_e32 v163, v157, v165
	v_max_f32_e32 v157, v157, v165
	v_min_f32_e32 v165, v158, v163
	v_max_f32_e32 v158, v158, v163
	v_min_f32_e32 v163, v159, v165
	v_max_f32_e32 v159, v159, v165
	v_min_f32_e32 v165, v160, v163
	v_max_f32_e32 v160, v160, v163
	v_min_f32_e32 v163, v161, v165
	v_max_f32_e32 v161, v161, v165
	v_max_f32_e32 v162, v162, v163
	v_add_f32_e32 v163, v91, v9
	v_and_or_b32 v163, v163, s0, 20
	v_min_f32_e32 v165, v156, v163
	v_max_f32_e32 v156, v156, v163
	v_min_f32_e32 v163, v157, v165
	v_max_f32_e32 v157, v157, v165
	v_min_f32_e32 v165, v158, v163
	v_max_f32_e32 v158, v158, v163
	v_min_f32_e32 v163, v159, v165
	v_max_f32_e32 v159, v159, v165
	v_min_f32_e32 v165, v160, v163
	v_max_f32_e32 v160, v160, v163
	v_min_f32_e32 v163, v161, v165
	v_max_f32_e32 v161, v161, v165
	v_max_f32_e32 v162, v162, v163
	v_add_f32_e32 v163, v91, v12
	v_and_or_b32 v163, v163, s0, 21
	v_min_f32_e32 v165, v158, v163
	v_max_f32_e32 v158, v158, v163
	v_min_f32_e32 v163, v159, v165
	v_max_f32_e32 v159, v159, v165
	v_min_f32_e32 v165, v160, v163
	v_max_f32_e32 v160, v160, v163
	v_min_f32_e32 v163, v161, v165
	v_max_f32_e32 v161, v161, v165
	v_max_f32_e32 v162, v162, v163
	v_add_f32_e32 v163, v91, v11
	v_and_or_b32 v163, v163, s0, 22
	v_min_f32_e32 v165, v160, v163
	v_max_f32_e32 v160, v160, v163
	v_min_f32_e32 v163, v161, v165
	v_max_f32_e32 v161, v161, v165
	v_max_f32_e32 v162, v162, v163
	v_add_f32_e32 v163, v91, v10
	v_and_or_b32 v163, v163, s0, 23
	v_max_f32_e32 v162, v162, v163
	v_add_f32_e32 v163, v87, v2
	v_and_or_b32 v163, v163, s0, 32
	v_min_f32_e32 v165, v149, v163
	v_max_f32_e32 v149, v149, v163
	v_min_f32_e32 v163, v150, v165
	v_max_f32_e32 v150, v150, v165
	v_min_f32_e32 v165, v151, v163
	v_max_f32_e32 v151, v151, v163
	v_min_f32_e32 v163, v152, v165
	v_max_f32_e32 v152, v152, v165
	v_min_f32_e32 v165, v153, v163
	v_max_f32_e32 v153, v153, v163
	v_min_f32_e32 v163, v154, v165
	v_max_f32_e32 v154, v154, v165
	v_min_f32_e32 v165, v155, v163
	v_max_f32_e32 v155, v155, v163
	v_min_f32_e32 v163, v156, v165
	v_max_f32_e32 v156, v156, v165
	v_min_f32_e32 v165, v157, v163
	v_max_f32_e32 v157, v157, v163
	v_min_f32_e32 v163, v158, v165
	v_max_f32_e32 v158, v158, v165
	v_min_f32_e32 v165, v159, v163
	v_max_f32_e32 v159, v159, v163
	v_min_f32_e32 v163, v160, v165
	v_max_f32_e32 v160, v160, v165
	v_min_f32_e32 v165, v161, v163
	v_max_f32_e32 v161, v161, v163
	v_max_f32_e32 v162, v162, v165
	v_add_f32_e32 v163, v87, v4
	v_and_or_b32 v163, v163, s0, 33
	v_min_f32_e32 v165, v152, v163
	v_max_f32_e32 v152, v152, v163
	v_min_f32_e32 v163, v153, v165
	v_max_f32_e32 v153, v153, v165
	v_min_f32_e32 v165, v154, v163
	v_max_f32_e32 v154, v154, v163
	v_min_f32_e32 v163, v155, v165
	v_max_f32_e32 v155, v155, v165
	v_min_f32_e32 v165, v156, v163
	v_max_f32_e32 v156, v156, v163
	v_min_f32_e32 v163, v157, v165
	v_max_f32_e32 v157, v157, v165
; DEV void ce(float& a, float& b) { float hi = fmaxf(a, b), lo = fminf(a, b); a = hi; b = lo; }
; DEV void phase_peer_score(const Params& p, int layer, int M, char* smem) {
;     ...
;     for (int i = 0; i < 16; i++)
; #pragma unroll
;       for (int j = 0; j < 16; j++)
;         if ((i + 1) * (j + 1) <= 16) {
;           float v = L0[i] + L1[j];
;           v = __uint_as_float((__float_as_uint(v) & ~255u) | (unsigned)(i * 16 + j));
; #pragma unroll
;           for (int t = 0; t < 16; t++)
;             if (t >= (i + 1) * (j + 1) - 1) ce(R[t], v);
;         }
	v_min_f32_e32 v165, v158, v163
	v_max_f32_e32 v158, v158, v163
	v_min_f32_e32 v163, v159, v165
	v_max_f32_e32 v159, v159, v165
	v_min_f32_e32 v165, v160, v163
	v_max_f32_e32 v160, v160, v163
	v_min_f32_e32 v163, v161, v165
	v_max_f32_e32 v161, v161, v165
	v_max_f32_e32 v162, v162, v163
	v_add_f32_e32 v163, v87, v7
	v_and_or_b32 v163, v163, s0, 34
	v_min_f32_e32 v165, v155, v163
	v_max_f32_e32 v155, v155, v163
	v_min_f32_e32 v163, v156, v165
	v_max_f32_e32 v156, v156, v165
	v_min_f32_e32 v165, v157, v163
	v_max_f32_e32 v157, v157, v163
	v_min_f32_e32 v163, v158, v165
	v_max_f32_e32 v158, v158, v165
	v_min_f32_e32 v165, v159, v163
	v_max_f32_e32 v159, v159, v163
	v_min_f32_e32 v163, v160, v165
	v_max_f32_e32 v160, v160, v165
	v_min_f32_e32 v165, v161, v163
	v_max_f32_e32 v161, v161, v163
	v_max_f32_e32 v162, v162, v165
	v_add_f32_e32 v163, v87, v8
	v_and_or_b32 v163, v163, s0, 35
	v_min_f32_e32 v165, v158, v163
	v_max_f32_e32 v158, v158, v163
	v_min_f32_e32 v163, v159, v165
	v_max_f32_e32 v159, v159, v165
	v_min_f32_e32 v165, v160, v163
	v_max_f32_e32 v160, v160, v163
	v_min_f32_e32 v163, v161, v165
	v_max_f32_e32 v161, v161, v165
	v_max_f32_e32 v162, v162, v163
	v_add_f32_e32 v163, v87, v9
	v_and_or_b32 v163, v163, s0, 36
	v_min_f32_e32 v165, v161, v163
	v_max_f32_e32 v161, v161, v163
	v_max_f32_e32 v162, v162, v165
	v_add_f32_e32 v163, v83, v2
	v_and_or_b32 v163, v163, s0, 48
	v_min_f32_e32 v165, v150, v163
	v_max_f32_e32 v150, v150, v163
	v_min_f32_e32 v163, v151, v165
	v_max_f32_e32 v151, v151, v165
	v_min_f32_e32 v165, v152, v163
	v_max_f32_e32 v152, v152, v163
	v_min_f32_e32 v163, v153, v165
	v_max_f32_e32 v153, v153, v165
	v_min_f32_e32 v165, v154, v163
	v_max_f32_e32 v154, v154, v163
	v_min_f32_e32 v163, v155, v165
	v_max_f32_e32 v155, v155, v165
	v_min_f32_e32 v165, v156, v163
	v_max_f32_e32 v156, v156, v163
	v_min_f32_e32 v163, v157, v165
	v_max_f32_e32 v157, v157, v165
	v_min_f32_e32 v165, v158, v163
	v_max_f32_e32 v158, v158, v163
	v_min_f32_e32 v163, v159, v165
	v_max_f32_e32 v159, v159, v165
	v_min_f32_e32 v165, v160, v163
	v_max_f32_e32 v160, v160, v163
	v_min_f32_e32 v163, v161, v165
	v_max_f32_e32 v161, v161, v165
	v_max_f32_e32 v162, v162, v163
	v_add_f32_e32 v163, v83, v4
	v_and_or_b32 v163, v163, s0, 49
	v_min_f32_e32 v165, v154, v163
	v_max_f32_e32 v154, v154, v163
	v_min_f32_e32 v163, v155, v165
	v_max_f32_e32 v155, v155, v165
	v_min_f32_e32 v165, v156, v163
	v_max_f32_e32 v156, v156, v163
	v_min_f32_e32 v163, v157, v165
	v_max_f32_e32 v157, v157, v165
	v_min_f32_e32 v165, v158, v163
	v_max_f32_e32 v158, v158, v163
	v_min_f32_e32 v163, v159, v165
	v_max_f32_e32 v159, v159, v165
	v_min_f32_e32 v165, v160, v163
	v_max_f32_e32 v160, v160, v163
	v_min_f32_e32 v163, v161, v165
	v_max_f32_e32 v161, v161, v165
	v_max_f32_e32 v162, v162, v163
	v_add_f32_e32 v163, v83, v7
	v_and_or_b32 v163, v163, s0, 50
	v_min_f32_e32 v165, v158, v163
	v_max_f32_e32 v158, v158, v163
	v_min_f32_e32 v163, v159, v165
	v_max_f32_e32 v159, v159, v165
	v_min_f32_e32 v165, v160, v163
	v_max_f32_e32 v160, v160, v163
	v_min_f32_e32 v163, v161, v165
	v_max_f32_e32 v161, v161, v165
	v_max_f32_e32 v162, v162, v163
	v_add_f32_e32 v163, v83, v8
	v_and_or_b32 v163, v163, s0, 51
	v_max_f32_e32 v162, v162, v163
	v_add_f32_e32 v163, v79, v2
	v_and_or_b32 v163, v163, s0, 64
	v_min_f32_e32 v165, v151, v163
	v_max_f32_e32 v151, v151, v163
	v_min_f32_e32 v163, v152, v165
	v_max_f32_e32 v152, v152, v165
	v_min_f32_e32 v165, v153, v163
	v_max_f32_e32 v153, v153, v163
	v_min_f32_e32 v163, v154, v165
	v_max_f32_e32 v154, v154, v165
	v_min_f32_e32 v165, v155, v163
	v_max_f32_e32 v155, v155, v163
	v_min_f32_e32 v163, v156, v165
	v_max_f32_e32 v156, v156, v165
	v_min_f32_e32 v165, v157, v163
	v_max_f32_e32 v157, v157, v163
	v_min_f32_e32 v163, v158, v165
	v_max_f32_e32 v158, v158, v165
	v_min_f32_e32 v165, v159, v163
	v_max_f32_e32 v159, v159, v163
	v_min_f32_e32 v163, v160, v165
	v_max_f32_e32 v160, v160, v165
	v_min_f32_e32 v165, v161, v163
	v_max_f32_e32 v161, v161, v163
	v_max_f32_e32 v162, v162, v165
	v_add_f32_e32 v163, v79, v4
	v_and_b32_e32 v163, 0xffffff00, v163
	v_or_b32_e32 v163, 0x41, v163
	v_min_f32_e32 v165, v156, v163
	v_max_f32_e32 v156, v156, v163
	v_min_f32_e32 v163, v157, v165
	v_max_f32_e32 v157, v157, v165
	v_min_f32_e32 v165, v158, v163
	v_max_f32_e32 v158, v158, v163
	v_min_f32_e32 v163, v159, v165
	v_max_f32_e32 v159, v159, v165
	v_min_f32_e32 v165, v160, v163
	v_max_f32_e32 v160, v160, v163
	v_min_f32_e32 v163, v161, v165
	v_max_f32_e32 v161, v161, v165
	v_max_f32_e32 v162, v162, v163
	v_add_f32_e32 v163, v79, v7
	v_and_b32_e32 v163, 0xffffff00, v163
	v_or_b32_e32 v163, 0x42, v163
	v_min_f32_e32 v165, v161, v163
	v_max_f32_e32 v161, v161, v163
	v_max_f32_e32 v162, v162, v165
	v_add_f32_e32 v163, v75, v2
	v_and_b32_e32 v163, 0xffffff00, v163
	v_or_b32_e32 v163, 0x50, v163
	v_min_f32_e32 v165, v152, v163
	v_max_f32_e32 v152, v152, v163
	v_min_f32_e32 v163, v153, v165
	v_max_f32_e32 v153, v153, v165
	v_min_f32_e32 v165, v154, v163
	v_max_f32_e32 v154, v154, v163
	v_min_f32_e32 v163, v155, v165
	v_max_f32_e32 v155, v155, v165
	v_min_f32_e32 v165, v156, v163
	v_max_f32_e32 v156, v156, v163
	v_min_f32_e32 v163, v157, v165
	v_max_f32_e32 v157, v157, v165
	v_min_f32_e32 v165, v158, v163
	v_max_f32_e32 v158, v158, v163
	v_min_f32_e32 v163, v159, v165
	v_max_f32_e32 v159, v159, v165
	v_min_f32_e32 v165, v160, v163
	v_max_f32_e32 v160, v160, v163
	v_min_f32_e32 v163, v161, v165
	v_max_f32_e32 v161, v161, v165
	v_max_f32_e32 v162, v162, v163
	v_add_f32_e32 v163, v75, v4
	v_and_b32_e32 v163, 0xffffff00, v163
	v_or_b32_e32 v163, 0x51, v163
; DEV void ce(float& a, float& b) { float hi = fmaxf(a, b), lo = fminf(a, b); a = hi; b = lo; }
; DEV void phase_peer_score(const Params& p, int layer, int M, char* smem) {
;     ...
;     for (int i = 0; i < 16; i++)
; #pragma unroll
;       for (int j = 0; j < 16; j++)
;         if ((i + 1) * (j + 1) <= 16) {
;           float v = L0[i] + L1[j];
;           v = __uint_as_float((__float_as_uint(v) & ~255u) | (unsigned)(i * 16 + j));
; #pragma unroll
;           for (int t = 0; t < 16; t++)
;             if (t >= (i + 1) * (j + 1) - 1) ce(R[t], v);
;         }
	v_min_f32_e32 v165, v158, v163
	v_max_f32_e32 v158, v158, v163
	v_min_f32_e32 v163, v159, v165
	v_max_f32_e32 v159, v159, v165
	v_min_f32_e32 v165, v160, v163
	v_max_f32_e32 v160, v160, v163
	v_min_f32_e32 v163, v161, v165
	v_max_f32_e32 v161, v161, v165
	v_max_f32_e32 v162, v162, v163
	v_add_f32_e32 v163, v71, v2
	v_and_b32_e32 v163, 0xffffff00, v163
	v_or_b32_e32 v163, 0x60, v163
	v_min_f32_e32 v165, v153, v163
	v_max_f32_e32 v153, v153, v163
	v_min_f32_e32 v163, v154, v165
	v_max_f32_e32 v154, v154, v165
	v_min_f32_e32 v165, v155, v163
	v_max_f32_e32 v155, v155, v163
	v_min_f32_e32 v163, v156, v165
	v_max_f32_e32 v156, v156, v165
	v_min_f32_e32 v165, v157, v163
	v_max_f32_e32 v157, v157, v163
	v_min_f32_e32 v163, v158, v165
	v_max_f32_e32 v158, v158, v165
	v_min_f32_e32 v165, v159, v163
	v_max_f32_e32 v159, v159, v163
	v_min_f32_e32 v163, v160, v165
	v_max_f32_e32 v160, v160, v165
	v_min_f32_e32 v165, v161, v163
	v_max_f32_e32 v161, v161, v163
	v_max_f32_e32 v162, v162, v165
	v_add_f32_e32 v163, v71, v4
	v_and_b32_e32 v163, 0xffffff00, v163
	v_or_b32_e32 v163, 0x61, v163
	v_min_f32_e32 v165, v160, v163
	v_max_f32_e32 v160, v160, v163
	v_min_f32_e32 v163, v161, v165
	v_max_f32_e32 v161, v161, v165
	v_max_f32_e32 v162, v162, v163
	v_add_f32_e32 v163, v63, v2
	v_and_b32_e32 v163, 0xffffff00, v163
	v_or_b32_e32 v163, 0x70, v163
	v_min_f32_e32 v165, v154, v163
	v_max_f32_e32 v154, v154, v163
	v_min_f32_e32 v163, v155, v165
	v_max_f32_e32 v155, v155, v165
	v_min_f32_e32 v165, v156, v163
	v_max_f32_e32 v156, v156, v163
	v_min_f32_e32 v163, v157, v165
	v_max_f32_e32 v157, v157, v165
	v_min_f32_e32 v165, v158, v163
	v_max_f32_e32 v158, v158, v163
	v_min_f32_e32 v163, v159, v165
	v_max_f32_e32 v159, v159, v165
	v_min_f32_e32 v165, v160, v163
	v_max_f32_e32 v160, v160, v163
	v_min_f32_e32 v163, v161, v165
	v_max_f32_e32 v161, v161, v165
	v_max_f32_e32 v162, v162, v163
	v_add_f32_e32 v163, v63, v4
	v_and_b32_e32 v163, 0xffffff00, v163
	v_or_b32_e32 v163, 0x71, v163
	v_max_f32_e32 v162, v162, v163
	v_add_f32_e32 v163, v67, v2
	v_and_b32_e32 v163, 0xffffff00, v163
	v_or_b32_e32 v163, 0x80, v163
	v_min_f32_e32 v165, v155, v163
	v_max_f32_e32 v155, v155, v163
	v_min_f32_e32 v163, v156, v165
	v_max_f32_e32 v156, v156, v165
	v_min_f32_e32 v165, v157, v163
	v_max_f32_e32 v157, v157, v163
	v_min_f32_e32 v163, v158, v165
	v_max_f32_e32 v158, v158, v165
	v_min_f32_e32 v165, v159, v163
	v_max_f32_e32 v159, v159, v163
	v_min_f32_e32 v163, v160, v165
	v_max_f32_e32 v160, v160, v165
	v_min_f32_e32 v165, v161, v163
	v_max_f32_e32 v161, v161, v163
	v_max_f32_e32 v162, v162, v165
	v_add_f32_e32 v163, v59, v2
	v_and_b32_e32 v163, 0xffffff00, v163
	v_or_b32_e32 v163, 0x90, v163
	v_min_f32_e32 v165, v156, v163
	v_max_f32_e32 v156, v156, v163
	v_min_f32_e32 v163, v157, v165
	v_max_f32_e32 v157, v157, v165
	v_min_f32_e32 v165, v158, v163
	v_max_f32_e32 v158, v158, v163
	v_min_f32_e32 v163, v159, v165
	v_max_f32_e32 v159, v159, v165
	v_min_f32_e32 v165, v160, v163
	v_max_f32_e32 v160, v160, v163
	v_min_f32_e32 v163, v161, v165
	v_max_f32_e32 v161, v161, v165
	v_max_f32_e32 v162, v162, v163
	v_add_f32_e32 v163, v55, v2
	v_and_b32_e32 v163, 0xffffff00, v163
	v_or_b32_e32 v163, 0xa0, v163
	v_min_f32_e32 v165, v157, v163
	v_max_f32_e32 v157, v157, v163
	v_min_f32_e32 v163, v158, v165
	v_max_f32_e32 v158, v158, v165
	v_min_f32_e32 v165, v159, v163
	v_max_f32_e32 v159, v159, v163
	v_min_f32_e32 v163, v160, v165
	v_max_f32_e32 v160, v160, v165
	v_min_f32_e32 v165, v161, v163
	v_max_f32_e32 v161, v161, v163
	v_max_f32_e32 v162, v162, v165
	v_add_f32_e32 v163, v47, v2
	v_and_b32_e32 v163, 0xffffff00, v163
	v_or_b32_e32 v163, 0xb0, v163
	v_min_f32_e32 v165, v158, v163
	v_max_f32_e32 v158, v158, v163
	v_min_f32_e32 v163, v159, v165
	v_max_f32_e32 v159, v159, v165
	v_min_f32_e32 v165, v160, v163
	v_max_f32_e32 v160, v160, v163
	v_min_f32_e32 v163, v161, v165
	v_max_f32_e32 v161, v161, v165
	v_max_f32_e32 v162, v162, v163
	v_add_f32_e32 v163, v51, v2
	v_and_b32_e32 v163, 0xffffff00, v163
	v_or_b32_e32 v163, 0xc0, v163
	v_min_f32_e32 v165, v159, v163
	v_max_f32_e32 v159, v159, v163
	v_min_f32_e32 v163, v160, v165
	v_max_f32_e32 v160, v160, v165
	v_min_f32_e32 v165, v161, v163
	v_max_f32_e32 v161, v161, v163
	v_max_f32_e32 v162, v162, v165
	v_add_f32_e32 v163, v39, v2
	v_and_b32_e32 v163, 0xffffff00, v163
	v_or_b32_e32 v163, 0xd0, v163
	v_min_f32_e32 v165, v160, v163
	v_max_f32_e32 v160, v160, v163
	v_min_f32_e32 v163, v161, v165
	v_max_f32_e32 v161, v161, v165
	v_max_f32_e32 v162, v162, v163
	v_add_f32_e32 v163, v43, v2
	v_and_b32_e32 v163, 0xffffff00, v163
	v_or_b32_e32 v163, 0xe0, v163
	v_min_f32_e32 v165, v161, v163
	v_max_f32_e32 v161, v161, v163
	v_max_f32_e32 v162, v162, v165
	v_add_f32_e32 v163, v0, v2
	v_and_b32_e32 v163, 0xffffff00, v163
	v_or_b32_e32 v163, 0xf0, v163
	v_max_f32_e32 v162, v162, v163
; DEV void phase_peer_score(const Params& p, int layer, int M, char* smem) {
;     ...
;     float ev[16]; float sum = 0.f;
; #pragma unroll
;     for (int t = 0; t < 16; t++) { ev[t] = __expf(R[t] - R[0]); sum += ev[t]; }
;     const float inv = 1.f / sum;
;     int eid[16];
; #pragma unroll
;     for (int t = 0; t < 16; t++) {
;       unsigned code = __float_as_uint(R[t]) & 255u;
;       eid[t] = (int)tab[code >> 4] * 128 + (int)tab[16 + (code & 15u)];
;     }
;     if (quad == 0) {
;       int* eo = EIDX + (size_t)m * 128 + h * 16;
;       float* go = GATE + (size_t)m * 128 + h * 16;
;       float* uo = go + (size_t)MT * 128;
;       float us[16], vs[16];
; #pragma unroll
;       for (int t = 0; t < 16; t++) { us[t] = USC[eid[t]]; vs[t] = USC[16384 + eid[t]]; }
.Lmed3_ok_bb_172:
	s_lshl_b32 s0, s18, 3
	s_andn2_b32 s0, s0, 63
	v_add_u32_e32 v18, s0, v117
	s_movk_i32 s0, 0xff00
	v_sub_f32_e32 v5, v164, v148
	v_mul_f32_e32 v5, 0x3fb8aa3b, v5
	v_exp_f32_e32 v101, v5
	v_sub_f32_e32 v5, v149, v148
	v_mul_f32_e32 v5, 0x3fb8aa3b, v5
	v_exp_f32_e32 v104, v5
	v_sub_f32_e32 v5, v150, v148
	v_mul_f32_e32 v5, 0x3fb8aa3b, v5
	v_exp_f32_e32 v105, v5
	v_sub_f32_e32 v5, v151, v148
	v_mul_f32_e32 v5, 0x3fb8aa3b, v5
	v_exp_f32_e32 v102, v5
	v_sub_f32_e32 v5, v152, v148
	v_mul_f32_e32 v5, 0x3fb8aa3b, v5
	v_exp_f32_e32 v103, v5
	v_sub_f32_e32 v5, v153, v148
	v_mul_f32_e32 v5, 0x3fb8aa3b, v5
	v_exp_f32_e32 v110, v5
	v_sub_f32_e32 v5, v154, v148
	v_sub_f32_e32 v3, v148, v148
	v_mul_f32_e32 v5, 0x3fb8aa3b, v5
	v_mul_f32_e32 v3, 0x3fb8aa3b, v3
	v_exp_f32_e32 v111, v5
	v_sub_f32_e32 v5, v155, v148
	v_exp_f32_e32 v100, v3
	v_mul_f32_e32 v5, 0x3fb8aa3b, v5
	v_exp_f32_e32 v112, v5
	v_sub_f32_e32 v5, v156, v148
	v_mul_f32_e32 v5, 0x3fb8aa3b, v5
	v_exp_f32_e32 v113, v5
	v_sub_f32_e32 v5, v157, v148
	v_add_f32_e32 v3, 0, v100
	v_mul_f32_e32 v5, 0x3fb8aa3b, v5
	v_add_f32_e32 v3, v3, v101
	v_exp_f32_e32 v114, v5
	v_sub_f32_e32 v5, v158, v148
	v_add_f32_e32 v3, v3, v104
	v_mul_f32_e32 v5, 0x3fb8aa3b, v5
	v_add_f32_e32 v3, v3, v105
	v_exp_f32_e32 v115, v5
	v_sub_f32_e32 v5, v159, v148
	v_add_f32_e32 v3, v3, v102
	v_mul_f32_e32 v5, 0x3fb8aa3b, v5
	v_add_f32_e32 v3, v3, v103
	v_exp_f32_e32 v106, v5
	v_sub_f32_e32 v5, v160, v148
	v_add_f32_e32 v3, v3, v110
	v_mul_f32_e32 v5, 0x3fb8aa3b, v5
	v_add_f32_e32 v3, v3, v111
	v_exp_f32_e32 v107, v5
	v_sub_f32_e32 v5, v161, v148
	v_add_f32_e32 v3, v3, v112
	v_mul_f32_e32 v5, 0x3fb8aa3b, v5
	v_add_f32_e32 v3, v3, v113
	v_exp_f32_e32 v108, v5
	v_sub_f32_e32 v5, v162, v148
	v_add_f32_e32 v3, v3, v114
	v_mul_f32_e32 v5, 0x3fb8aa3b, v5
	v_add_f32_e32 v3, v3, v115
	v_exp_f32_e32 v109, v5
	v_add_f32_e32 v3, v3, v106
	v_add_f32_e32 v3, v3, v107
	v_add_f32_e32 v3, v3, v108
	v_add_f32_e32 v3, v3, v109
	v_div_scale_f32 v5, s[0:1], v3, v3, 1.0
	v_rcp_f32_e32 v6, v5
	v_ashrrev_i32_e32 v19, 31, v18
	s_mov_b32 s0, 0x10000
	v_lshlrev_b64 v[120:121], 9, v[18:19]
	v_fma_f32 v17, -v5, v6, 1.0
	v_fmac_f32_e32 v6, v17, v6
	v_div_scale_f32 v17, vcc, 1.0, v3, 1.0
	v_mul_f32_e32 v20, v17, v6
	v_fma_f32 v21, -v5, v20, v17
	v_fmac_f32_e32 v20, v21, v6
	v_fma_f32 v5, -v5, v20, v17
	v_div_fmas_f32 v5, v5, v6, v20
	v_div_fixup_f32 v116, v5, v3, 1.0
	v_bfe_u32 v3, v162, 4, 4
	v_and_b32_e32 v2, 15, v162
	v_and_b32_e32 v17, 15, v154
	v_add_u32_e32 v3, v138, v3
	v_add_u32_e32 v2, v138, v2
	v_add_u32_e32 v17, v138, v17
	ds_read_u8 v3, v3
	ds_read_u8 v17, v17 offset:16
	ds_read_u8 v2, v2 offset:16
	v_and_b32_e32 v6, 15, v159
	v_add_u32_e32 v6, v138, v6
	ds_read_u8 v6, v6 offset:16
	v_lshl_add_u64 v[18:19], s[8:9], 0, v[120:121]
	s_waitcnt lgkmcnt(1)
	v_lshl_add_u32 v5, v3, 7, v2
	v_bfe_u32 v2, v161, 4, 4
	v_and_b32_e32 v3, 15, v161
	v_add_u32_e32 v2, v138, v2
	v_add_u32_e32 v3, v138, v3
	ds_read_u8 v2, v2
	ds_read_u8 v3, v3 offset:16
	s_lshl_b32 s52, s19, 6
	v_lshl_add_u64 v[118:119], v[18:19], 0, s[52:53]
	v_lshl_add_u64 v[120:121], s[6:7], 0, v[120:121]
	v_lshl_add_u64 v[120:121], v[120:121], 0, s[52:53]
	s_waitcnt lgkmcnt(0)
	v_lshl_add_u32 v4, v2, 7, v3
	v_bfe_u32 v2, v160, 4, 4
	v_and_b32_e32 v3, 15, v160
	v_add_u32_e32 v2, v138, v2
	v_add_u32_e32 v3, v138, v3
	ds_read_u8 v2, v2
	ds_read_u8 v3, v3 offset:16
	v_and_b32_e32 v7, 15, v158
	v_add_u32_e32 v7, v138, v7
	ds_read_u8 v7, v7 offset:16
	s_waitcnt lgkmcnt(1)
	v_lshl_add_u32 v3, v2, 7, v3
	v_bfe_u32 v2, v159, 4, 4
	v_add_u32_e32 v2, v138, v2
	ds_read_u8 v2, v2
	s_waitcnt lgkmcnt(0)
	v_lshl_add_u32 v2, v2, 7, v6
	v_bfe_u32 v6, v158, 4, 4
	v_add_u32_e32 v6, v138, v6
	ds_read_u8 v6, v6
	s_waitcnt lgkmcnt(0)
	v_lshl_add_u32 v9, v6, 7, v7
	v_bfe_u32 v6, v157, 4, 4
	v_and_b32_e32 v7, 15, v157
	v_add_u32_e32 v6, v138, v6
	v_add_u32_e32 v7, v138, v7
	ds_read_u8 v6, v6
	ds_read_u8 v7, v7 offset:16
	s_waitcnt lgkmcnt(0)
	v_lshl_add_u32 v8, v6, 7, v7
	v_bfe_u32 v6, v156, 4, 4
	v_and_b32_e32 v7, 15, v156
	v_add_u32_e32 v6, v138, v6
	v_add_u32_e32 v7, v138, v7
	ds_read_u8 v6, v6
	ds_read_u8 v7, v7 offset:16
	s_waitcnt lgkmcnt(0)
	v_lshl_add_u32 v7, v6, 7, v7
	v_bfe_u32 v6, v155, 4, 4
	v_and_b32_e32 v13, 15, v155
	v_add_u32_e32 v6, v138, v6
	v_add_u32_e32 v13, v138, v13
	ds_read_u8 v6, v6
	ds_read_u8 v13, v13 offset:16
	s_waitcnt lgkmcnt(0)
	v_lshl_add_u32 v6, v6, 7, v13
	v_bfe_u32 v13, v154, 4, 4
	v_add_u32_e32 v13, v138, v13
	ds_read_u8 v13, v13
	s_waitcnt lgkmcnt(0)
	v_lshl_add_u32 v13, v13, 7, v17
	v_bfe_u32 v17, v153, 4, 4
	v_and_b32_e32 v12, 15, v153
	v_add_u32_e32 v17, v138, v17
	v_add_u32_e32 v12, v138, v12
	ds_read_u8 v17, v17
	ds_read_u8 v12, v12 offset:16
	s_waitcnt lgkmcnt(0)
	v_lshl_add_u32 v12, v17, 7, v12
	v_bfe_u32 v17, v152, 4, 4
	v_and_b32_e32 v11, 15, v152
	v_add_u32_e32 v17, v138, v17
	v_add_u32_e32 v11, v138, v11
	ds_read_u8 v17, v17
	ds_read_u8 v11, v11 offset:16
	s_waitcnt lgkmcnt(0)
	v_lshl_add_u32 v11, v17, 7, v11
	v_bfe_u32 v17, v151, 4, 4
	v_and_b32_e32 v10, 15, v151
	v_add_u32_e32 v17, v138, v17
	v_add_u32_e32 v10, v138, v10
	ds_read_u8 v17, v17
	ds_read_u8 v10, v10 offset:16
	s_waitcnt lgkmcnt(0)
	v_lshl_add_u32 v10, v17, 7, v10
	v_bfe_u32 v17, v150, 4, 4
	v_and_b32_e32 v16, 15, v150
	v_add_u32_e32 v17, v138, v17
	v_add_u32_e32 v16, v138, v16
	ds_read_u8 v17, v17
	ds_read_u8 v16, v16 offset:16
	s_waitcnt lgkmcnt(0)
	v_lshl_add_u32 v17, v17, 7, v16
	v_bfe_u32 v16, v149, 4, 4
	v_and_b32_e32 v15, 15, v149
	v_add_u32_e32 v16, v138, v16
	v_add_u32_e32 v15, v138, v15
	ds_read_u8 v16, v16
	ds_read_u8 v15, v15 offset:16
	s_waitcnt lgkmcnt(0)
; DEV void phase_peer_score(const Params& p, int layer, int M, char* smem) {
;     ...
;     for (int t = 0; t < 16; t++) {
;       unsigned code = __float_as_uint(R[t]) & 255u;
;       eid[t] = (int)tab[code >> 4] * 128 + (int)tab[16 + (code & 15u)];
;     }
;     if (quad == 0) {
;       int* eo = EIDX + (size_t)m * 128 + h * 16;
;       float* go = GATE + (size_t)m * 128 + h * 16;
;       float* uo = go + (size_t)MT * 128;
;       float us[16], vs[16];
; #pragma unroll
;       for (int t = 0; t < 16; t++) { us[t] = USC[eid[t]]; vs[t] = USC[16384 + eid[t]]; }
; #pragma unroll
;       for (int t = 0; t < 16; t += 4) {
;         *(int4*)(eo + t) = make_int4(eid[t], eid[t + 1], eid[t + 2], eid[t + 3]);
;         *(float4*)(go + t) = make_float4(ev[t] * inv * vs[t], ev[t + 1] * inv * vs[t + 1], ev[t + 2] * inv * vs[t + 2], ev[t + 3] * inv * vs[t + 3]);
;         *(float4*)(uo + t) = make_float4(us[t], us[t + 1], us[t + 2], us[t + 3]);
;       }
	v_lshl_add_u32 v16, v16, 7, v15
	v_bfe_u32 v15, v164, 4, 4
	v_and_b32_e32 v14, 15, v164
	v_add_u32_e32 v15, v138, v15
	v_add_u32_e32 v14, v138, v14
	ds_read_u8 v15, v15
	ds_read_u8 v14, v14 offset:16
	s_waitcnt lgkmcnt(0)
	v_lshl_add_u32 v15, v15, 7, v14
	v_bfe_u32 v14, v148, 4, 4
	v_and_b32_e32 v0, 15, v148
	v_add_u32_e32 v14, v138, v14
	v_add_u32_e32 v0, v138, v0
	ds_read_u8 v14, v14
	ds_read_u8 v0, v0 offset:16
	s_waitcnt lgkmcnt(0)
	v_lshl_add_u32 v14, v14, 7, v0
	v_lshlrev_b32_e32 v0, 2, v14
	v_lshl_add_u64 v[20:21], s[10:11], 0, v[0:1]
	v_add_co_u32_e32 v20, vcc, s0, v20
	global_load_dword v18, v0, s[10:11]
	s_nop 0
	v_addc_co_u32_e32 v21, vcc, 0, v21, vcc
	global_load_dword v122, v[20:21], off
	v_lshlrev_b32_e32 v0, 2, v15
	v_lshl_add_u64 v[20:21], s[10:11], 0, v[0:1]
	v_add_co_u32_e32 v20, vcc, s0, v20
	global_load_dword v19, v0, s[10:11]
	s_nop 0
	v_addc_co_u32_e32 v21, vcc, 0, v21, vcc
	global_load_dword v123, v[20:21], off
	v_lshlrev_b32_e32 v0, 2, v16
	v_lshl_add_u64 v[22:23], s[10:11], 0, v[0:1]
	v_add_co_u32_e32 v22, vcc, s0, v22
	global_load_dword v20, v0, s[10:11]
	s_nop 0
	v_addc_co_u32_e32 v23, vcc, 0, v23, vcc
	global_load_dword v126, v[22:23], off
	v_lshlrev_b32_e32 v0, 2, v17
	v_lshl_add_u64 v[22:23], s[10:11], 0, v[0:1]
	v_add_co_u32_e32 v22, vcc, s0, v22
	global_load_dword v21, v0, s[10:11]
	s_nop 0
	v_addc_co_u32_e32 v23, vcc, 0, v23, vcc
	global_load_dword v127, v[22:23], off
	v_lshlrev_b32_e32 v0, 2, v10
	v_lshl_add_u64 v[24:25], s[10:11], 0, v[0:1]
	v_add_co_u32_e32 v24, vcc, s0, v24
	global_load_dword v22, v0, s[10:11]
	s_nop 0
	v_addc_co_u32_e32 v25, vcc, 0, v25, vcc
	global_load_dword v124, v[24:25], off
	v_lshlrev_b32_e32 v0, 2, v11
	v_lshl_add_u64 v[24:25], s[10:11], 0, v[0:1]
	v_add_co_u32_e32 v24, vcc, s0, v24
	global_load_dword v23, v0, s[10:11]
	s_nop 0
	v_addc_co_u32_e32 v25, vcc, 0, v25, vcc
	global_load_dword v125, v[24:25], off
	v_lshlrev_b32_e32 v0, 2, v12
	v_lshl_add_u64 v[26:27], s[10:11], 0, v[0:1]
	v_add_co_u32_e32 v26, vcc, s0, v26
	global_load_dword v24, v0, s[10:11]
	s_nop 0
	v_addc_co_u32_e32 v27, vcc, 0, v27, vcc
	global_load_dword v128, v[26:27], off
	v_lshlrev_b32_e32 v0, 2, v13
	v_lshl_add_u64 v[26:27], s[10:11], 0, v[0:1]
	v_add_co_u32_e32 v26, vcc, s0, v26
	global_load_dword v25, v0, s[10:11]
	s_nop 0
	v_addc_co_u32_e32 v27, vcc, 0, v27, vcc
	global_load_dword v129, v[26:27], off
	v_lshlrev_b32_e32 v0, 2, v6
	v_lshl_add_u64 v[28:29], s[10:11], 0, v[0:1]
	v_add_co_u32_e32 v28, vcc, s0, v28
	global_load_dword v26, v0, s[10:11]
	s_nop 0
	v_addc_co_u32_e32 v29, vcc, 0, v29, vcc
	global_load_dword v130, v[28:29], off
	v_lshlrev_b32_e32 v0, 2, v7
	v_lshl_add_u64 v[28:29], s[10:11], 0, v[0:1]
	v_add_co_u32_e32 v28, vcc, s0, v28
	global_load_dword v27, v0, s[10:11]
	s_nop 0
	v_addc_co_u32_e32 v29, vcc, 0, v29, vcc
	global_load_dword v131, v[28:29], off
	v_lshlrev_b32_e32 v0, 2, v8
	v_lshl_add_u64 v[30:31], s[10:11], 0, v[0:1]
	v_add_co_u32_e32 v30, vcc, s0, v30
	global_load_dword v28, v0, s[10:11]
	s_nop 0
	v_addc_co_u32_e32 v31, vcc, 0, v31, vcc
	global_load_dword v132, v[30:31], off
	v_lshlrev_b32_e32 v0, 2, v9
	v_lshl_add_u64 v[30:31], s[10:11], 0, v[0:1]
	v_add_co_u32_e32 v30, vcc, s0, v30
	global_load_dword v29, v0, s[10:11]
	s_nop 0
	v_addc_co_u32_e32 v31, vcc, 0, v31, vcc
	global_load_dword v133, v[30:31], off
	v_lshlrev_b32_e32 v0, 2, v2
	v_lshl_add_u64 v[32:33], s[10:11], 0, v[0:1]
	v_add_co_u32_e32 v32, vcc, s0, v32
	global_load_dword v30, v0, s[10:11]
	s_nop 0
	v_addc_co_u32_e32 v33, vcc, 0, v33, vcc
	global_load_dword v134, v[32:33], off
	v_lshlrev_b32_e32 v0, 2, v3
	v_lshl_add_u64 v[32:33], s[10:11], 0, v[0:1]
	v_add_co_u32_e32 v32, vcc, s0, v32
	global_load_dword v31, v0, s[10:11]
	s_nop 0
	v_addc_co_u32_e32 v33, vcc, 0, v33, vcc
	global_load_dword v135, v[32:33], off
	v_lshlrev_b32_e32 v0, 2, v4
	v_lshl_add_u64 v[136:137], s[10:11], 0, v[0:1]
	v_add_co_u32_e32 v136, vcc, s0, v136
	global_load_dword v32, v0, s[10:11]
	s_nop 0
	v_addc_co_u32_e32 v137, vcc, 0, v137, vcc
	global_load_dword v136, v[136:137], off
	v_lshlrev_b32_e32 v0, 2, v5
	v_lshl_add_u64 v[140:141], s[10:11], 0, v[0:1]
	v_add_co_u32_e32 v140, vcc, s0, v140
	global_load_dword v33, v0, s[10:11]
	s_nop 0
	v_addc_co_u32_e32 v141, vcc, 0, v141, vcc
	global_load_dword v137, v[140:141], off
	s_mov_b32 s0, 0x840000
	global_store_dwordx4 v[120:121], v[14:17], off
	s_nop 1
	v_pk_mul_f32 v[14:15], v[100:101], v[116:117] op_sel_hi:[1,0]
	v_pk_mul_f32 v[16:17], v[104:105], v[116:117] op_sel_hi:[1,0]
	s_waitcnt vmcnt(29)
	v_pk_mul_f32 v[14:15], v[14:15], v[122:123]
	s_waitcnt vmcnt(25)
	v_pk_mul_f32 v[16:17], v[16:17], v[126:127]
	global_store_dwordx4 v[118:119], v[14:17], off
	s_nop 1
	v_add_co_u32_e32 v14, vcc, s0, v118
	s_nop 1
	v_addc_co_u32_e32 v15, vcc, 0, v119, vcc
	global_store_dwordx4 v[14:15], v[18:21], off
	global_store_dwordx4 v[120:121], v[10:13], off offset:16
	s_nop 1
	v_pk_mul_f32 v[10:11], v[102:103], v[116:117] op_sel_hi:[1,0]
	v_pk_mul_f32 v[12:13], v[110:111], v[116:117] op_sel_hi:[1,0]
	s_waitcnt vmcnt(24)
	v_pk_mul_f32 v[10:11], v[10:11], v[124:125]
	s_waitcnt vmcnt(20)
	v_pk_mul_f32 v[12:13], v[12:13], v[128:129]
	global_store_dwordx4 v[118:119], v[10:13], off offset:16
	global_store_dwordx4 v[14:15], v[22:25], off offset:16
	global_store_dwordx4 v[120:121], v[6:9], off offset:32
	s_nop 1
	v_pk_mul_f32 v[6:7], v[112:113], v[116:117] op_sel_hi:[1,0]
	v_pk_mul_f32 v[8:9], v[114:115], v[116:117] op_sel_hi:[1,0]
	s_waitcnt vmcnt(19)
	v_pk_mul_f32 v[6:7], v[6:7], v[130:131]
	s_waitcnt vmcnt(15)
	v_pk_mul_f32 v[8:9], v[8:9], v[132:133]
	global_store_dwordx4 v[118:119], v[6:9], off offset:32
	global_store_dwordx4 v[14:15], v[26:29], off offset:32
	global_store_dwordx4 v[120:121], v[2:5], off offset:48
	s_nop 1
	v_pk_mul_f32 v[2:3], v[106:107], v[116:117] op_sel_hi:[1,0]
	v_pk_mul_f32 v[4:5], v[108:109], v[116:117] op_sel_hi:[1,0]
	s_waitcnt vmcnt(14)
	v_pk_mul_f32 v[2:3], v[2:3], v[134:135]
	s_waitcnt vmcnt(10)
	v_pk_mul_f32 v[4:5], v[4:5], v[136:137]
	global_store_dwordx4 v[118:119], v[2:5], off offset:48
	global_store_dwordx4 v[14:15], v[30:33], off offset:48
	s_branch .LBB0_162

; DEV f32x4 mfma16(bf16x8 a, bf16x8 b, f32x4 c) { return __builtin_amdgcn_mfma_f32_16x16x32_bf16(a, b, c, 0, 0, 0); }
; DEV void peer_top16(const bf16_t* __restrict__ pq, const bf16_t* sk  , float (&l)[16]) {
;     ...
; #pragma unroll 1
;   for (int ks = 0; ks < 4; ks++) {
;     const bf16x8 bqk = *(const bf16x8*)(pq + ks * 32 + quad * 8);
; #pragma unroll
;     for (int nt = 0; nt < 8; nt++) {
;       bf16x8 ak = *(const bf16x8*)(sk + (nt * 16 + l15) * 144 + ks * 32 + quad * 8);
;       acc[nt] = mfma16(ak, bqk, acc[nt]);
;     }
;   }
.LBB0_635:
	v_add_u32_e32 v139, 0x10e00, v122
	ds_read_b128 v[164:167], v122 offset:36864
	ds_read_b128 v[168:171], v122 offset:41472
	ds_read_b128 v[172:175], v122 offset:46080
	ds_read_b128 v[176:179], v122 offset:50688
	ds_read_b128 v[180:183], v122 offset:55296
	ds_read_b128 v[184:187], v122 offset:59904
	ds_read_b128 v[188:191], v122 offset:64512
	ds_read_b128 v[128:131], v139
	s_waitcnt vmcnt(3) lgkmcnt(7)
	v_mfma_f32_16x16x32_bf16 v[30:33], v[164:167], v[148:151], v[30:33]
	ds_read_b128 v[164:167], v122 offset:36928
	s_waitcnt lgkmcnt(7)
	v_mfma_f32_16x16x32_bf16 v[22:25], v[168:171], v[148:151], v[22:25]
	ds_read_b128 v[168:171], v122 offset:41536
	s_waitcnt lgkmcnt(7)
	v_mfma_f32_16x16x32_bf16 v[14:17], v[172:175], v[148:151], v[14:17]
	ds_read_b128 v[172:175], v122 offset:46144
	s_waitcnt lgkmcnt(7)
	v_mfma_f32_16x16x32_bf16 v[6:9], v[176:179], v[148:151], v[6:9]
	ds_read_b128 v[176:179], v122 offset:50752
	s_waitcnt lgkmcnt(7)
	v_mfma_f32_16x16x32_bf16 v[26:29], v[180:183], v[148:151], v[26:29]
	ds_read_b128 v[180:183], v122 offset:55360
	s_waitcnt lgkmcnt(7)
	v_mfma_f32_16x16x32_bf16 v[18:21], v[184:187], v[148:151], v[18:21]
	ds_read_b128 v[184:187], v122 offset:59968
	s_waitcnt lgkmcnt(7)
	v_mfma_f32_16x16x32_bf16 v[10:13], v[188:191], v[148:151], v[10:13]
	ds_read_b128 v[188:191], v122 offset:64576
	s_waitcnt lgkmcnt(7)
	v_mfma_f32_16x16x32_bf16 v[2:5], v[128:131], v[148:151], v[2:5]
	ds_read_b128 v[128:131], v139 offset:64
	s_waitcnt vmcnt(2) lgkmcnt(7)
	v_mfma_f32_16x16x32_bf16 v[30:33], v[164:167], v[152:155], v[30:33]
	ds_read_b128 v[164:167], v122 offset:36992
	s_waitcnt lgkmcnt(7)
	v_mfma_f32_16x16x32_bf16 v[22:25], v[168:171], v[152:155], v[22:25]
	ds_read_b128 v[168:171], v122 offset:41600
	s_waitcnt lgkmcnt(7)
	v_mfma_f32_16x16x32_bf16 v[14:17], v[172:175], v[152:155], v[14:17]
	ds_read_b128 v[172:175], v122 offset:46208
	s_waitcnt lgkmcnt(7)
	v_mfma_f32_16x16x32_bf16 v[6:9], v[176:179], v[152:155], v[6:9]
	ds_read_b128 v[176:179], v122 offset:50816
	s_waitcnt lgkmcnt(7)
	v_mfma_f32_16x16x32_bf16 v[26:29], v[180:183], v[152:155], v[26:29]
	ds_read_b128 v[180:183], v122 offset:55424
	s_waitcnt lgkmcnt(7)
	v_mfma_f32_16x16x32_bf16 v[18:21], v[184:187], v[152:155], v[18:21]
	ds_read_b128 v[184:187], v122 offset:60032
	s_waitcnt lgkmcnt(7)
	v_mfma_f32_16x16x32_bf16 v[10:13], v[188:191], v[152:155], v[10:13]
	ds_read_b128 v[188:191], v122 offset:64640
	s_waitcnt lgkmcnt(7)
	v_mfma_f32_16x16x32_bf16 v[2:5], v[128:131], v[152:155], v[2:5]
	ds_read_b128 v[128:131], v139 offset:128
	s_waitcnt vmcnt(1) lgkmcnt(7)
	v_mfma_f32_16x16x32_bf16 v[30:33], v[164:167], v[156:159], v[30:33]
	ds_read_b128 v[164:167], v122 offset:37056
	s_waitcnt lgkmcnt(7)
	v_mfma_f32_16x16x32_bf16 v[22:25], v[168:171], v[156:159], v[22:25]
	ds_read_b128 v[168:171], v122 offset:41664
	s_waitcnt lgkmcnt(7)
	v_mfma_f32_16x16x32_bf16 v[14:17], v[172:175], v[156:159], v[14:17]
	ds_read_b128 v[172:175], v122 offset:46272
	s_waitcnt lgkmcnt(7)
	v_mfma_f32_16x16x32_bf16 v[6:9], v[176:179], v[156:159], v[6:9]
	ds_read_b128 v[176:179], v122 offset:50880
	s_waitcnt lgkmcnt(7)
	v_mfma_f32_16x16x32_bf16 v[26:29], v[180:183], v[156:159], v[26:29]
	ds_read_b128 v[180:183], v122 offset:55488
	s_waitcnt lgkmcnt(7)
	v_mfma_f32_16x16x32_bf16 v[18:21], v[184:187], v[156:159], v[18:21]
	ds_read_b128 v[184:187], v122 offset:60096
	s_waitcnt lgkmcnt(7)
	v_mfma_f32_16x16x32_bf16 v[10:13], v[188:191], v[156:159], v[10:13]
	ds_read_b128 v[188:191], v122 offset:64704
	s_waitcnt lgkmcnt(7)
	v_mfma_f32_16x16x32_bf16 v[2:5], v[128:131], v[156:159], v[2:5]
	ds_read_b128 v[128:131], v139 offset:192
	s_waitcnt vmcnt(0) lgkmcnt(7)
	v_mfma_f32_16x16x32_bf16 v[30:33], v[164:167], v[160:163], v[30:33]
	s_waitcnt lgkmcnt(6)
	v_mfma_f32_16x16x32_bf16 v[22:25], v[168:171], v[160:163], v[22:25]
	s_waitcnt lgkmcnt(5)
	v_mfma_f32_16x16x32_bf16 v[14:17], v[172:175], v[160:163], v[14:17]
	s_waitcnt lgkmcnt(4)
	v_mfma_f32_16x16x32_bf16 v[6:9], v[176:179], v[160:163], v[6:9]
	s_waitcnt lgkmcnt(3)
	v_mfma_f32_16x16x32_bf16 v[26:29], v[180:183], v[160:163], v[26:29]
	s_waitcnt lgkmcnt(2)
	v_mfma_f32_16x16x32_bf16 v[18:21], v[184:187], v[160:163], v[18:21]
	s_waitcnt lgkmcnt(1)
	v_mfma_f32_16x16x32_bf16 v[10:13], v[188:191], v[160:163], v[10:13]
	s_waitcnt lgkmcnt(0)
; DEV void peer_top16(const bf16_t* __restrict__ pq, const bf16_t* sk  , float (&l)[16]) {
;     ...
;   float hi[16];
; #pragma unroll
;   for (int nt = 0; nt < 4; nt++)
; #pragma unroll
;     for (int r = 0; r < 4; r++) {
;       l[nt * 4 + r] = __uint_as_float((__float_as_uint(acc[nt][r]) & ~127u) | (unsigned)(nt * 16 + quad * 4 + r));
;       hi[nt * 4 + r] = __uint_as_float((__float_as_uint(acc[nt + 4][r]) & ~127u) | (unsigned)((nt + 4) * 16 + quad * 4 + r));
;     }
;   sort16_desc(l);
;   sort16_desc(hi);
; #pragma unroll
;   for (int i = 0; i < 16; i++) l[i] = fmaxf(l[i], hi[15 - i]);
	v_mfma_f32_16x16x32_bf16 v[2:5], v[128:131], v[160:163], v[2:5]
	s_movk_i32 s18, 0x100
	v_max_f32_e32 v0, v109, v121
	v_max_f32_e32 v100, v107, v120
	v_max_f32_e32 v101, v105, v119
	v_max_f32_e32 v103, v103, v118
	v_max_f32_e32 v87, v87, v116
	v_max_f32_e32 v79, v79, v115
	v_max_f32_e32 v75, v75, v114
	v_max_f32_e32 v71, v71, v113
	v_max_f32_e32 v67, v67, v112
	v_max_f32_e32 v63, v63, v111
	v_max_f32_e32 v59, v59, v110
	v_max_f32_e32 v55, v55, v108
	v_max_f32_e32 v51, v51, v106
	v_max_f32_e32 v47, v47, v104
	v_max_f32_e32 v43, v43, v91
	v_max_f32_e32 v39, v39, v83
	v_max_f32_e32 v83, v0, v67
	v_min_f32_e32 v0, v0, v67
	v_max_f32_e32 v67, v100, v63
	v_min_f32_e32 v63, v100, v63
	v_max_f32_e32 v91, v101, v59
	v_min_f32_e32 v59, v101, v59
	v_max_f32_e32 v100, v103, v55
	v_min_f32_e32 v55, v103, v55
	v_max_f32_e32 v101, v87, v51
	v_min_f32_e32 v51, v87, v51
	v_max_f32_e32 v87, v79, v47
	v_min_f32_e32 v47, v79, v47
	v_max_f32_e32 v79, v75, v43
	v_min_f32_e32 v43, v75, v43
	v_max_f32_e32 v75, v71, v39
	v_min_f32_e32 v39, v71, v39
	v_max_f32_e32 v71, v83, v101
	v_min_f32_e32 v101, v83, v101
	v_max_f32_e32 v103, v67, v87
	v_min_f32_e32 v67, v67, v87
	v_max_f32_e32 v87, v91, v79
	v_min_f32_e32 v79, v91, v79
	v_max_f32_e32 v91, v100, v75
	v_min_f32_e32 v75, v100, v75
	v_max_f32_e32 v100, v0, v51
	v_min_f32_e32 v0, v0, v51
	v_max_f32_e32 v51, v63, v47
	v_max_f32_e32 v105, v59, v43
	v_min_f32_e32 v43, v59, v43
	v_max_f32_e32 v59, v55, v39
	v_min_f32_e32 v107, v101, v79
	v_min_f32_e32 v108, v67, v75
	v_min_f32_e32 v110, v51, v59
	v_max_f32_e32 v79, v101, v79
	v_max_f32_e32 v67, v67, v75
	v_max_f32_e32 v101, v100, v105
	v_max_f32_e32 v51, v51, v59
	v_min_f32_e32 v75, v79, v67
	v_min_f32_e32 v59, v101, v51
	v_max_f32_e32 v79, v79, v67
	v_max_f32_e32 v67, v101, v51
	v_lshlrev_b32_e32 v101, 2, v102
	s_movk_i32 s8, 0xff80
	v_and_or_b32 v30, v30, s8, v101
	v_and_b32_e32 v27, 0xffffff80, v27
	s_movk_i32 s8, 0x41
	v_or3_b32 v27, v101, v27, s8
	v_and_b32_e32 v28, 0xffffff80, v28
	s_movk_i32 s8, 0x42
	v_or3_b32 v28, v101, v28, s8
	v_and_b32_e32 v29, 0xffffff80, v29
	s_movk_i32 s8, 0x43
	v_or3_b32 v29, v101, v29, s8
	v_and_b32_e32 v18, 0xffffff80, v18
	s_movk_i32 s8, 0x50
	v_or3_b32 v18, v101, v18, s8
	v_and_b32_e32 v19, 0xffffff80, v19
	s_movk_i32 s8, 0x51
	v_or3_b32 v19, v101, v19, s8
	v_and_b32_e32 v20, 0xffffff80, v20
	s_movk_i32 s8, 0x52
	v_or3_b32 v20, v101, v20, s8
	v_and_b32_e32 v21, 0xffffff80, v21
	s_movk_i32 s8, 0x53
	v_or3_b32 v21, v101, v21, s8
	v_and_b32_e32 v10, 0xffffff80, v10
	s_movk_i32 s8, 0x60
	v_or3_b32 v10, v101, v10, s8
	v_and_b32_e32 v11, 0xffffff80, v11
	s_movk_i32 s8, 0x61
	v_or3_b32 v11, v101, v11, s8
	v_and_b32_e32 v12, 0xffffff80, v12
	s_movk_i32 s8, 0x62
	v_or3_b32 v12, v101, v12, s8
	v_and_b32_e32 v13, 0xffffff80, v13
	s_movk_i32 s8, 0x63
	v_or3_b32 v13, v101, v13, s8
	v_and_b32_e32 v2, 0xffffff80, v2
	s_movk_i32 s8, 0x70
	v_and_b32_e32 v26, 0xffffff80, v26
	v_and_b32_e32 v31, 0xffffff80, v31
	v_or3_b32 v2, v101, v2, s8
	v_and_b32_e32 v3, 0xffffff80, v3
	s_movk_i32 s8, 0x71
	v_or3_b32 v26, v101, v26, 64
	v_or3_b32 v31, v101, v31, 1
	v_and_b32_e32 v32, 0xffffff80, v32
	v_and_b32_e32 v33, 0xffffff80, v33
	v_and_b32_e32 v22, 0xffffff80, v22
	v_and_b32_e32 v23, 0xffffff80, v23
	v_or3_b32 v3, v101, v3, s8
	v_and_b32_e32 v4, 0xffffff80, v4
	s_movk_i32 s8, 0x72
	v_min_f32_e32 v39, v55, v39
	v_min_f32_e32 v55, v71, v87
	v_min_f32_e32 v106, v103, v91
	v_min_f32_e32 v109, v100, v105
	v_max_f32_e32 v71, v71, v87
	v_max_f32_e32 v87, v103, v91
	v_or3_b32 v32, v101, v32, 2
	v_or3_b32 v33, v101, v33, 3
	v_or3_b32 v22, v101, v22, 16
	v_or3_b32 v23, v101, v23, 17
	v_and_b32_e32 v24, 0xffffff80, v24
	v_and_b32_e32 v25, 0xffffff80, v25
	v_and_b32_e32 v14, 0xffffff80, v14
	v_and_b32_e32 v15, 0xffffff80, v15
	v_and_b32_e32 v16, 0xffffff80, v16
	v_and_b32_e32 v17, 0xffffff80, v17
	v_and_b32_e32 v6, 0xffffff80, v6
	v_and_b32_e32 v7, 0xffffff80, v7
	v_and_b32_e32 v8, 0xffffff80, v8
	v_or3_b32 v4, v101, v4, s8
	v_and_b32_e32 v9, 0xffffff80, v9
	v_and_b32_e32 v5, 0xffffff80, v5
	s_movk_i32 s8, 0x73
	v_min_f32_e32 v104, v63, v47
	v_min_f32_e32 v83, v55, v106
	v_min_f32_e32 v47, v109, v110
	v_min_f32_e32 v91, v71, v87
	v_max_f32_e32 v100, v71, v87
	v_max_f32_e32 v87, v55, v106
	v_max_f32_e32 v55, v109, v110
	v_or3_b32 v24, v101, v24, 18
	v_or3_b32 v25, v101, v25, 19
	v_or3_b32 v14, v101, v14, 32
	v_or3_b32 v15, v101, v15, 33
	v_or3_b32 v16, v101, v16, 34
	v_or3_b32 v17, v101, v17, 35
	v_or3_b32 v6, v101, v6, 48
	v_or3_b32 v7, v101, v7, 49
	v_or3_b32 v8, v101, v8, 50
	v_or3_b32 v9, v101, v9, 51
	v_or3_b32 v5, v101, v5, s8
	v_max_f32_e32 v101, v30, v31
	v_min_f32_e32 v30, v30, v31
	v_max_f32_e32 v31, v32, v32
	v_max_f32_e32 v32, v33, v33
	v_max_f32_e32 v109, v26, v27
	v_min_f32_e32 v26, v26, v27
	v_max_f32_e32 v27, v28, v28
	v_max_f32_e32 v28, v29, v29
	v_max_f32_e32 v33, v32, v31
	v_min_f32_e32 v31, v32, v31
	v_max_f32_e32 v32, v22, v23
	v_min_f32_e32 v22, v22, v23
	v_max_f32_e32 v23, v24, v24
	v_max_f32_e32 v24, v25, v25
	v_max_f32_e32 v29, v28, v27
	v_min_f32_e32 v27, v28, v27
	v_max_f32_e32 v28, v18, v19
	v_min_f32_e32 v18, v18, v19
	v_max_f32_e32 v19, v20, v20
	v_max_f32_e32 v20, v21, v21
	v_max_f32_e32 v25, v24, v23
	v_min_f32_e32 v23, v24, v23
	v_max_f32_e32 v24, v14, v15
	v_min_f32_e32 v14, v14, v15
	v_max_f32_e32 v15, v16, v16
	v_max_f32_e32 v16, v17, v17
	v_max_f32_e32 v21, v20, v19
	v_min_f32_e32 v19, v20, v19
	v_max_f32_e32 v20, v10, v11
	v_min_f32_e32 v10, v10, v11
	v_max_f32_e32 v11, v12, v12
	v_max_f32_e32 v12, v13, v13
	v_max_f32_e32 v17, v16, v15
	v_min_f32_e32 v15, v16, v15
	v_max_f32_e32 v16, v6, v7
	v_min_f32_e32 v6, v6, v7
; DEV void ce(float& a, float& b) { float hi = fmaxf(a, b), lo = fminf(a, b); a = hi; b = lo; }
; DEV void sort16_desc(float (&a)[16]) {
; #pragma unroll
;   for (int k = 2; k <= 16; k <<= 1)
; #pragma unroll
;     for (int j = k >> 1; j > 0; j >>= 1)
; #pragma unroll
;       for (int i = 0; i < 16; i++) {
;         const int p = i ^ j;
;         if (p > i) { if ((i & k) == 0) ce(a[i], a[p]); else ce(a[p], a[i]); }
;       }
; }
	v_max_f32_e32 v7, v8, v8
	v_max_f32_e32 v8, v9, v9
	v_max_f32_e32 v13, v12, v11
	v_min_f32_e32 v11, v12, v11
	v_max_f32_e32 v12, v2, v3
	v_min_f32_e32 v2, v2, v3
	v_max_f32_e32 v3, v4, v4
	v_max_f32_e32 v4, v5, v5
	v_max_f32_e32 v9, v8, v7
	v_min_f32_e32 v7, v8, v7
	v_max_f32_e32 v5, v4, v3
	v_min_f32_e32 v3, v4, v3
	v_max_f32_e32 v8, v101, v31
	v_min_f32_e32 v31, v101, v31
	v_max_f32_e32 v101, v30, v33
	v_min_f32_e32 v30, v30, v33
	v_max_f32_e32 v33, v23, v32
	v_min_f32_e32 v23, v23, v32
	v_max_f32_e32 v32, v25, v22
	v_min_f32_e32 v22, v25, v22
	v_max_f32_e32 v25, v24, v15
	v_min_f32_e32 v15, v24, v15
	v_max_f32_e32 v24, v14, v17
	v_min_f32_e32 v14, v14, v17
	v_max_f32_e32 v17, v7, v16
	v_min_f32_e32 v7, v7, v16
	v_max_f32_e32 v16, v9, v6
	v_min_f32_e32 v6, v9, v6
	v_max_f32_e32 v4, v109, v27
	v_min_f32_e32 v27, v109, v27
	v_max_f32_e32 v109, v26, v29
	v_min_f32_e32 v26, v26, v29
	v_max_f32_e32 v29, v19, v28
	v_min_f32_e32 v19, v19, v28
	v_max_f32_e32 v28, v21, v18
	v_min_f32_e32 v18, v21, v18
	v_max_f32_e32 v21, v20, v11
	v_min_f32_e32 v11, v20, v11
	v_max_f32_e32 v20, v10, v13
	v_min_f32_e32 v10, v10, v13
	v_max_f32_e32 v13, v3, v12
	v_min_f32_e32 v3, v3, v12
	v_max_f32_e32 v12, v5, v2
	v_min_f32_e32 v2, v5, v2
	v_max_f32_e32 v9, v8, v101
	v_min_f32_e32 v8, v8, v101
	v_max_f32_e32 v101, v31, v30
	v_min_f32_e32 v30, v31, v30
	v_max_f32_e32 v31, v22, v23
	v_min_f32_e32 v22, v22, v23
	v_max_f32_e32 v23, v32, v33
	v_min_f32_e32 v32, v32, v33
	v_max_f32_e32 v33, v25, v24
	v_min_f32_e32 v24, v25, v24
	v_max_f32_e32 v25, v15, v14
	v_min_f32_e32 v14, v15, v14
	v_max_f32_e32 v15, v6, v7
	v_min_f32_e32 v6, v6, v7
	v_max_f32_e32 v7, v16, v17
	v_min_f32_e32 v16, v16, v17
	v_max_f32_e32 v5, v4, v109
	v_min_f32_e32 v4, v4, v109
	v_max_f32_e32 v109, v27, v26
	v_min_f32_e32 v26, v27, v26
	v_max_f32_e32 v27, v18, v19
	v_min_f32_e32 v18, v18, v19
	v_max_f32_e32 v19, v28, v29
	v_min_f32_e32 v28, v28, v29
	v_max_f32_e32 v29, v21, v20
	v_min_f32_e32 v20, v21, v20
	v_max_f32_e32 v21, v11, v10
	v_min_f32_e32 v10, v11, v10
	v_max_f32_e32 v11, v2, v3
	v_min_f32_e32 v2, v2, v3
	v_max_f32_e32 v3, v12, v13
	v_min_f32_e32 v12, v12, v13
	v_max_f32_e32 v17, v9, v22
	v_min_f32_e32 v9, v9, v22
	v_max_f32_e32 v22, v8, v31
	v_min_f32_e32 v8, v8, v31
	v_max_f32_e32 v31, v101, v32
	v_min_f32_e32 v32, v101, v32
	v_max_f32_e32 v101, v30, v23
	v_min_f32_e32 v23, v30, v23
	v_max_f32_e32 v30, v6, v33
	v_min_f32_e32 v6, v6, v33
	v_max_f32_e32 v33, v15, v24
	v_min_f32_e32 v15, v15, v24
	v_max_f32_e32 v24, v16, v25
	v_min_f32_e32 v16, v16, v25
	v_max_f32_e32 v25, v7, v14
	v_min_f32_e32 v7, v7, v14
	v_max_f32_e32 v13, v5, v18
	v_min_f32_e32 v5, v5, v18
	v_max_f32_e32 v18, v4, v27
	v_min_f32_e32 v4, v4, v27
	v_max_f32_e32 v27, v109, v28
	v_min_f32_e32 v28, v109, v28
	v_max_f32_e32 v109, v26, v19
	v_min_f32_e32 v19, v26, v19
	v_max_f32_e32 v26, v2, v29
	v_min_f32_e32 v2, v2, v29
	v_max_f32_e32 v29, v11, v20
	v_min_f32_e32 v11, v11, v20
	v_max_f32_e32 v20, v12, v21
	v_min_f32_e32 v12, v12, v21
	v_max_f32_e32 v21, v3, v10
	v_min_f32_e32 v3, v3, v10
	v_max_f32_e32 v14, v17, v31
	v_min_f32_e32 v17, v17, v31
	v_max_f32_e32 v31, v22, v101
	v_min_f32_e32 v22, v22, v101
	v_max_f32_e32 v101, v9, v32
	v_min_f32_e32 v9, v9, v32
	v_max_f32_e32 v32, v8, v23
	v_min_f32_e32 v8, v8, v23
	v_max_f32_e32 v23, v16, v6
	v_min_f32_e32 v6, v16, v6
	v_max_f32_e32 v16, v7, v15
	v_min_f32_e32 v7, v7, v15
	v_max_f32_e32 v15, v24, v30
	v_min_f32_e32 v24, v24, v30
	v_max_f32_e32 v30, v25, v33
	v_min_f32_e32 v25, v25, v33
	v_max_f32_e32 v10, v13, v27
	v_min_f32_e32 v13, v13, v27
	v_max_f32_e32 v27, v18, v109
	v_min_f32_e32 v18, v18, v109
	v_max_f32_e32 v109, v5, v28
	v_min_f32_e32 v5, v5, v28
	v_max_f32_e32 v28, v4, v19
	v_min_f32_e32 v4, v4, v19
	v_max_f32_e32 v19, v12, v2
	v_min_f32_e32 v2, v12, v2
	v_max_f32_e32 v12, v3, v11
	v_min_f32_e32 v3, v3, v11
	v_max_f32_e32 v11, v20, v26
	v_min_f32_e32 v20, v20, v26
	v_max_f32_e32 v26, v21, v29
	v_min_f32_e32 v21, v21, v29
	v_max_f32_e32 v33, v14, v31
	v_min_f32_e32 v14, v14, v31
	v_max_f32_e32 v31, v17, v22
	v_min_f32_e32 v17, v17, v22
	v_max_f32_e32 v22, v101, v32
	v_min_f32_e32 v32, v101, v32
	v_max_f32_e32 v101, v9, v8
	v_min_f32_e32 v8, v9, v8
	v_max_f32_e32 v9, v7, v6
	v_min_f32_e32 v6, v7, v6
	v_max_f32_e32 v7, v16, v23
	v_min_f32_e32 v16, v16, v23
	v_max_f32_e32 v23, v25, v24
	v_min_f32_e32 v24, v25, v24
	v_max_f32_e32 v25, v30, v15
	v_min_f32_e32 v15, v30, v15
	v_max_f32_e32 v29, v10, v27
	v_min_f32_e32 v10, v10, v27
	v_max_f32_e32 v27, v13, v18
	v_min_f32_e32 v13, v13, v18
	v_max_f32_e32 v18, v109, v28
	v_min_f32_e32 v28, v109, v28
	v_max_f32_e32 v109, v5, v4
	v_min_f32_e32 v4, v5, v4
	v_max_f32_e32 v5, v3, v2
	v_min_f32_e32 v2, v3, v2
	v_max_f32_e32 v3, v12, v19
	v_min_f32_e32 v12, v12, v19
	v_max_f32_e32 v19, v21, v20
	v_min_f32_e32 v20, v21, v20
	v_max_f32_e32 v21, v26, v11
	v_min_f32_e32 v11, v26, v11
	v_max_f32_e32 v30, v33, v6
	v_min_f32_e32 v6, v33, v6
	v_max_f32_e32 v33, v14, v9
	v_min_f32_e32 v9, v14, v9
	v_max_f32_e32 v14, v31, v16
	v_min_f32_e32 v16, v31, v16
	v_max_f32_e32 v31, v17, v7
	v_min_f32_e32 v7, v17, v7
	v_max_f32_e32 v17, v22, v24
	v_min_f32_e32 v22, v22, v24
	v_max_f32_e32 v24, v32, v23
	v_min_f32_e32 v23, v32, v23
	v_max_f32_e32 v32, v101, v15
	v_min_f32_e32 v15, v101, v15
	v_max_f32_e32 v101, v8, v25
	v_min_f32_e32 v8, v8, v25
	v_max_f32_e32 v26, v29, v2
	v_min_f32_e32 v2, v29, v2
	v_max_f32_e32 v29, v10, v5
	v_min_f32_e32 v5, v10, v5
	v_max_f32_e32 v10, v27, v12
	v_min_f32_e32 v12, v27, v12
	v_max_f32_e32 v27, v13, v3
	v_min_f32_e32 v3, v13, v3
	v_max_f32_e32 v13, v18, v20
	v_min_f32_e32 v18, v18, v20
	v_max_f32_e32 v20, v28, v19
; DEV void merge_xor(float (&l)[16], int mask) {
;   float t[16];
; #pragma unroll
;   for (int i = 0; i < 16; i++) t[i] = __shfl_xor(l[15 - i], mask);
; #pragma unroll
;   for (int i = 0; i < 16; i++) l[i] = fmaxf(l[i], t[i]);
;   bitonic16(l);
; DEV void peer_top16(const bf16_t* __restrict__ pq, const bf16_t* sk  , float (&l)[16]) {
;     ...
;   sort16_desc(l);
;   sort16_desc(hi);
; #pragma unroll
;   for (int i = 0; i < 16; i++) l[i] = fmaxf(l[i], hi[15 - i]);
;   bitonic16(l);
;   merge_xor(l, 16);
;   merge_xor(l, 32);
	v_min_f32_e32 v19, v28, v19
	v_max_f32_e32 v28, v109, v11
	v_min_f32_e32 v11, v109, v11
	v_max_f32_e32 v109, v4, v21
	v_min_f32_e32 v4, v4, v21
	v_max_f32_e32 v25, v30, v17
	v_min_f32_e32 v17, v30, v17
	v_max_f32_e32 v30, v33, v24
	v_min_f32_e32 v24, v33, v24
	v_max_f32_e32 v33, v14, v32
	v_min_f32_e32 v14, v14, v32
	v_max_f32_e32 v32, v31, v101
	v_min_f32_e32 v31, v31, v101
	v_max_f32_e32 v101, v6, v22
	v_min_f32_e32 v6, v6, v22
	v_max_f32_e32 v22, v9, v23
	v_min_f32_e32 v9, v9, v23
	v_max_f32_e32 v23, v16, v15
	v_min_f32_e32 v15, v16, v15
	v_max_f32_e32 v16, v7, v8
	v_min_f32_e32 v7, v7, v8
	v_max_f32_e32 v21, v26, v13
	v_min_f32_e32 v13, v26, v13
	v_max_f32_e32 v26, v29, v20
	v_min_f32_e32 v20, v29, v20
	v_max_f32_e32 v29, v10, v28
	v_min_f32_e32 v10, v10, v28
	v_max_f32_e32 v28, v27, v109
	v_min_f32_e32 v27, v27, v109
	v_max_f32_e32 v109, v2, v18
	v_min_f32_e32 v2, v2, v18
	v_max_f32_e32 v18, v5, v19
	v_min_f32_e32 v5, v5, v19
	v_max_f32_e32 v19, v12, v11
	v_min_f32_e32 v11, v12, v11
	v_max_f32_e32 v12, v3, v4
	v_min_f32_e32 v3, v3, v4
	v_max_f32_e32 v111, v0, v43
	v_min_f32_e32 v112, v104, v39
	v_max_f32_e32 v103, v104, v39
	v_min_f32_e32 v0, v0, v43
	v_max_f32_e32 v8, v25, v33
	v_min_f32_e32 v25, v25, v33
	v_max_f32_e32 v33, v30, v32
	v_min_f32_e32 v30, v30, v32
	v_max_f32_e32 v32, v17, v14
	v_min_f32_e32 v14, v17, v14
	v_max_f32_e32 v17, v24, v31
	v_min_f32_e32 v24, v24, v31
	v_max_f32_e32 v31, v101, v23
	v_min_f32_e32 v23, v101, v23
	v_max_f32_e32 v101, v22, v16
	v_min_f32_e32 v16, v22, v16
	v_max_f32_e32 v22, v6, v15
	v_min_f32_e32 v6, v6, v15
	v_max_f32_e32 v15, v9, v7
	v_min_f32_e32 v7, v9, v7
	v_max_f32_e32 v4, v21, v29
	v_min_f32_e32 v21, v21, v29
	v_max_f32_e32 v29, v26, v28
	v_min_f32_e32 v26, v26, v28
	v_max_f32_e32 v28, v13, v10
	v_min_f32_e32 v10, v13, v10
	v_max_f32_e32 v13, v20, v27
	v_min_f32_e32 v20, v20, v27
	v_max_f32_e32 v27, v109, v19
	v_min_f32_e32 v19, v109, v19
	v_max_f32_e32 v109, v18, v12
	v_min_f32_e32 v12, v18, v12
	v_max_f32_e32 v18, v2, v11
	v_min_f32_e32 v2, v2, v11
	v_max_f32_e32 v11, v5, v3
	v_min_f32_e32 v3, v5, v3
	v_min_f32_e32 v63, v107, v108
	v_min_f32_e32 v39, v111, v103
	v_max_f32_e32 v71, v107, v108
	v_max_f32_e32 v51, v111, v103
	v_max_f32_e32 v43, v0, v112
	v_min_f32_e32 v0, v0, v112
	v_min_f32_e32 v9, v8, v33
	v_min_f32_e32 v102, v25, v30
	v_min_f32_e32 v103, v32, v17
	v_min_f32_e32 v104, v14, v24
	v_min_f32_e32 v105, v31, v101
	v_min_f32_e32 v106, v23, v16
	v_min_f32_e32 v107, v22, v15
	v_min_f32_e32 v108, v6, v7
	v_min_f32_e32 v5, v4, v29
	v_min_f32_e32 v110, v21, v26
	v_min_f32_e32 v111, v28, v13
	v_min_f32_e32 v112, v10, v20
	v_min_f32_e32 v113, v27, v109
	v_min_f32_e32 v114, v19, v12
	v_min_f32_e32 v115, v18, v11
	v_min_f32_e32 v116, v2, v3
	v_max3_f32 v8, v8, v33, v116
	v_max3_f32 v2, v9, v2, v3
	v_max3_f32 v3, v25, v30, v115
	v_max3_f32 v9, v102, v18, v11
	v_max3_f32 v11, v32, v17, v114
	v_max3_f32 v12, v103, v19, v12
	v_max3_f32 v14, v14, v24, v113
	v_max3_f32 v17, v104, v27, v109
	v_max3_f32 v18, v31, v101, v112
	v_max3_f32 v10, v105, v10, v20
	v_max3_f32 v16, v23, v16, v111
	v_max3_f32 v13, v106, v28, v13
	v_max3_f32 v15, v22, v15, v110
	v_max3_f32 v19, v107, v21, v26
	v_max3_f32 v5, v6, v7, v5
	v_max3_f32 v4, v108, v4, v29
	v_max_f32_e32 v6, v8, v18
	v_min_f32_e32 v7, v8, v18
	v_max_f32_e32 v8, v2, v10
	v_min_f32_e32 v2, v2, v10
	v_max_f32_e32 v10, v3, v16
	v_min_f32_e32 v3, v3, v16
	v_max_f32_e32 v16, v9, v13
	v_min_f32_e32 v9, v9, v13
	v_max_f32_e32 v13, v11, v15
	v_min_f32_e32 v11, v11, v15
	v_max_f32_e32 v15, v12, v19
	v_min_f32_e32 v12, v12, v19
	v_max_f32_e32 v18, v14, v5
	v_min_f32_e32 v5, v14, v5
	v_max_f32_e32 v14, v17, v4
	v_min_f32_e32 v4, v17, v4
	v_max_f32_e32 v17, v6, v13
	v_min_f32_e32 v6, v6, v13
	v_max_f32_e32 v13, v8, v15
	v_min_f32_e32 v8, v8, v15
	v_max_f32_e32 v15, v10, v18
	v_min_f32_e32 v10, v10, v18
	v_max_f32_e32 v18, v16, v14
	v_min_f32_e32 v14, v16, v14
	v_max_f32_e32 v16, v7, v11
	v_min_f32_e32 v7, v7, v11
	v_max_f32_e32 v11, v2, v12
	v_min_f32_e32 v2, v2, v12
	v_max_f32_e32 v12, v3, v5
	v_min_f32_e32 v3, v3, v5
	v_max_f32_e32 v5, v9, v4
	v_min_f32_e32 v4, v9, v4
	v_max_f32_e32 v9, v17, v15
	v_min_f32_e32 v15, v17, v15
	v_max_f32_e32 v17, v13, v18
	v_min_f32_e32 v13, v13, v18
	v_max_f32_e32 v18, v6, v10
	v_min_f32_e32 v6, v6, v10
	v_max_f32_e32 v10, v8, v14
	v_min_f32_e32 v8, v8, v14
	v_max_f32_e32 v14, v16, v12
	v_min_f32_e32 v12, v16, v12
	v_max_f32_e32 v16, v11, v5
	v_min_f32_e32 v5, v11, v5
	v_max_f32_e32 v11, v7, v3
	v_min_f32_e32 v3, v7, v3
	v_max_f32_e32 v7, v2, v4
	v_min_f32_e32 v2, v2, v4
	v_max_f32_e32 v4, v9, v17
	v_min_f32_e32 v9, v9, v17
	v_max_f32_e32 v17, v15, v13
	v_min_f32_e32 v13, v15, v13
	v_max_f32_e32 v15, v18, v10
	v_min_f32_e32 v10, v18, v10
	v_max_f32_e32 v18, v6, v8
	v_min_f32_e32 v6, v6, v8
	v_max_f32_e32 v8, v14, v16
	v_min_f32_e32 v14, v14, v16
	v_max_f32_e32 v16, v12, v5
	v_min_f32_e32 v5, v12, v5
	v_max_f32_e32 v12, v11, v7
	v_min_f32_e32 v7, v11, v7
	v_max_f32_e32 v11, v3, v2
	v_min_f32_e32 v2, v3, v2
	ds_bpermute_b32 v3, v95, v2
	ds_bpermute_b32 v19, v95, v11
	ds_bpermute_b32 v20, v95, v7
	ds_bpermute_b32 v21, v95, v12
	ds_bpermute_b32 v22, v95, v5
	ds_bpermute_b32 v23, v95, v16
	s_waitcnt lgkmcnt(5)
	ds_bpermute_b32 v24, v95, v14
	ds_bpermute_b32 v33, v95, v4
	v_max_f32_e32 v3, v4, v3
	s_waitcnt lgkmcnt(6)
	ds_bpermute_b32 v25, v95, v8
	ds_bpermute_b32 v32, v95, v9
	v_max_f32_e32 v4, v9, v19
	s_waitcnt lgkmcnt(7)
	ds_bpermute_b32 v26, v95, v6
	ds_bpermute_b32 v31, v95, v17
	v_max_f32_e32 v9, v17, v20
	s_waitcnt lgkmcnt(8)
	ds_bpermute_b32 v27, v95, v18
	ds_bpermute_b32 v30, v95, v13
	v_max_f32_e32 v13, v13, v21
	s_waitcnt lgkmcnt(9)
; DEV void merge_xor(float (&l)[16], int mask) {
;   float t[16];
; #pragma unroll
;   for (int i = 0; i < 16; i++) t[i] = __shfl_xor(l[15 - i], mask);
; #pragma unroll
;   for (int i = 0; i < 16; i++) l[i] = fmaxf(l[i], t[i]);
;   bitonic16(l);
; }
; DEV void phase_peer_score(const Params& p, int layer, int M, char* smem) {
;     ...
;     unsigned char* tab = (unsigned char*)smem + 73728 + (w * 16 + l15) * 32;
; #pragma unroll
;     for (int i = 0; i < 16; i++) { tab[i] = (unsigned char)(__float_as_uint(L0[i]) & 127u); tab[16 + i] = (unsigned char)(__float_as_uint(L1[i]) & 127u); }
	ds_bpermute_b32 v28, v95, v10
	ds_bpermute_b32 v29, v95, v15
	v_max_f32_e32 v15, v15, v22
	s_waitcnt lgkmcnt(10)
	v_max_f32_e32 v10, v10, v23
	s_waitcnt lgkmcnt(9)
	v_max_f32_e32 v17, v18, v24
	s_waitcnt lgkmcnt(7)
	v_max_f32_e32 v6, v6, v25
	s_waitcnt lgkmcnt(5)
	v_max_f32_e32 v8, v8, v26
	s_waitcnt lgkmcnt(3)
	v_max_f32_e32 v14, v14, v27
	s_waitcnt lgkmcnt(1)
	v_max_f32_e32 v16, v16, v28
	s_waitcnt lgkmcnt(0)
	v_max_f32_e32 v5, v5, v29
	v_max_f32_e32 v12, v12, v30
	v_max_f32_e32 v7, v7, v31
	v_max_f32_e32 v11, v11, v32
	v_max_f32_e32 v2, v2, v33
	v_max_f32_e32 v18, v3, v8
	v_min_f32_e32 v3, v3, v8
	v_max_f32_e32 v8, v4, v14
	v_min_f32_e32 v4, v4, v14
	v_max_f32_e32 v14, v9, v16
	v_min_f32_e32 v9, v9, v16
	v_max_f32_e32 v16, v13, v5
	v_min_f32_e32 v5, v13, v5
	v_max_f32_e32 v13, v15, v12
	v_min_f32_e32 v12, v15, v12
	v_max_f32_e32 v15, v10, v7
	v_min_f32_e32 v7, v10, v7
	v_max_f32_e32 v10, v17, v11
	v_min_f32_e32 v11, v17, v11
	v_max_f32_e32 v17, v6, v2
	v_min_f32_e32 v2, v6, v2
	v_max_f32_e32 v6, v18, v13
	v_min_f32_e32 v13, v18, v13
	v_max_f32_e32 v18, v8, v15
	v_min_f32_e32 v8, v8, v15
	v_max_f32_e32 v15, v14, v10
	v_min_f32_e32 v10, v14, v10
	v_max_f32_e32 v14, v16, v17
	v_min_f32_e32 v16, v16, v17
	v_max_f32_e32 v17, v3, v12
	v_min_f32_e32 v3, v3, v12
	v_max_f32_e32 v12, v4, v7
	v_min_f32_e32 v4, v4, v7
	v_max_f32_e32 v7, v9, v11
	v_min_f32_e32 v9, v9, v11
	v_max_f32_e32 v11, v5, v2
	v_min_f32_e32 v2, v5, v2
	v_max_f32_e32 v5, v6, v15
	v_min_f32_e32 v6, v6, v15
	v_max_f32_e32 v15, v18, v14
	v_min_f32_e32 v14, v18, v14
	v_max_f32_e32 v18, v13, v10
	v_min_f32_e32 v10, v13, v10
	v_max_f32_e32 v13, v8, v16
	v_min_f32_e32 v8, v8, v16
	v_max_f32_e32 v16, v17, v7
	v_min_f32_e32 v7, v17, v7
	v_max_f32_e32 v17, v12, v11
	v_min_f32_e32 v11, v12, v11
	v_max_f32_e32 v12, v3, v9
	v_min_f32_e32 v3, v3, v9
	v_max_f32_e32 v9, v4, v2
	v_min_f32_e32 v2, v4, v2
	v_max_f32_e32 v4, v5, v15
	v_min_f32_e32 v5, v5, v15
	v_max_f32_e32 v15, v6, v14
	v_min_f32_e32 v6, v6, v14
	v_max_f32_e32 v14, v18, v13
	v_min_f32_e32 v13, v18, v13
	v_max_f32_e32 v18, v10, v8
	v_min_f32_e32 v8, v10, v8
	v_max_f32_e32 v10, v16, v17
	v_min_f32_e32 v16, v16, v17
	v_max_f32_e32 v17, v7, v11
	v_min_f32_e32 v7, v7, v11
	v_max_f32_e32 v11, v12, v9
	v_min_f32_e32 v9, v12, v9
	v_max_f32_e32 v12, v3, v2
	v_min_f32_e32 v2, v3, v2
	ds_bpermute_b32 v3, v99, v2
	ds_bpermute_b32 v19, v99, v12
	ds_bpermute_b32 v20, v99, v9
	ds_bpermute_b32 v21, v99, v11
	ds_bpermute_b32 v22, v99, v7
	ds_bpermute_b32 v23, v99, v17
	s_waitcnt lgkmcnt(5)
	ds_bpermute_b32 v24, v99, v16
	ds_bpermute_b32 v33, v99, v4
	v_max_f32_e32 v3, v4, v3
	s_waitcnt lgkmcnt(6)
	ds_bpermute_b32 v25, v99, v10
	ds_bpermute_b32 v32, v99, v5
	v_max_f32_e32 v4, v5, v19
	s_waitcnt lgkmcnt(7)
	ds_bpermute_b32 v26, v99, v8
	ds_bpermute_b32 v31, v99, v15
	v_max_f32_e32 v5, v15, v20
	s_waitcnt lgkmcnt(8)
	ds_bpermute_b32 v27, v99, v18
	ds_bpermute_b32 v30, v99, v6
	v_max_f32_e32 v6, v6, v21
	s_waitcnt lgkmcnt(9)
	ds_bpermute_b32 v28, v99, v13
	ds_bpermute_b32 v29, v99, v14
	v_max_f32_e32 v14, v14, v22
	s_waitcnt lgkmcnt(10)
	v_max_f32_e32 v13, v13, v23
	s_waitcnt lgkmcnt(9)
	v_max_f32_e32 v15, v18, v24
	s_waitcnt lgkmcnt(7)
	v_max_f32_e32 v8, v8, v25
	s_waitcnt lgkmcnt(5)
	v_max_f32_e32 v10, v10, v26
	s_waitcnt lgkmcnt(3)
	v_max_f32_e32 v16, v16, v27
	s_waitcnt lgkmcnt(1)
	v_max_f32_e32 v17, v17, v28
	s_waitcnt lgkmcnt(0)
	v_max_f32_e32 v7, v7, v29
	v_max_f32_e32 v11, v11, v30
	v_max_f32_e32 v9, v9, v31
	v_max_f32_e32 v12, v12, v32
	v_max_f32_e32 v2, v2, v33
	v_max_f32_e32 v18, v3, v10
	v_min_f32_e32 v3, v3, v10
	v_max_f32_e32 v10, v4, v16
	v_min_f32_e32 v4, v4, v16
	v_max_f32_e32 v16, v5, v17
	v_min_f32_e32 v5, v5, v17
	v_max_f32_e32 v17, v6, v7
	v_min_f32_e32 v6, v6, v7
	v_max_f32_e32 v7, v14, v11
	v_min_f32_e32 v11, v14, v11
	v_max_f32_e32 v14, v13, v9
	v_min_f32_e32 v9, v13, v9
	v_max_f32_e32 v13, v15, v12
	v_min_f32_e32 v12, v15, v12
	v_max_f32_e32 v15, v8, v2
	v_min_f32_e32 v2, v8, v2
	v_max_f32_e32 v8, v18, v7
	v_min_f32_e32 v7, v18, v7
	v_max_f32_e32 v18, v10, v14
	v_min_f32_e32 v10, v10, v14
	v_max_f32_e32 v14, v16, v13
	v_min_f32_e32 v13, v16, v13
	v_max_f32_e32 v16, v17, v15
	v_min_f32_e32 v15, v17, v15
	v_max_f32_e32 v17, v3, v11
	v_min_f32_e32 v3, v3, v11
	v_max_f32_e32 v11, v4, v9
	v_min_f32_e32 v4, v4, v9
	v_max_f32_e32 v9, v5, v12
	v_min_f32_e32 v5, v5, v12
	v_max_f32_e32 v12, v6, v2
	v_min_f32_e32 v2, v6, v2
	v_max_f32_e32 v6, v8, v14
	v_min_f32_e32 v8, v8, v14
	v_max_f32_e32 v14, v18, v16
	v_min_f32_e32 v16, v18, v16
	v_max_f32_e32 v18, v7, v13
	v_max_f32_e32 v19, v10, v15
	s_movk_i32 s8, 0x7f
	v_min_f32_e32 v13, v7, v13
	v_min_f32_e32 v10, v10, v15
	v_max_f32_e32 v15, v17, v9
	v_min_f32_e32 v21, v17, v9
	v_max_f32_e32 v17, v11, v12
	v_min_f32_e32 v22, v11, v12
	v_max_f32_e32 v23, v3, v5
	v_min_f32_e32 v3, v3, v5
	v_max_f32_e32 v5, v4, v2
	v_min_f32_e32 v24, v4, v2
	v_max_f32_e32 v9, v18, v19
	v_min_f32_e32 v12, v18, v19
	v_and_b32_sdwa v18, v63, s8 dst_sel:BYTE_1 dst_unused:UNUSED_PAD src0_sel:DWORD src1_sel:DWORD
	v_max_f32_e32 v2, v6, v14
	v_min_f32_e32 v4, v6, v14
	v_max_f32_e32 v11, v13, v10
	v_min_f32_e32 v10, v13, v10
	v_max_f32_e32 v14, v23, v5
	v_min_f32_e32 v13, v23, v5
	v_max_f32_e32 v6, v3, v24
	v_min_f32_e32 v5, v3, v24
	v_and_b32_sdwa v3, v75, s8 dst_sel:BYTE_1 dst_unused:UNUSED_PAD src0_sel:DWORD src1_sel:DWORD
	v_bitop3_b16 v18, v71, v18, s8 bitop3:0xec
	v_bitop3_b16 v3, v79, v3, s8 bitop3:0xec
	v_lshlrev_b32_e32 v18, 16, v18
	v_or_b32_sdwa v23, v3, v18 dst_sel:DWORD dst_unused:UNUSED_PAD src0_sel:WORD_0 src1_sel:DWORD
	v_and_b32_sdwa v18, v83, s8 dst_sel:BYTE_1 dst_unused:UNUSED_PAD src0_sel:DWORD src1_sel:DWORD
; DEV void ce(float& a, float& b) { float hi = fmaxf(a, b), lo = fminf(a, b); a = hi; b = lo; }
; DEV void phase_peer_score(const Params& p, int layer, int M, char* smem) {
;     ...
; #pragma unroll
;     for (int i = 0; i < 16; i++) R[i] = -3.0e38f;
; #pragma unroll
;     for (int i = 0; i < 16; i++)
; #pragma unroll
;       for (int j = 0; j < 16; j++)
;         if ((i + 1) * (j + 1) <= 16) {
;           float v = L0[i] + L1[j];
;           v = __uint_as_float((__float_as_uint(v) & ~255u) | (unsigned)(i * 16 + j));
; #pragma unroll
;           for (int t = 0; t < 16; t++)
;             if (t >= (i + 1) * (j + 1) - 1) ce(R[t], v);
;         }
;     unsigned char* tab = (unsigned char*)smem + 73728 + (w * 16 + l15) * 32;
; #pragma unroll
;     for (int i = 0; i < 16; i++) { tab[i] = (unsigned char)(__float_as_uint(L0[i]) & 127u); tab[16 + i] = (unsigned char)(__float_as_uint(L1[i]) & 127u); }
	v_and_b32_sdwa v3, v91, s8 dst_sel:BYTE_1 dst_unused:UNUSED_PAD src0_sel:DWORD src1_sel:DWORD
	v_bitop3_b16 v18, v87, v18, s8 bitop3:0xec
	v_bitop3_b16 v3, v100, v3, s8 bitop3:0xec
	v_lshlrev_b32_e32 v18, 16, v18
	v_max_f32_e32 v7, v8, v16
	v_min_f32_e32 v8, v8, v16
	v_max_f32_e32 v20, v15, v17
	v_min_f32_e32 v17, v15, v17
	v_max_f32_e32 v16, v21, v22
	v_min_f32_e32 v15, v21, v22
	v_or_b32_sdwa v22, v3, v18 dst_sel:DWORD dst_unused:UNUSED_PAD src0_sel:WORD_0 src1_sel:DWORD
	v_and_b32_sdwa v18, v10, s8 dst_sel:BYTE_1 dst_unused:UNUSED_PAD src0_sel:DWORD src1_sel:DWORD
	v_and_b32_sdwa v3, v12, s8 dst_sel:BYTE_1 dst_unused:UNUSED_PAD src0_sel:DWORD src1_sel:DWORD
	v_bitop3_b16 v18, v11, v18, s8 bitop3:0xec
	v_bitop3_b16 v3, v9, v3, s8 bitop3:0xec
	v_lshlrev_b32_e32 v18, 16, v18
	v_or_b32_sdwa v27, v3, v18 dst_sel:DWORD dst_unused:UNUSED_PAD src0_sel:WORD_0 src1_sel:DWORD
	v_and_b32_sdwa v18, v8, s8 dst_sel:BYTE_1 dst_unused:UNUSED_PAD src0_sel:DWORD src1_sel:DWORD
	v_and_b32_sdwa v3, v4, s8 dst_sel:BYTE_1 dst_unused:UNUSED_PAD src0_sel:DWORD src1_sel:DWORD
	v_bitop3_b16 v18, v7, v18, s8 bitop3:0xec
	v_bitop3_b16 v3, v2, v3, s8 bitop3:0xec
	v_lshlrev_b32_e32 v18, 16, v18
	v_or_b32_sdwa v26, v3, v18 dst_sel:DWORD dst_unused:UNUSED_PAD src0_sel:WORD_0 src1_sel:DWORD
	v_and_b32_sdwa v18, v0, s8 dst_sel:BYTE_1 dst_unused:UNUSED_PAD src0_sel:DWORD src1_sel:DWORD
	v_and_b32_sdwa v3, v39, s8 dst_sel:BYTE_1 dst_unused:UNUSED_PAD src0_sel:DWORD src1_sel:DWORD
	v_bitop3_b16 v18, v43, v18, s8 bitop3:0xec
	v_bitop3_b16 v3, v51, v3, s8 bitop3:0xec
	v_lshlrev_b32_e32 v18, 16, v18
	v_or_b32_sdwa v25, v3, v18 dst_sel:DWORD dst_unused:UNUSED_PAD src0_sel:WORD_0 src1_sel:DWORD
	v_and_b32_sdwa v18, v47, s8 dst_sel:BYTE_1 dst_unused:UNUSED_PAD src0_sel:DWORD src1_sel:DWORD
	v_and_b32_sdwa v3, v59, s8 dst_sel:BYTE_1 dst_unused:UNUSED_PAD src0_sel:DWORD src1_sel:DWORD
	v_bitop3_b16 v18, v55, v18, s8 bitop3:0xec
	v_bitop3_b16 v3, v67, v3, s8 bitop3:0xec
	v_lshlrev_b32_e32 v18, 16, v18
	v_or_b32_sdwa v24, v3, v18 dst_sel:DWORD dst_unused:UNUSED_PAD src0_sel:WORD_0 src1_sel:DWORD
	v_and_b32_sdwa v18, v5, s8 dst_sel:BYTE_1 dst_unused:UNUSED_PAD src0_sel:DWORD src1_sel:DWORD
	v_and_b32_sdwa v3, v13, s8 dst_sel:BYTE_1 dst_unused:UNUSED_PAD src0_sel:DWORD src1_sel:DWORD
	v_bitop3_b16 v18, v6, v18, s8 bitop3:0xec
	v_bitop3_b16 v3, v14, v3, s8 bitop3:0xec
	v_lshlrev_b32_e32 v18, 16, v18
	v_or_b32_sdwa v29, v3, v18 dst_sel:DWORD dst_unused:UNUSED_PAD src0_sel:WORD_0 src1_sel:DWORD
	v_and_b32_sdwa v18, v15, s8 dst_sel:BYTE_1 dst_unused:UNUSED_PAD src0_sel:DWORD src1_sel:DWORD
	v_and_b32_sdwa v3, v17, s8 dst_sel:BYTE_1 dst_unused:UNUSED_PAD src0_sel:DWORD src1_sel:DWORD
	v_bitop3_b16 v18, v16, v18, s8 bitop3:0xec
	v_bitop3_b16 v3, v20, v3, s8 bitop3:0xec
	v_lshlrev_b32_e32 v18, 16, v18
	v_or_b32_sdwa v28, v3, v18 dst_sel:DWORD dst_unused:UNUSED_PAD src0_sel:WORD_0 src1_sel:DWORD
	ds_write_b128 v138, v[22:25]
	ds_write_b128 v138, v[26:29] offset:16
	s_and_saveexec_b64 s[8:9], s[38:39]
	s_cbranch_execz .LBB0_627
	s_movk_i32 s18, 0xff00
	v_add_f32_e32 v164, v100, v2
	v_and_or_b32 v164, v164, s18, 0
	v_max_f32_e32 v148, 0xff61b1e6, v164
	v_add_f32_e32 v164, v100, v4
	v_and_or_b32 v164, v164, s18, 1
	v_max_f32_e32 v149, 0xff61b1e6, v164
	v_add_f32_e32 v164, v100, v7
	v_and_or_b32 v164, v164, s18, 2
	v_max_f32_e32 v150, 0xff61b1e6, v164
	v_add_f32_e32 v164, v100, v8
	v_and_or_b32 v164, v164, s18, 3
	v_max_f32_e32 v151, 0xff61b1e6, v164
	v_add_f32_e32 v164, v100, v9
	v_and_or_b32 v164, v164, s18, 4
	v_max_f32_e32 v152, 0xff61b1e6, v164
	v_add_f32_e32 v164, v100, v12
	v_and_or_b32 v164, v164, s18, 5
	v_max_f32_e32 v153, 0xff61b1e6, v164
	v_add_f32_e32 v164, v100, v11
	v_and_or_b32 v164, v164, s18, 6
	v_max_f32_e32 v154, 0xff61b1e6, v164
	v_add_f32_e32 v164, v100, v10
	v_and_or_b32 v164, v164, s18, 7
	v_max_f32_e32 v155, 0xff61b1e6, v164
	v_add_f32_e32 v164, v100, v20
	v_and_or_b32 v164, v164, s18, 8
	v_max_f32_e32 v156, 0xff61b1e6, v164
	v_add_f32_e32 v164, v100, v17
	v_and_or_b32 v164, v164, s18, 9
	v_max_f32_e32 v157, 0xff61b1e6, v164
	v_add_f32_e32 v164, v100, v16
	v_and_or_b32 v164, v164, s18, 10
	v_max_f32_e32 v158, 0xff61b1e6, v164
	v_add_f32_e32 v164, v100, v15
	v_and_or_b32 v164, v164, s18, 11
	v_max_f32_e32 v159, 0xff61b1e6, v164
	v_add_f32_e32 v164, v100, v14
	v_and_or_b32 v164, v164, s18, 12
	v_max_f32_e32 v160, 0xff61b1e6, v164
	v_add_f32_e32 v164, v100, v13
	v_and_or_b32 v164, v164, s18, 13
	v_max_f32_e32 v161, 0xff61b1e6, v164
	v_add_f32_e32 v164, v100, v6
	v_and_or_b32 v164, v164, s18, 14
	v_max_f32_e32 v162, 0xff61b1e6, v164
	v_add_f32_e32 v164, v100, v5
	v_and_or_b32 v164, v164, s18, 15
	v_max_f32_e32 v163, 0xff61b1e6, v164
	v_min_f32_e32 v164, v148, v149
	v_max_f32_e32 v148, v148, v149
	v_min_f32_e32 v149, v164, v150
	v_max_f32_e32 v164, v164, v150
	v_min_f32_e32 v150, v149, v151
	v_max_f32_e32 v149, v149, v151
	v_min_f32_e32 v151, v150, v152
	v_max_f32_e32 v150, v150, v152
	v_min_f32_e32 v152, v151, v153
	v_max_f32_e32 v151, v151, v153
	v_min_f32_e32 v153, v152, v154
	v_max_f32_e32 v152, v152, v154
	v_min_f32_e32 v154, v153, v155
	v_max_f32_e32 v153, v153, v155
	v_min_f32_e32 v155, v154, v156
	v_max_f32_e32 v154, v154, v156
	v_min_f32_e32 v156, v155, v157
	v_max_f32_e32 v155, v155, v157
	v_min_f32_e32 v157, v156, v158
	v_max_f32_e32 v156, v156, v158
	v_min_f32_e32 v158, v157, v159
	v_max_f32_e32 v157, v157, v159
	v_min_f32_e32 v159, v158, v160
	v_max_f32_e32 v158, v158, v160
	v_min_f32_e32 v160, v159, v161
	v_max_f32_e32 v159, v159, v161
	v_min_f32_e32 v161, v160, v162
	v_max_f32_e32 v160, v160, v162
	v_min_f32_e32 v162, v161, v163
	v_max_f32_e32 v161, v161, v163
; DEV void ce(float& a, float& b) { float hi = fmaxf(a, b), lo = fminf(a, b); a = hi; b = lo; }
; DEV void phase_peer_score(const Params& p, int layer, int M, char* smem) {
;     ...
;     for (int i = 0; i < 16; i++)
; #pragma unroll
;       for (int j = 0; j < 16; j++)
;         if ((i + 1) * (j + 1) <= 16) {
;           float v = L0[i] + L1[j];
;           v = __uint_as_float((__float_as_uint(v) & ~255u) | (unsigned)(i * 16 + j));
; #pragma unroll
;           for (int t = 0; t < 16; t++)
;             if (t >= (i + 1) * (j + 1) - 1) ce(R[t], v);
;         }
	v_add_f32_e32 v163, v91, v2
	v_and_or_b32 v163, v163, s18, 16
	v_med3_f32 v162, v161, v162, v163
	v_med3_f32 v161, v160, v161, v163
	v_med3_f32 v160, v159, v160, v163
	v_med3_f32 v159, v158, v159, v163
	v_med3_f32 v158, v157, v158, v163
	v_med3_f32 v157, v156, v157, v163
	v_med3_f32 v156, v155, v156, v163
	v_med3_f32 v155, v154, v155, v163
	v_med3_f32 v154, v153, v154, v163
	v_med3_f32 v153, v152, v153, v163
	v_med3_f32 v152, v151, v152, v163
	v_med3_f32 v151, v150, v151, v163
	v_med3_f32 v150, v149, v150, v163
	v_med3_f32 v149, v164, v149, v163
	v_med3_f32 v164, v148, v164, v163
	v_max_f32_e32 v148, v148, v163
	v_add_f32_e32 v163, v91, v4
	v_and_or_b32 v163, v163, s18, 17
	v_med3_f32 v162, v161, v162, v163
	v_med3_f32 v161, v160, v161, v163
	v_med3_f32 v160, v159, v160, v163
	v_med3_f32 v159, v158, v159, v163
	v_med3_f32 v158, v157, v158, v163
	v_med3_f32 v157, v156, v157, v163
	v_med3_f32 v156, v155, v156, v163
	v_med3_f32 v155, v154, v155, v163
	v_med3_f32 v154, v153, v154, v163
	v_med3_f32 v153, v152, v153, v163
	v_med3_f32 v152, v151, v152, v163
	v_med3_f32 v151, v150, v151, v163
	v_med3_f32 v150, v149, v150, v163
	v_max_f32_e32 v149, v149, v163
	v_add_f32_e32 v163, v91, v7
	v_and_or_b32 v163, v163, s18, 18
	v_med3_f32 v162, v161, v162, v163
	v_med3_f32 v161, v160, v161, v163
	v_med3_f32 v160, v159, v160, v163
	v_med3_f32 v159, v158, v159, v163
	v_med3_f32 v158, v157, v158, v163
	v_med3_f32 v157, v156, v157, v163
	v_med3_f32 v156, v155, v156, v163
	v_med3_f32 v155, v154, v155, v163
	v_med3_f32 v154, v153, v154, v163
	v_med3_f32 v153, v152, v153, v163
	v_med3_f32 v152, v151, v152, v163
	v_max_f32_e32 v151, v151, v163
	v_add_f32_e32 v163, v91, v8
	v_and_or_b32 v163, v163, s18, 19
	v_med3_f32 v162, v161, v162, v163
	v_med3_f32 v161, v160, v161, v163
	v_med3_f32 v160, v159, v160, v163
	v_med3_f32 v159, v158, v159, v163
	v_med3_f32 v158, v157, v158, v163
	v_med3_f32 v157, v156, v157, v163
	v_med3_f32 v156, v155, v156, v163
	v_med3_f32 v155, v154, v155, v163
	v_med3_f32 v154, v153, v154, v163
	v_max_f32_e32 v153, v153, v163
	v_add_f32_e32 v163, v91, v9
	v_and_or_b32 v163, v163, s18, 20
	v_med3_f32 v162, v161, v162, v163
	v_med3_f32 v161, v160, v161, v163
	v_med3_f32 v160, v159, v160, v163
	v_med3_f32 v159, v158, v159, v163
	v_med3_f32 v158, v157, v158, v163
	v_med3_f32 v157, v156, v157, v163
	v_med3_f32 v156, v155, v156, v163
	v_max_f32_e32 v155, v155, v163
	v_add_f32_e32 v163, v91, v12
	v_and_or_b32 v163, v163, s18, 21
	v_med3_f32 v162, v161, v162, v163
	v_med3_f32 v161, v160, v161, v163
	v_med3_f32 v160, v159, v160, v163
	v_med3_f32 v159, v158, v159, v163
	v_med3_f32 v158, v157, v158, v163
	v_max_f32_e32 v157, v157, v163
	v_add_f32_e32 v163, v91, v11
	v_and_or_b32 v163, v163, s18, 22
	v_med3_f32 v162, v161, v162, v163
	v_med3_f32 v161, v160, v161, v163
	v_med3_f32 v160, v159, v160, v163
	v_max_f32_e32 v159, v159, v163
	v_add_f32_e32 v163, v91, v10
	v_and_or_b32 v163, v163, s18, 23
	v_med3_f32 v162, v161, v162, v163
	v_max_f32_e32 v161, v161, v163
	v_add_f32_e32 v163, v87, v2
	v_and_or_b32 v163, v163, s18, 32
	v_med3_f32 v162, v161, v162, v163
	v_med3_f32 v161, v160, v161, v163
	v_med3_f32 v160, v159, v160, v163
	v_med3_f32 v159, v158, v159, v163
	v_med3_f32 v158, v157, v158, v163
	v_med3_f32 v157, v156, v157, v163
	v_med3_f32 v156, v155, v156, v163
	v_med3_f32 v155, v154, v155, v163
	v_med3_f32 v154, v153, v154, v163
	v_med3_f32 v153, v152, v153, v163
	v_med3_f32 v152, v151, v152, v163
	v_med3_f32 v151, v150, v151, v163
	v_med3_f32 v150, v149, v150, v163
	v_med3_f32 v149, v164, v149, v163
	v_max_f32_e32 v164, v164, v163
	v_add_f32_e32 v163, v87, v4
	v_and_or_b32 v163, v163, s18, 33
	v_med3_f32 v162, v161, v162, v163
	v_med3_f32 v161, v160, v161, v163
	v_med3_f32 v160, v159, v160, v163
	v_med3_f32 v159, v158, v159, v163
	v_med3_f32 v158, v157, v158, v163
	v_med3_f32 v157, v156, v157, v163
	v_med3_f32 v156, v155, v156, v163
	v_med3_f32 v155, v154, v155, v163
	v_med3_f32 v154, v153, v154, v163
	v_med3_f32 v153, v152, v153, v163
	v_med3_f32 v152, v151, v152, v163
	v_max_f32_e32 v151, v151, v163
	v_add_f32_e32 v163, v87, v7
	v_and_or_b32 v163, v163, s18, 34
	v_med3_f32 v162, v161, v162, v163
	v_med3_f32 v161, v160, v161, v163
	v_med3_f32 v160, v159, v160, v163
	v_med3_f32 v159, v158, v159, v163
	v_med3_f32 v158, v157, v158, v163
	v_med3_f32 v157, v156, v157, v163
	v_med3_f32 v156, v155, v156, v163
	v_med3_f32 v155, v154, v155, v163
	v_max_f32_e32 v154, v154, v163
	v_add_f32_e32 v163, v87, v8
	v_and_or_b32 v163, v163, s18, 35
	v_med3_f32 v162, v161, v162, v163
	v_med3_f32 v161, v160, v161, v163
	v_med3_f32 v160, v159, v160, v163
	v_med3_f32 v159, v158, v159, v163
	v_med3_f32 v158, v157, v158, v163
	v_max_f32_e32 v157, v157, v163
	v_add_f32_e32 v163, v87, v9
	v_and_or_b32 v163, v163, s18, 36
	v_med3_f32 v162, v161, v162, v163
	v_med3_f32 v161, v160, v161, v163
	v_max_f32_e32 v160, v160, v163
	v_add_f32_e32 v163, v83, v2
	v_and_or_b32 v163, v163, s18, 48
	v_med3_f32 v162, v161, v162, v163
	v_med3_f32 v161, v160, v161, v163
	v_med3_f32 v160, v159, v160, v163
	v_med3_f32 v159, v158, v159, v163
	v_med3_f32 v158, v157, v158, v163
	v_med3_f32 v157, v156, v157, v163
	v_med3_f32 v156, v155, v156, v163
	v_med3_f32 v155, v154, v155, v163
	v_med3_f32 v154, v153, v154, v163
	v_med3_f32 v153, v152, v153, v163
	v_med3_f32 v152, v151, v152, v163
	v_med3_f32 v151, v150, v151, v163
	v_med3_f32 v150, v149, v150, v163
	v_max_f32_e32 v149, v149, v163
	v_add_f32_e32 v163, v83, v4
	v_and_or_b32 v163, v163, s18, 49
	v_med3_f32 v162, v161, v162, v163
	v_med3_f32 v161, v160, v161, v163
	v_med3_f32 v160, v159, v160, v163
	v_med3_f32 v159, v158, v159, v163
; DEV void ce(float& a, float& b) { float hi = fmaxf(a, b), lo = fminf(a, b); a = hi; b = lo; }
; DEV void phase_peer_score(const Params& p, int layer, int M, char* smem) {
;     ...
;     for (int i = 0; i < 16; i++)
; #pragma unroll
;       for (int j = 0; j < 16; j++)
;         if ((i + 1) * (j + 1) <= 16) {
;           float v = L0[i] + L1[j];
;           v = __uint_as_float((__float_as_uint(v) & ~255u) | (unsigned)(i * 16 + j));
; #pragma unroll
;           for (int t = 0; t < 16; t++)
;             if (t >= (i + 1) * (j + 1) - 1) ce(R[t], v);
;         }
	v_med3_f32 v158, v157, v158, v163
	v_med3_f32 v157, v156, v157, v163
	v_med3_f32 v156, v155, v156, v163
	v_med3_f32 v155, v154, v155, v163
	v_med3_f32 v154, v153, v154, v163
	v_max_f32_e32 v153, v153, v163
	v_add_f32_e32 v163, v83, v7
	v_and_or_b32 v163, v163, s18, 50
	v_med3_f32 v162, v161, v162, v163
	v_med3_f32 v161, v160, v161, v163
	v_med3_f32 v160, v159, v160, v163
	v_med3_f32 v159, v158, v159, v163
	v_med3_f32 v158, v157, v158, v163
	v_max_f32_e32 v157, v157, v163
	v_add_f32_e32 v163, v83, v8
	v_and_or_b32 v163, v163, s18, 51
	v_med3_f32 v162, v161, v162, v163
	v_max_f32_e32 v161, v161, v163
	v_add_f32_e32 v163, v79, v2
	v_and_or_b32 v163, v163, s18, 64
	v_med3_f32 v162, v161, v162, v163
	v_med3_f32 v161, v160, v161, v163
	v_med3_f32 v160, v159, v160, v163
	v_med3_f32 v159, v158, v159, v163
	v_med3_f32 v158, v157, v158, v163
	v_med3_f32 v157, v156, v157, v163
	v_med3_f32 v156, v155, v156, v163
	v_med3_f32 v155, v154, v155, v163
	v_med3_f32 v154, v153, v154, v163
	v_med3_f32 v153, v152, v153, v163
	v_med3_f32 v152, v151, v152, v163
	v_med3_f32 v151, v150, v151, v163
	v_max_f32_e32 v150, v150, v163
	v_add_f32_e32 v163, v79, v4
	v_and_b32_e32 v163, 0xffffff00, v163
	v_or_b32_e32 v163, 0x41, v163
	v_med3_f32 v162, v161, v162, v163
	v_med3_f32 v161, v160, v161, v163
	v_med3_f32 v160, v159, v160, v163
	v_med3_f32 v159, v158, v159, v163
	v_med3_f32 v158, v157, v158, v163
	v_med3_f32 v157, v156, v157, v163
	v_med3_f32 v156, v155, v156, v163
	v_max_f32_e32 v155, v155, v163
	v_add_f32_e32 v163, v79, v7
	v_and_b32_e32 v163, 0xffffff00, v163
	v_or_b32_e32 v163, 0x42, v163
	v_med3_f32 v162, v161, v162, v163
	v_med3_f32 v161, v160, v161, v163
	v_max_f32_e32 v160, v160, v163
	v_add_f32_e32 v163, v75, v2
	v_and_b32_e32 v163, 0xffffff00, v163
	v_or_b32_e32 v163, 0x50, v163
	v_med3_f32 v162, v161, v162, v163
	v_med3_f32 v161, v160, v161, v163
	v_med3_f32 v160, v159, v160, v163
	v_med3_f32 v159, v158, v159, v163
	v_med3_f32 v158, v157, v158, v163
	v_med3_f32 v157, v156, v157, v163
	v_med3_f32 v156, v155, v156, v163
	v_med3_f32 v155, v154, v155, v163
	v_med3_f32 v154, v153, v154, v163
	v_med3_f32 v153, v152, v153, v163
	v_med3_f32 v152, v151, v152, v163
	v_max_f32_e32 v151, v151, v163
	v_add_f32_e32 v163, v75, v4
	v_and_b32_e32 v163, 0xffffff00, v163
	v_or_b32_e32 v163, 0x51, v163
	v_med3_f32 v162, v161, v162, v163
	v_med3_f32 v161, v160, v161, v163
	v_med3_f32 v160, v159, v160, v163
	v_med3_f32 v159, v158, v159, v163
	v_med3_f32 v158, v157, v158, v163
	v_max_f32_e32 v157, v157, v163
	v_add_f32_e32 v163, v71, v2
	v_and_b32_e32 v163, 0xffffff00, v163
	v_or_b32_e32 v163, 0x60, v163
	v_med3_f32 v162, v161, v162, v163
	v_med3_f32 v161, v160, v161, v163
	v_med3_f32 v160, v159, v160, v163
	v_med3_f32 v159, v158, v159, v163
	v_med3_f32 v158, v157, v158, v163
	v_med3_f32 v157, v156, v157, v163
	v_med3_f32 v156, v155, v156, v163
	v_med3_f32 v155, v154, v155, v163
	v_med3_f32 v154, v153, v154, v163
	v_med3_f32 v153, v152, v153, v163
	v_max_f32_e32 v152, v152, v163
	v_add_f32_e32 v163, v71, v4
	v_and_b32_e32 v163, 0xffffff00, v163
	v_or_b32_e32 v163, 0x61, v163
	v_med3_f32 v162, v161, v162, v163
	v_med3_f32 v161, v160, v161, v163
	v_med3_f32 v160, v159, v160, v163
	v_max_f32_e32 v159, v159, v163
	v_add_f32_e32 v163, v63, v2
	v_and_b32_e32 v163, 0xffffff00, v163
	v_or_b32_e32 v163, 0x70, v163
	v_med3_f32 v162, v161, v162, v163
	v_med3_f32 v161, v160, v161, v163
	v_med3_f32 v160, v159, v160, v163
	v_med3_f32 v159, v158, v159, v163
	v_med3_f32 v158, v157, v158, v163
	v_med3_f32 v157, v156, v157, v163
	v_med3_f32 v156, v155, v156, v163
	v_med3_f32 v155, v154, v155, v163
	v_med3_f32 v154, v153, v154, v163
	v_max_f32_e32 v153, v153, v163
	v_add_f32_e32 v163, v63, v4
	v_and_b32_e32 v163, 0xffffff00, v163
	v_or_b32_e32 v163, 0x71, v163
	v_med3_f32 v162, v161, v162, v163
	v_max_f32_e32 v161, v161, v163
	v_add_f32_e32 v163, v67, v2
	v_and_b32_e32 v163, 0xffffff00, v163
	v_or_b32_e32 v163, 0x80, v163
	v_med3_f32 v162, v161, v162, v163
	v_med3_f32 v161, v160, v161, v163
	v_med3_f32 v160, v159, v160, v163
	v_med3_f32 v159, v158, v159, v163
	v_med3_f32 v158, v157, v158, v163
	v_med3_f32 v157, v156, v157, v163
	v_med3_f32 v156, v155, v156, v163
	v_med3_f32 v155, v154, v155, v163
	v_max_f32_e32 v154, v154, v163
	v_add_f32_e32 v163, v59, v2
	v_and_b32_e32 v163, 0xffffff00, v163
	v_or_b32_e32 v163, 0x90, v163
	v_med3_f32 v162, v161, v162, v163
	v_med3_f32 v161, v160, v161, v163
	v_med3_f32 v160, v159, v160, v163
	v_med3_f32 v159, v158, v159, v163
	v_med3_f32 v158, v157, v158, v163
	v_med3_f32 v157, v156, v157, v163
	v_med3_f32 v156, v155, v156, v163
	v_max_f32_e32 v155, v155, v163
	v_add_f32_e32 v163, v55, v2
	v_and_b32_e32 v163, 0xffffff00, v163
	v_or_b32_e32 v163, 0xa0, v163
	v_med3_f32 v162, v161, v162, v163
	v_med3_f32 v161, v160, v161, v163
	v_med3_f32 v160, v159, v160, v163
	v_med3_f32 v159, v158, v159, v163
	v_med3_f32 v158, v157, v158, v163
	v_med3_f32 v157, v156, v157, v163
	v_max_f32_e32 v156, v156, v163
	v_add_f32_e32 v163, v47, v2
	v_and_b32_e32 v163, 0xffffff00, v163
	v_or_b32_e32 v163, 0xb0, v163
	v_med3_f32 v162, v161, v162, v163
	v_med3_f32 v161, v160, v161, v163
	v_med3_f32 v160, v159, v160, v163
	v_med3_f32 v159, v158, v159, v163
	v_med3_f32 v158, v157, v158, v163
	v_max_f32_e32 v157, v157, v163
	v_add_f32_e32 v163, v51, v2
	v_and_b32_e32 v163, 0xffffff00, v163
	v_or_b32_e32 v163, 0xc0, v163
	v_med3_f32 v162, v161, v162, v163
	v_med3_f32 v161, v160, v161, v163
	v_med3_f32 v160, v159, v160, v163
	v_med3_f32 v159, v158, v159, v163
	v_max_f32_e32 v158, v158, v163
	v_add_f32_e32 v163, v39, v2
	v_and_b32_e32 v163, 0xffffff00, v163
	v_or_b32_e32 v163, 0xd0, v163
; DEV void ce(float& a, float& b) { float hi = fmaxf(a, b), lo = fminf(a, b); a = hi; b = lo; }
; DEV void phase_peer_score(const Params& p, int layer, int M, char* smem) {
;     ...
;     for (int i = 0; i < 16; i++)
; #pragma unroll
;       for (int j = 0; j < 16; j++)
;         if ((i + 1) * (j + 1) <= 16) {
;           float v = L0[i] + L1[j];
;           v = __uint_as_float((__float_as_uint(v) & ~255u) | (unsigned)(i * 16 + j));
; #pragma unroll
;           for (int t = 0; t < 16; t++)
;             if (t >= (i + 1) * (j + 1) - 1) ce(R[t], v);
;         }
	v_med3_f32 v162, v161, v162, v163
	v_med3_f32 v161, v160, v161, v163
	v_med3_f32 v160, v159, v160, v163
	v_max_f32_e32 v159, v159, v163
	v_add_f32_e32 v163, v43, v2
	v_and_b32_e32 v163, 0xffffff00, v163
	v_or_b32_e32 v163, 0xe0, v163
	v_med3_f32 v162, v161, v162, v163
	v_med3_f32 v161, v160, v161, v163
	v_max_f32_e32 v160, v160, v163
	v_add_f32_e32 v163, v0, v2
	v_and_b32_e32 v163, 0xffffff00, v163
	v_or_b32_e32 v163, 0xf0, v163
	v_med3_f32 v162, v161, v162, v163
	v_max_f32_e32 v161, v161, v163
	v_cmp_le_f32_e64 s[40:41], v148, v164
	v_cmp_le_f32_e32 vcc, v164, v149
	s_or_b64 s[40:41], s[40:41], vcc
	v_cmp_le_f32_e32 vcc, v149, v150
	s_or_b64 s[40:41], s[40:41], vcc
	v_cmp_le_f32_e32 vcc, v150, v151
	s_or_b64 s[40:41], s[40:41], vcc
	v_cmp_le_f32_e32 vcc, v151, v152
	s_or_b64 s[40:41], s[40:41], vcc
	v_cmp_le_f32_e32 vcc, v152, v153
	s_or_b64 s[40:41], s[40:41], vcc
	v_cmp_le_f32_e32 vcc, v153, v154
	s_or_b64 s[40:41], s[40:41], vcc
	v_cmp_le_f32_e32 vcc, v154, v155
	s_or_b64 s[40:41], s[40:41], vcc
	v_cmp_le_f32_e32 vcc, v155, v156
	s_or_b64 s[40:41], s[40:41], vcc
	v_cmp_le_f32_e32 vcc, v156, v157
	s_or_b64 s[40:41], s[40:41], vcc
	v_cmp_le_f32_e32 vcc, v157, v158
	s_or_b64 s[40:41], s[40:41], vcc
	v_cmp_le_f32_e32 vcc, v158, v159
	s_or_b64 s[40:41], s[40:41], vcc
	v_cmp_le_f32_e32 vcc, v159, v160
	s_or_b64 s[40:41], s[40:41], vcc
	v_cmp_le_f32_e32 vcc, v160, v161
	s_or_b64 s[40:41], s[40:41], vcc
	v_cmp_le_f32_e32 vcc, v161, v162
	s_or_b64 s[40:41], s[40:41], vcc
	s_and_b64 s[40:41], s[40:41], exec
	s_cbranch_scc0 .Lmed3_ok_bb_637
	v_mov_b32_e32 v148, 0xff61b1e6
	v_mov_b32_e32 v164, 0xff61b1e6
	v_mov_b32_e32 v149, 0xff61b1e6
	v_mov_b32_e32 v150, 0xff61b1e6
	v_mov_b32_e32 v151, 0xff61b1e6
	v_mov_b32_e32 v152, 0xff61b1e6
	v_mov_b32_e32 v153, 0xff61b1e6
	v_mov_b32_e32 v154, 0xff61b1e6
	v_mov_b32_e32 v155, 0xff61b1e6
	v_mov_b32_e32 v156, 0xff61b1e6
	v_mov_b32_e32 v157, 0xff61b1e6
	v_mov_b32_e32 v158, 0xff61b1e6
	v_mov_b32_e32 v159, 0xff61b1e6
	v_mov_b32_e32 v160, 0xff61b1e6
	v_mov_b32_e32 v161, 0xff61b1e6
	v_mov_b32_e32 v162, 0xff61b1e6
	v_add_f32_e32 v163, v100, v2
	v_and_or_b32 v163, v163, s18, 0
	v_min_f32_e32 v165, v148, v163
	v_max_f32_e32 v148, v148, v163
	v_min_f32_e32 v163, v164, v165
	v_max_f32_e32 v164, v164, v165
	v_min_f32_e32 v165, v149, v163
	v_max_f32_e32 v149, v149, v163
	v_min_f32_e32 v163, v150, v165
	v_max_f32_e32 v150, v150, v165
	v_min_f32_e32 v165, v151, v163
	v_max_f32_e32 v151, v151, v163
	v_min_f32_e32 v163, v152, v165
	v_max_f32_e32 v152, v152, v165
	v_min_f32_e32 v165, v153, v163
	v_max_f32_e32 v153, v153, v163
	v_min_f32_e32 v163, v154, v165
	v_max_f32_e32 v154, v154, v165
	v_min_f32_e32 v165, v155, v163
	v_max_f32_e32 v155, v155, v163
	v_min_f32_e32 v163, v156, v165
	v_max_f32_e32 v156, v156, v165
	v_min_f32_e32 v165, v157, v163
	v_max_f32_e32 v157, v157, v163
	v_min_f32_e32 v163, v158, v165
	v_max_f32_e32 v158, v158, v165
	v_min_f32_e32 v165, v159, v163
	v_max_f32_e32 v159, v159, v163
	v_min_f32_e32 v163, v160, v165
	v_max_f32_e32 v160, v160, v165
	v_min_f32_e32 v165, v161, v163
	v_max_f32_e32 v161, v161, v163
	v_max_f32_e32 v162, v162, v165
	v_add_f32_e32 v163, v100, v4
	v_and_or_b32 v163, v163, s18, 1
	v_min_f32_e32 v165, v164, v163
	v_max_f32_e32 v164, v164, v163
	v_min_f32_e32 v163, v149, v165
	v_max_f32_e32 v149, v149, v165
	v_min_f32_e32 v165, v150, v163
	v_max_f32_e32 v150, v150, v163
	v_min_f32_e32 v163, v151, v165
	v_max_f32_e32 v151, v151, v165
	v_min_f32_e32 v165, v152, v163
	v_max_f32_e32 v152, v152, v163
	v_min_f32_e32 v163, v153, v165
	v_max_f32_e32 v153, v153, v165
	v_min_f32_e32 v165, v154, v163
	v_max_f32_e32 v154, v154, v163
	v_min_f32_e32 v163, v155, v165
	v_max_f32_e32 v155, v155, v165
	v_min_f32_e32 v165, v156, v163
	v_max_f32_e32 v156, v156, v163
	v_min_f32_e32 v163, v157, v165
	v_max_f32_e32 v157, v157, v165
	v_min_f32_e32 v165, v158, v163
	v_max_f32_e32 v158, v158, v163
	v_min_f32_e32 v163, v159, v165
	v_max_f32_e32 v159, v159, v165
	v_min_f32_e32 v165, v160, v163
	v_max_f32_e32 v160, v160, v163
	v_min_f32_e32 v163, v161, v165
	v_max_f32_e32 v161, v161, v165
	v_max_f32_e32 v162, v162, v163
	v_add_f32_e32 v163, v100, v7
	v_and_or_b32 v163, v163, s18, 2
	v_min_f32_e32 v165, v149, v163
	v_max_f32_e32 v149, v149, v163
	v_min_f32_e32 v163, v150, v165
	v_max_f32_e32 v150, v150, v165
	v_min_f32_e32 v165, v151, v163
	v_max_f32_e32 v151, v151, v163
	v_min_f32_e32 v163, v152, v165
	v_max_f32_e32 v152, v152, v165
	v_min_f32_e32 v165, v153, v163
	v_max_f32_e32 v153, v153, v163
	v_min_f32_e32 v163, v154, v165
	v_max_f32_e32 v154, v154, v165
	v_min_f32_e32 v165, v155, v163
	v_max_f32_e32 v155, v155, v163
	v_min_f32_e32 v163, v156, v165
	v_max_f32_e32 v156, v156, v165
	v_min_f32_e32 v165, v157, v163
	v_max_f32_e32 v157, v157, v163
	v_min_f32_e32 v163, v158, v165
	v_max_f32_e32 v158, v158, v165
	v_min_f32_e32 v165, v159, v163
	v_max_f32_e32 v159, v159, v163
	v_min_f32_e32 v163, v160, v165
	v_max_f32_e32 v160, v160, v165
	v_min_f32_e32 v165, v161, v163
	v_max_f32_e32 v161, v161, v163
	v_max_f32_e32 v162, v162, v165
	v_add_f32_e32 v163, v100, v8
	v_and_or_b32 v163, v163, s18, 3
	v_min_f32_e32 v165, v150, v163
	v_max_f32_e32 v150, v150, v163
	v_min_f32_e32 v163, v151, v165
	v_max_f32_e32 v151, v151, v165
	v_min_f32_e32 v165, v152, v163
	v_max_f32_e32 v152, v152, v163
	v_min_f32_e32 v163, v153, v165
	v_max_f32_e32 v153, v153, v165
	v_min_f32_e32 v165, v154, v163
	v_max_f32_e32 v154, v154, v163
	v_min_f32_e32 v163, v155, v165
	v_max_f32_e32 v155, v155, v165
	v_min_f32_e32 v165, v156, v163
	v_max_f32_e32 v156, v156, v163
	v_min_f32_e32 v163, v157, v165
	v_max_f32_e32 v157, v157, v165
	v_min_f32_e32 v165, v158, v163
; DEV void ce(float& a, float& b) { float hi = fmaxf(a, b), lo = fminf(a, b); a = hi; b = lo; }
; DEV void phase_peer_score(const Params& p, int layer, int M, char* smem) {
;     ...
; #pragma unroll
;     for (int i = 0; i < 16; i++) R[i] = -3.0e38f;
; #pragma unroll
;     for (int i = 0; i < 16; i++)
; #pragma unroll
;       for (int j = 0; j < 16; j++)
;         if ((i + 1) * (j + 1) <= 16) {
;           float v = L0[i] + L1[j];
;           v = __uint_as_float((__float_as_uint(v) & ~255u) | (unsigned)(i * 16 + j));
; #pragma unroll
;           for (int t = 0; t < 16; t++)
;             if (t >= (i + 1) * (j + 1) - 1) ce(R[t], v);
;         }
	v_max_f32_e32 v158, v158, v163
	v_min_f32_e32 v163, v159, v165
	v_max_f32_e32 v159, v159, v165
	v_min_f32_e32 v165, v160, v163
	v_max_f32_e32 v160, v160, v163
	v_min_f32_e32 v163, v161, v165
	v_max_f32_e32 v161, v161, v165
	v_max_f32_e32 v162, v162, v163
	v_add_f32_e32 v163, v100, v9
	v_and_or_b32 v163, v163, s18, 4
	v_min_f32_e32 v165, v151, v163
	v_max_f32_e32 v151, v151, v163
	v_min_f32_e32 v163, v152, v165
	v_max_f32_e32 v152, v152, v165
	v_min_f32_e32 v165, v153, v163
	v_max_f32_e32 v153, v153, v163
	v_min_f32_e32 v163, v154, v165
	v_max_f32_e32 v154, v154, v165
	v_min_f32_e32 v165, v155, v163
	v_max_f32_e32 v155, v155, v163
	v_min_f32_e32 v163, v156, v165
	v_max_f32_e32 v156, v156, v165
	v_min_f32_e32 v165, v157, v163
	v_max_f32_e32 v157, v157, v163
	v_min_f32_e32 v163, v158, v165
	v_max_f32_e32 v158, v158, v165
	v_min_f32_e32 v165, v159, v163
	v_max_f32_e32 v159, v159, v163
	v_min_f32_e32 v163, v160, v165
	v_max_f32_e32 v160, v160, v165
	v_min_f32_e32 v165, v161, v163
	v_max_f32_e32 v161, v161, v163
	v_max_f32_e32 v162, v162, v165
	v_add_f32_e32 v163, v100, v12
	v_and_or_b32 v163, v163, s18, 5
	v_min_f32_e32 v165, v152, v163
	v_max_f32_e32 v152, v152, v163
	v_min_f32_e32 v163, v153, v165
	v_max_f32_e32 v153, v153, v165
	v_min_f32_e32 v165, v154, v163
	v_max_f32_e32 v154, v154, v163
	v_min_f32_e32 v163, v155, v165
	v_max_f32_e32 v155, v155, v165
	v_min_f32_e32 v165, v156, v163
	v_max_f32_e32 v156, v156, v163
	v_min_f32_e32 v163, v157, v165
	v_max_f32_e32 v157, v157, v165
	v_min_f32_e32 v165, v158, v163
	v_max_f32_e32 v158, v158, v163
	v_min_f32_e32 v163, v159, v165
	v_max_f32_e32 v159, v159, v165
	v_min_f32_e32 v165, v160, v163
	v_max_f32_e32 v160, v160, v163
	v_min_f32_e32 v163, v161, v165
	v_max_f32_e32 v161, v161, v165
	v_max_f32_e32 v162, v162, v163
	v_add_f32_e32 v163, v100, v11
	v_and_or_b32 v163, v163, s18, 6
	v_min_f32_e32 v165, v153, v163
	v_max_f32_e32 v153, v153, v163
	v_min_f32_e32 v163, v154, v165
	v_max_f32_e32 v154, v154, v165
	v_min_f32_e32 v165, v155, v163
	v_max_f32_e32 v155, v155, v163
	v_min_f32_e32 v163, v156, v165
	v_max_f32_e32 v156, v156, v165
	v_min_f32_e32 v165, v157, v163
	v_max_f32_e32 v157, v157, v163
	v_min_f32_e32 v163, v158, v165
	v_max_f32_e32 v158, v158, v165
	v_min_f32_e32 v165, v159, v163
	v_max_f32_e32 v159, v159, v163
	v_min_f32_e32 v163, v160, v165
	v_max_f32_e32 v160, v160, v165
	v_min_f32_e32 v165, v161, v163
	v_max_f32_e32 v161, v161, v163
	v_max_f32_e32 v162, v162, v165
	v_add_f32_e32 v163, v100, v10
	v_and_or_b32 v163, v163, s18, 7
	v_min_f32_e32 v165, v154, v163
	v_max_f32_e32 v154, v154, v163
	v_min_f32_e32 v163, v155, v165
	v_max_f32_e32 v155, v155, v165
	v_min_f32_e32 v165, v156, v163
	v_max_f32_e32 v156, v156, v163
	v_min_f32_e32 v163, v157, v165
	v_max_f32_e32 v157, v157, v165
	v_min_f32_e32 v165, v158, v163
	v_max_f32_e32 v158, v158, v163
	v_min_f32_e32 v163, v159, v165
	v_max_f32_e32 v159, v159, v165
	v_min_f32_e32 v165, v160, v163
	v_max_f32_e32 v160, v160, v163
	v_min_f32_e32 v163, v161, v165
	v_max_f32_e32 v161, v161, v165
	v_max_f32_e32 v162, v162, v163
	v_add_f32_e32 v163, v100, v20
	v_and_or_b32 v163, v163, s18, 8
	v_min_f32_e32 v165, v155, v163
	v_max_f32_e32 v155, v155, v163
	v_min_f32_e32 v163, v156, v165
	v_max_f32_e32 v156, v156, v165
	v_min_f32_e32 v165, v157, v163
	v_max_f32_e32 v157, v157, v163
	v_min_f32_e32 v163, v158, v165
	v_max_f32_e32 v158, v158, v165
	v_min_f32_e32 v165, v159, v163
	v_max_f32_e32 v159, v159, v163
	v_min_f32_e32 v163, v160, v165
	v_max_f32_e32 v160, v160, v165
	v_min_f32_e32 v165, v161, v163
	v_max_f32_e32 v161, v161, v163
	v_max_f32_e32 v162, v162, v165
	v_add_f32_e32 v163, v100, v17
	v_and_or_b32 v163, v163, s18, 9
	v_min_f32_e32 v165, v156, v163
	v_max_f32_e32 v156, v156, v163
	v_min_f32_e32 v163, v157, v165
	v_max_f32_e32 v157, v157, v165
	v_min_f32_e32 v165, v158, v163
	v_max_f32_e32 v158, v158, v163
	v_min_f32_e32 v163, v159, v165
	v_max_f32_e32 v159, v159, v165
	v_min_f32_e32 v165, v160, v163
	v_max_f32_e32 v160, v160, v163
	v_min_f32_e32 v163, v161, v165
	v_max_f32_e32 v161, v161, v165
	v_max_f32_e32 v162, v162, v163
	v_add_f32_e32 v163, v100, v16
	v_and_or_b32 v163, v163, s18, 10
	v_min_f32_e32 v165, v157, v163
	v_max_f32_e32 v157, v157, v163
	v_min_f32_e32 v163, v158, v165
	v_max_f32_e32 v158, v158, v165
	v_min_f32_e32 v165, v159, v163
	v_max_f32_e32 v159, v159, v163
	v_min_f32_e32 v163, v160, v165
	v_max_f32_e32 v160, v160, v165
	v_min_f32_e32 v165, v161, v163
	v_max_f32_e32 v161, v161, v163
	v_max_f32_e32 v162, v162, v165
	v_add_f32_e32 v163, v100, v15
	v_and_or_b32 v163, v163, s18, 11
	v_min_f32_e32 v165, v158, v163
	v_max_f32_e32 v158, v158, v163
	v_min_f32_e32 v163, v159, v165
	v_max_f32_e32 v159, v159, v165
	v_min_f32_e32 v165, v160, v163
	v_max_f32_e32 v160, v160, v163
	v_min_f32_e32 v163, v161, v165
	v_max_f32_e32 v161, v161, v165
	v_max_f32_e32 v162, v162, v163
	v_add_f32_e32 v163, v100, v14
	v_and_or_b32 v163, v163, s18, 12
	v_min_f32_e32 v165, v159, v163
	v_max_f32_e32 v159, v159, v163
	v_min_f32_e32 v163, v160, v165
	v_max_f32_e32 v160, v160, v165
	v_min_f32_e32 v165, v161, v163
	v_max_f32_e32 v161, v161, v163
	v_max_f32_e32 v162, v162, v165
	v_add_f32_e32 v163, v100, v13
	v_and_or_b32 v163, v163, s18, 13
	v_min_f32_e32 v165, v160, v163
	v_max_f32_e32 v160, v160, v163
	v_min_f32_e32 v163, v161, v165
	v_max_f32_e32 v161, v161, v165
	v_max_f32_e32 v162, v162, v163
	v_add_f32_e32 v163, v100, v6
	v_and_or_b32 v163, v163, s18, 14
	v_min_f32_e32 v165, v161, v163
	v_max_f32_e32 v161, v161, v163
	v_max_f32_e32 v162, v162, v165
	v_add_f32_e32 v163, v100, v5
	v_and_or_b32 v163, v163, s18, 15
	v_max_f32_e32 v162, v162, v163
; DEV void ce(float& a, float& b) { float hi = fmaxf(a, b), lo = fminf(a, b); a = hi; b = lo; }
; DEV void phase_peer_score(const Params& p, int layer, int M, char* smem) {
;     ...
; #pragma unroll
;     for (int i = 0; i < 16; i++) R[i] = -3.0e38f;
; #pragma unroll
;     for (int i = 0; i < 16; i++)
; #pragma unroll
;       for (int j = 0; j < 16; j++)
;         if ((i + 1) * (j + 1) <= 16) {
;           float v = L0[i] + L1[j];
;           v = __uint_as_float((__float_as_uint(v) & ~255u) | (unsigned)(i * 16 + j));
; #pragma unroll
;           for (int t = 0; t < 16; t++)
;             if (t >= (i + 1) * (j + 1) - 1) ce(R[t], v);
;         }
	v_add_f32_e32 v163, v91, v2
	v_and_or_b32 v163, v163, s18, 16
	v_min_f32_e32 v165, v164, v163
	v_max_f32_e32 v164, v164, v163
	v_min_f32_e32 v163, v149, v165
	v_max_f32_e32 v149, v149, v165
	v_min_f32_e32 v165, v150, v163
	v_max_f32_e32 v150, v150, v163
	v_min_f32_e32 v163, v151, v165
	v_max_f32_e32 v151, v151, v165
	v_min_f32_e32 v165, v152, v163
	v_max_f32_e32 v152, v152, v163
	v_min_f32_e32 v163, v153, v165
	v_max_f32_e32 v153, v153, v165
	v_min_f32_e32 v165, v154, v163
	v_max_f32_e32 v154, v154, v163
	v_min_f32_e32 v163, v155, v165
	v_max_f32_e32 v155, v155, v165
	v_min_f32_e32 v165, v156, v163
	v_max_f32_e32 v156, v156, v163
	v_min_f32_e32 v163, v157, v165
	v_max_f32_e32 v157, v157, v165
	v_min_f32_e32 v165, v158, v163
	v_max_f32_e32 v158, v158, v163
	v_min_f32_e32 v163, v159, v165
	v_max_f32_e32 v159, v159, v165
	v_min_f32_e32 v165, v160, v163
	v_max_f32_e32 v160, v160, v163
	v_min_f32_e32 v163, v161, v165
	v_max_f32_e32 v161, v161, v165
	v_max_f32_e32 v162, v162, v163
	v_add_f32_e32 v163, v91, v4
	v_and_or_b32 v163, v163, s18, 17
	v_min_f32_e32 v165, v150, v163
	v_max_f32_e32 v150, v150, v163
	v_min_f32_e32 v163, v151, v165
	v_max_f32_e32 v151, v151, v165
	v_min_f32_e32 v165, v152, v163
	v_max_f32_e32 v152, v152, v163
	v_min_f32_e32 v163, v153, v165
	v_max_f32_e32 v153, v153, v165
	v_min_f32_e32 v165, v154, v163
	v_max_f32_e32 v154, v154, v163
	v_min_f32_e32 v163, v155, v165
	v_max_f32_e32 v155, v155, v165
	v_min_f32_e32 v165, v156, v163
	v_max_f32_e32 v156, v156, v163
	v_min_f32_e32 v163, v157, v165
	v_max_f32_e32 v157, v157, v165
	v_min_f32_e32 v165, v158, v163
	v_max_f32_e32 v158, v158, v163
	v_min_f32_e32 v163, v159, v165
	v_max_f32_e32 v159, v159, v165
	v_min_f32_e32 v165, v160, v163
	v_max_f32_e32 v160, v160, v163
	v_min_f32_e32 v163, v161, v165
	v_max_f32_e32 v161, v161, v165
	v_max_f32_e32 v162, v162, v163
	v_add_f32_e32 v163, v91, v7
	v_and_or_b32 v163, v163, s18, 18
	v_min_f32_e32 v165, v152, v163
	v_max_f32_e32 v152, v152, v163
	v_min_f32_e32 v163, v153, v165
	v_max_f32_e32 v153, v153, v165
	v_min_f32_e32 v165, v154, v163
	v_max_f32_e32 v154, v154, v163
	v_min_f32_e32 v163, v155, v165
	v_max_f32_e32 v155, v155, v165
	v_min_f32_e32 v165, v156, v163
	v_max_f32_e32 v156, v156, v163
	v_min_f32_e32 v163, v157, v165
	v_max_f32_e32 v157, v157, v165
	v_min_f32_e32 v165, v158, v163
	v_max_f32_e32 v158, v158, v163
	v_min_f32_e32 v163, v159, v165
	v_max_f32_e32 v159, v159, v165
	v_min_f32_e32 v165, v160, v163
	v_max_f32_e32 v160, v160, v163
	v_min_f32_e32 v163, v161, v165
	v_max_f32_e32 v161, v161, v165
	v_max_f32_e32 v162, v162, v163
	v_add_f32_e32 v163, v91, v8
	v_and_or_b32 v163, v163, s18, 19
	v_min_f32_e32 v165, v154, v163
	v_max_f32_e32 v154, v154, v163
	v_min_f32_e32 v163, v155, v165
	v_max_f32_e32 v155, v155, v165
	v_min_f32_e32 v165, v156, v163
	v_max_f32_e32 v156, v156, v163
	v_min_f32_e32 v163, v157, v165
	v_max_f32_e32 v157, v157, v165
	v_min_f32_e32 v165, v158, v163
	v_max_f32_e32 v158, v158, v163
	v_min_f32_e32 v163, v159, v165
	v_max_f32_e32 v159, v159, v165
	v_min_f32_e32 v165, v160, v163
	v_max_f32_e32 v160, v160, v163
	v_min_f32_e32 v163, v161, v165
	v_max_f32_e32 v161, v161, v165
	v_max_f32_e32 v162, v162, v163
	v_add_f32_e32 v163, v91, v9
	v_and_or_b32 v163, v163, s18, 20
	v_min_f32_e32 v165, v156, v163
	v_max_f32_e32 v156, v156, v163
	v_min_f32_e32 v163, v157, v165
	v_max_f32_e32 v157, v157, v165
	v_min_f32_e32 v165, v158, v163
	v_max_f32_e32 v158, v158, v163
	v_min_f32_e32 v163, v159, v165
	v_max_f32_e32 v159, v159, v165
	v_min_f32_e32 v165, v160, v163
	v_max_f32_e32 v160, v160, v163
	v_min_f32_e32 v163, v161, v165
	v_max_f32_e32 v161, v161, v165
	v_max_f32_e32 v162, v162, v163
	v_add_f32_e32 v163, v91, v12
	v_and_or_b32 v163, v163, s18, 21
	v_min_f32_e32 v165, v158, v163
	v_max_f32_e32 v158, v158, v163
	v_min_f32_e32 v163, v159, v165
	v_max_f32_e32 v159, v159, v165
	v_min_f32_e32 v165, v160, v163
	v_max_f32_e32 v160, v160, v163
	v_min_f32_e32 v163, v161, v165
	v_max_f32_e32 v161, v161, v165
	v_max_f32_e32 v162, v162, v163
	v_add_f32_e32 v163, v91, v11
	v_and_or_b32 v163, v163, s18, 22
	v_min_f32_e32 v165, v160, v163
	v_max_f32_e32 v160, v160, v163
	v_min_f32_e32 v163, v161, v165
	v_max_f32_e32 v161, v161, v165
	v_max_f32_e32 v162, v162, v163
	v_add_f32_e32 v163, v91, v10
	v_and_or_b32 v163, v163, s18, 23
	v_max_f32_e32 v162, v162, v163
	v_add_f32_e32 v163, v87, v2
	v_and_or_b32 v163, v163, s18, 32
	v_min_f32_e32 v165, v149, v163
	v_max_f32_e32 v149, v149, v163
	v_min_f32_e32 v163, v150, v165
	v_max_f32_e32 v150, v150, v165
	v_min_f32_e32 v165, v151, v163
	v_max_f32_e32 v151, v151, v163
	v_min_f32_e32 v163, v152, v165
	v_max_f32_e32 v152, v152, v165
	v_min_f32_e32 v165, v153, v163
	v_max_f32_e32 v153, v153, v163
	v_min_f32_e32 v163, v154, v165
	v_max_f32_e32 v154, v154, v165
	v_min_f32_e32 v165, v155, v163
	v_max_f32_e32 v155, v155, v163
	v_min_f32_e32 v163, v156, v165
	v_max_f32_e32 v156, v156, v165
	v_min_f32_e32 v165, v157, v163
	v_max_f32_e32 v157, v157, v163
	v_min_f32_e32 v163, v158, v165
	v_max_f32_e32 v158, v158, v165
	v_min_f32_e32 v165, v159, v163
	v_max_f32_e32 v159, v159, v163
	v_min_f32_e32 v163, v160, v165
	v_max_f32_e32 v160, v160, v165
	v_min_f32_e32 v165, v161, v163
	v_max_f32_e32 v161, v161, v163
	v_max_f32_e32 v162, v162, v165
	v_add_f32_e32 v163, v87, v4
	v_and_or_b32 v163, v163, s18, 33
	v_min_f32_e32 v165, v152, v163
	v_max_f32_e32 v152, v152, v163
	v_min_f32_e32 v163, v153, v165
	v_max_f32_e32 v153, v153, v165
	v_min_f32_e32 v165, v154, v163
	v_max_f32_e32 v154, v154, v163
	v_min_f32_e32 v163, v155, v165
	v_max_f32_e32 v155, v155, v165
	v_min_f32_e32 v165, v156, v163
; DEV void ce(float& a, float& b) { float hi = fmaxf(a, b), lo = fminf(a, b); a = hi; b = lo; }
; DEV void phase_peer_score(const Params& p, int layer, int M, char* smem) {
;     ...
; #pragma unroll
;     for (int i = 0; i < 16; i++) R[i] = -3.0e38f;
; #pragma unroll
;     for (int i = 0; i < 16; i++)
; #pragma unroll
;       for (int j = 0; j < 16; j++)
;         if ((i + 1) * (j + 1) <= 16) {
;           float v = L0[i] + L1[j];
;           v = __uint_as_float((__float_as_uint(v) & ~255u) | (unsigned)(i * 16 + j));
; #pragma unroll
;           for (int t = 0; t < 16; t++)
;             if (t >= (i + 1) * (j + 1) - 1) ce(R[t], v);
;         }
	v_max_f32_e32 v156, v156, v163
	v_min_f32_e32 v163, v157, v165
	v_max_f32_e32 v157, v157, v165
	v_min_f32_e32 v165, v158, v163
	v_max_f32_e32 v158, v158, v163
	v_min_f32_e32 v163, v159, v165
	v_max_f32_e32 v159, v159, v165
	v_min_f32_e32 v165, v160, v163
	v_max_f32_e32 v160, v160, v163
	v_min_f32_e32 v163, v161, v165
	v_max_f32_e32 v161, v161, v165
	v_max_f32_e32 v162, v162, v163
	v_add_f32_e32 v163, v87, v7
	v_and_or_b32 v163, v163, s18, 34
	v_min_f32_e32 v165, v155, v163
	v_max_f32_e32 v155, v155, v163
	v_min_f32_e32 v163, v156, v165
	v_max_f32_e32 v156, v156, v165
	v_min_f32_e32 v165, v157, v163
	v_max_f32_e32 v157, v157, v163
	v_min_f32_e32 v163, v158, v165
	v_max_f32_e32 v158, v158, v165
	v_min_f32_e32 v165, v159, v163
	v_max_f32_e32 v159, v159, v163
	v_min_f32_e32 v163, v160, v165
	v_max_f32_e32 v160, v160, v165
	v_min_f32_e32 v165, v161, v163
	v_max_f32_e32 v161, v161, v163
	v_max_f32_e32 v162, v162, v165
	v_add_f32_e32 v163, v87, v8
	v_and_or_b32 v163, v163, s18, 35
	v_min_f32_e32 v165, v158, v163
	v_max_f32_e32 v158, v158, v163
	v_min_f32_e32 v163, v159, v165
	v_max_f32_e32 v159, v159, v165
	v_min_f32_e32 v165, v160, v163
	v_max_f32_e32 v160, v160, v163
	v_min_f32_e32 v163, v161, v165
	v_max_f32_e32 v161, v161, v165
	v_max_f32_e32 v162, v162, v163
	v_add_f32_e32 v163, v87, v9
	v_and_or_b32 v163, v163, s18, 36
	v_min_f32_e32 v165, v161, v163
	v_max_f32_e32 v161, v161, v163
	v_max_f32_e32 v162, v162, v165
	v_add_f32_e32 v163, v83, v2
	v_and_or_b32 v163, v163, s18, 48
	v_min_f32_e32 v165, v150, v163
	v_max_f32_e32 v150, v150, v163
	v_min_f32_e32 v163, v151, v165
	v_max_f32_e32 v151, v151, v165
	v_min_f32_e32 v165, v152, v163
	v_max_f32_e32 v152, v152, v163
	v_min_f32_e32 v163, v153, v165
	v_max_f32_e32 v153, v153, v165
	v_min_f32_e32 v165, v154, v163
	v_max_f32_e32 v154, v154, v163
	v_min_f32_e32 v163, v155, v165
	v_max_f32_e32 v155, v155, v165
	v_min_f32_e32 v165, v156, v163
	v_max_f32_e32 v156, v156, v163
	v_min_f32_e32 v163, v157, v165
	v_max_f32_e32 v157, v157, v165
	v_min_f32_e32 v165, v158, v163
	v_max_f32_e32 v158, v158, v163
	v_min_f32_e32 v163, v159, v165
	v_max_f32_e32 v159, v159, v165
	v_min_f32_e32 v165, v160, v163
	v_max_f32_e32 v160, v160, v163
	v_min_f32_e32 v163, v161, v165
	v_max_f32_e32 v161, v161, v165
	v_max_f32_e32 v162, v162, v163
	v_add_f32_e32 v163, v83, v4
	v_and_or_b32 v163, v163, s18, 49
	v_min_f32_e32 v165, v154, v163
	v_max_f32_e32 v154, v154, v163
	v_min_f32_e32 v163, v155, v165
	v_max_f32_e32 v155, v155, v165
	v_min_f32_e32 v165, v156, v163
	v_max_f32_e32 v156, v156, v163
	v_min_f32_e32 v163, v157, v165
	v_max_f32_e32 v157, v157, v165
	v_min_f32_e32 v165, v158, v163
	v_max_f32_e32 v158, v158, v163
	v_min_f32_e32 v163, v159, v165
	v_max_f32_e32 v159, v159, v165
	v_min_f32_e32 v165, v160, v163
	v_max_f32_e32 v160, v160, v163
	v_min_f32_e32 v163, v161, v165
	v_max_f32_e32 v161, v161, v165
	v_max_f32_e32 v162, v162, v163
	v_add_f32_e32 v163, v83, v7
	v_and_or_b32 v163, v163, s18, 50
	v_min_f32_e32 v165, v158, v163
	v_max_f32_e32 v158, v158, v163
	v_min_f32_e32 v163, v159, v165
	v_max_f32_e32 v159, v159, v165
	v_min_f32_e32 v165, v160, v163
	v_max_f32_e32 v160, v160, v163
	v_min_f32_e32 v163, v161, v165
	v_max_f32_e32 v161, v161, v165
	v_max_f32_e32 v162, v162, v163
	v_add_f32_e32 v163, v83, v8
	v_and_or_b32 v163, v163, s18, 51
	v_max_f32_e32 v162, v162, v163
	v_add_f32_e32 v163, v79, v2
	v_and_or_b32 v163, v163, s18, 64
	v_min_f32_e32 v165, v151, v163
	v_max_f32_e32 v151, v151, v163
	v_min_f32_e32 v163, v152, v165
	v_max_f32_e32 v152, v152, v165
	v_min_f32_e32 v165, v153, v163
	v_max_f32_e32 v153, v153, v163
	v_min_f32_e32 v163, v154, v165
	v_max_f32_e32 v154, v154, v165
	v_min_f32_e32 v165, v155, v163
	v_max_f32_e32 v155, v155, v163
	v_min_f32_e32 v163, v156, v165
	v_max_f32_e32 v156, v156, v165
	v_min_f32_e32 v165, v157, v163
	v_max_f32_e32 v157, v157, v163
	v_min_f32_e32 v163, v158, v165
	v_max_f32_e32 v158, v158, v165
	v_min_f32_e32 v165, v159, v163
	v_max_f32_e32 v159, v159, v163
	v_min_f32_e32 v163, v160, v165
	v_max_f32_e32 v160, v160, v165
	v_min_f32_e32 v165, v161, v163
	v_max_f32_e32 v161, v161, v163
	v_max_f32_e32 v162, v162, v165
	v_add_f32_e32 v163, v79, v4
	v_and_b32_e32 v163, 0xffffff00, v163
	v_or_b32_e32 v163, 0x41, v163
	v_min_f32_e32 v165, v156, v163
	v_max_f32_e32 v156, v156, v163
	v_min_f32_e32 v163, v157, v165
	v_max_f32_e32 v157, v157, v165
	v_min_f32_e32 v165, v158, v163
	v_max_f32_e32 v158, v158, v163
	v_min_f32_e32 v163, v159, v165
	v_max_f32_e32 v159, v159, v165
	v_min_f32_e32 v165, v160, v163
	v_max_f32_e32 v160, v160, v163
	v_min_f32_e32 v163, v161, v165
	v_max_f32_e32 v161, v161, v165
	v_max_f32_e32 v162, v162, v163
	v_add_f32_e32 v163, v79, v7
	v_and_b32_e32 v163, 0xffffff00, v163
	v_or_b32_e32 v163, 0x42, v163
	v_min_f32_e32 v165, v161, v163
	v_max_f32_e32 v161, v161, v163
	v_max_f32_e32 v162, v162, v165
	v_add_f32_e32 v163, v75, v2
	v_and_b32_e32 v163, 0xffffff00, v163
	v_or_b32_e32 v163, 0x50, v163
	v_min_f32_e32 v165, v152, v163
	v_max_f32_e32 v152, v152, v163
	v_min_f32_e32 v163, v153, v165
	v_max_f32_e32 v153, v153, v165
	v_min_f32_e32 v165, v154, v163
	v_max_f32_e32 v154, v154, v163
	v_min_f32_e32 v163, v155, v165
	v_max_f32_e32 v155, v155, v165
	v_min_f32_e32 v165, v156, v163
	v_max_f32_e32 v156, v156, v163
	v_min_f32_e32 v163, v157, v165
	v_max_f32_e32 v157, v157, v165
	v_min_f32_e32 v165, v158, v163
	v_max_f32_e32 v158, v158, v163
	v_min_f32_e32 v163, v159, v165
	v_max_f32_e32 v159, v159, v165
	v_min_f32_e32 v165, v160, v163
	v_max_f32_e32 v160, v160, v163
	v_min_f32_e32 v163, v161, v165
	v_max_f32_e32 v161, v161, v165
	v_max_f32_e32 v162, v162, v163
; DEV void ce(float& a, float& b) { float hi = fmaxf(a, b), lo = fminf(a, b); a = hi; b = lo; }
; DEV void phase_peer_score(const Params& p, int layer, int M, char* smem) {
;     ...
; #pragma unroll
;     for (int i = 0; i < 16; i++) R[i] = -3.0e38f;
; #pragma unroll
;     for (int i = 0; i < 16; i++)
; #pragma unroll
;       for (int j = 0; j < 16; j++)
;         if ((i + 1) * (j + 1) <= 16) {
;           float v = L0[i] + L1[j];
;           v = __uint_as_float((__float_as_uint(v) & ~255u) | (unsigned)(i * 16 + j));
; #pragma unroll
;           for (int t = 0; t < 16; t++)
;             if (t >= (i + 1) * (j + 1) - 1) ce(R[t], v);
;         }
	v_add_f32_e32 v163, v75, v4
	v_and_b32_e32 v163, 0xffffff00, v163
	v_or_b32_e32 v163, 0x51, v163
	v_min_f32_e32 v165, v158, v163
	v_max_f32_e32 v158, v158, v163
	v_min_f32_e32 v163, v159, v165
	v_max_f32_e32 v159, v159, v165
	v_min_f32_e32 v165, v160, v163
	v_max_f32_e32 v160, v160, v163
	v_min_f32_e32 v163, v161, v165
	v_max_f32_e32 v161, v161, v165
	v_max_f32_e32 v162, v162, v163
	v_add_f32_e32 v163, v71, v2
	v_and_b32_e32 v163, 0xffffff00, v163
	v_or_b32_e32 v163, 0x60, v163
	v_min_f32_e32 v165, v153, v163
	v_max_f32_e32 v153, v153, v163
	v_min_f32_e32 v163, v154, v165
	v_max_f32_e32 v154, v154, v165
	v_min_f32_e32 v165, v155, v163
	v_max_f32_e32 v155, v155, v163
	v_min_f32_e32 v163, v156, v165
	v_max_f32_e32 v156, v156, v165
	v_min_f32_e32 v165, v157, v163
	v_max_f32_e32 v157, v157, v163
	v_min_f32_e32 v163, v158, v165
	v_max_f32_e32 v158, v158, v165
	v_min_f32_e32 v165, v159, v163
	v_max_f32_e32 v159, v159, v163
	v_min_f32_e32 v163, v160, v165
	v_max_f32_e32 v160, v160, v165
	v_min_f32_e32 v165, v161, v163
	v_max_f32_e32 v161, v161, v163
	v_max_f32_e32 v162, v162, v165
	v_add_f32_e32 v163, v71, v4
	v_and_b32_e32 v163, 0xffffff00, v163
	v_or_b32_e32 v163, 0x61, v163
	v_min_f32_e32 v165, v160, v163
	v_max_f32_e32 v160, v160, v163
	v_min_f32_e32 v163, v161, v165
	v_max_f32_e32 v161, v161, v165
	v_max_f32_e32 v162, v162, v163
	v_add_f32_e32 v163, v63, v2
	v_and_b32_e32 v163, 0xffffff00, v163
	v_or_b32_e32 v163, 0x70, v163
	v_min_f32_e32 v165, v154, v163
	v_max_f32_e32 v154, v154, v163
	v_min_f32_e32 v163, v155, v165
	v_max_f32_e32 v155, v155, v165
	v_min_f32_e32 v165, v156, v163
	v_max_f32_e32 v156, v156, v163
	v_min_f32_e32 v163, v157, v165
	v_max_f32_e32 v157, v157, v165
	v_min_f32_e32 v165, v158, v163
	v_max_f32_e32 v158, v158, v163
	v_min_f32_e32 v163, v159, v165
	v_max_f32_e32 v159, v159, v165
	v_min_f32_e32 v165, v160, v163
	v_max_f32_e32 v160, v160, v163
	v_min_f32_e32 v163, v161, v165
	v_max_f32_e32 v161, v161, v165
	v_max_f32_e32 v162, v162, v163
	v_add_f32_e32 v163, v63, v4
	v_and_b32_e32 v163, 0xffffff00, v163
	v_or_b32_e32 v163, 0x71, v163
	v_max_f32_e32 v162, v162, v163
	v_add_f32_e32 v163, v67, v2
	v_and_b32_e32 v163, 0xffffff00, v163
	v_or_b32_e32 v163, 0x80, v163
	v_min_f32_e32 v165, v155, v163
	v_max_f32_e32 v155, v155, v163
	v_min_f32_e32 v163, v156, v165
	v_max_f32_e32 v156, v156, v165
	v_min_f32_e32 v165, v157, v163
	v_max_f32_e32 v157, v157, v163
	v_min_f32_e32 v163, v158, v165
	v_max_f32_e32 v158, v158, v165
	v_min_f32_e32 v165, v159, v163
	v_max_f32_e32 v159, v159, v163
	v_min_f32_e32 v163, v160, v165
	v_max_f32_e32 v160, v160, v165
	v_min_f32_e32 v165, v161, v163
	v_max_f32_e32 v161, v161, v163
	v_max_f32_e32 v162, v162, v165
	v_add_f32_e32 v163, v59, v2
	v_and_b32_e32 v163, 0xffffff00, v163
	v_or_b32_e32 v163, 0x90, v163
	v_min_f32_e32 v165, v156, v163
	v_max_f32_e32 v156, v156, v163
	v_min_f32_e32 v163, v157, v165
	v_max_f32_e32 v157, v157, v165
	v_min_f32_e32 v165, v158, v163
	v_max_f32_e32 v158, v158, v163
	v_min_f32_e32 v163, v159, v165
	v_max_f32_e32 v159, v159, v165
	v_min_f32_e32 v165, v160, v163
	v_max_f32_e32 v160, v160, v163
	v_min_f32_e32 v163, v161, v165
	v_max_f32_e32 v161, v161, v165
	v_max_f32_e32 v162, v162, v163
	v_add_f32_e32 v163, v55, v2
	v_and_b32_e32 v163, 0xffffff00, v163
	v_or_b32_e32 v163, 0xa0, v163
	v_min_f32_e32 v165, v157, v163
	v_max_f32_e32 v157, v157, v163
	v_min_f32_e32 v163, v158, v165
	v_max_f32_e32 v158, v158, v165
	v_min_f32_e32 v165, v159, v163
	v_max_f32_e32 v159, v159, v163
	v_min_f32_e32 v163, v160, v165
	v_max_f32_e32 v160, v160, v165
	v_min_f32_e32 v165, v161, v163
	v_max_f32_e32 v161, v161, v163
	v_max_f32_e32 v162, v162, v165
	v_add_f32_e32 v163, v47, v2
	v_and_b32_e32 v163, 0xffffff00, v163
	v_or_b32_e32 v163, 0xb0, v163
	v_min_f32_e32 v165, v158, v163
	v_max_f32_e32 v158, v158, v163
	v_min_f32_e32 v163, v159, v165
	v_max_f32_e32 v159, v159, v165
	v_min_f32_e32 v165, v160, v163
	v_max_f32_e32 v160, v160, v163
	v_min_f32_e32 v163, v161, v165
	v_max_f32_e32 v161, v161, v165
	v_max_f32_e32 v162, v162, v163
	v_add_f32_e32 v163, v51, v2
	v_and_b32_e32 v163, 0xffffff00, v163
	v_or_b32_e32 v163, 0xc0, v163
	v_min_f32_e32 v165, v159, v163
	v_max_f32_e32 v159, v159, v163
	v_min_f32_e32 v163, v160, v165
	v_max_f32_e32 v160, v160, v165
	v_min_f32_e32 v165, v161, v163
	v_max_f32_e32 v161, v161, v163
	v_max_f32_e32 v162, v162, v165
	v_add_f32_e32 v163, v39, v2
	v_and_b32_e32 v163, 0xffffff00, v163
	v_or_b32_e32 v163, 0xd0, v163
	v_min_f32_e32 v165, v160, v163
	v_max_f32_e32 v160, v160, v163
	v_min_f32_e32 v163, v161, v165
	v_max_f32_e32 v161, v161, v165
	v_max_f32_e32 v162, v162, v163
	v_add_f32_e32 v163, v43, v2
	v_and_b32_e32 v163, 0xffffff00, v163
	v_or_b32_e32 v163, 0xe0, v163
	v_min_f32_e32 v165, v161, v163
	v_max_f32_e32 v161, v161, v163
	v_max_f32_e32 v162, v162, v165
	v_add_f32_e32 v163, v0, v2
	v_and_b32_e32 v163, 0xffffff00, v163
	v_or_b32_e32 v163, 0xf0, v163
	v_max_f32_e32 v162, v162, v163
; DEV void phase_peer_score(const Params& p, int layer, int M, char* smem) {
;     ...
;     float ev[16]; float sum = 0.f;
; #pragma unroll
;     for (int t = 0; t < 16; t++) { ev[t] = __expf(R[t] - R[0]); sum += ev[t]; }
;     const float inv = 1.f / sum;
;     int eid[16];
; #pragma unroll
;     for (int t = 0; t < 16; t++) {
;       unsigned code = __float_as_uint(R[t]) & 255u;
;       eid[t] = (int)tab[code >> 4] * 128 + (int)tab[16 + (code & 15u)];
;     }
.Lmed3_ok_bb_637:
	s_lshl_b32 s18, s16, 3
	s_andn2_b32 s18, s18, 63
	v_add_u32_e32 v18, s18, v117
	s_movk_i32 s18, 0xff00
	v_sub_f32_e32 v5, v164, v148
	v_mul_f32_e32 v5, 0x3fb8aa3b, v5
	v_exp_f32_e32 v101, v5
	v_sub_f32_e32 v5, v149, v148
	v_mul_f32_e32 v5, 0x3fb8aa3b, v5
	v_exp_f32_e32 v104, v5
	v_sub_f32_e32 v5, v150, v148
	v_mul_f32_e32 v5, 0x3fb8aa3b, v5
	v_exp_f32_e32 v105, v5
	v_sub_f32_e32 v5, v151, v148
	v_mul_f32_e32 v5, 0x3fb8aa3b, v5
	v_exp_f32_e32 v102, v5
	v_sub_f32_e32 v5, v152, v148
	v_mul_f32_e32 v5, 0x3fb8aa3b, v5
	v_exp_f32_e32 v103, v5
	v_sub_f32_e32 v5, v153, v148
	v_mul_f32_e32 v5, 0x3fb8aa3b, v5
	v_exp_f32_e32 v110, v5
	v_sub_f32_e32 v5, v154, v148
	v_sub_f32_e32 v3, v148, v148
	v_mul_f32_e32 v5, 0x3fb8aa3b, v5
	v_mul_f32_e32 v3, 0x3fb8aa3b, v3
	v_exp_f32_e32 v111, v5
	v_sub_f32_e32 v5, v155, v148
	v_exp_f32_e32 v100, v3
	v_mul_f32_e32 v5, 0x3fb8aa3b, v5
	v_exp_f32_e32 v112, v5
	v_sub_f32_e32 v5, v156, v148
	v_mul_f32_e32 v5, 0x3fb8aa3b, v5
	v_exp_f32_e32 v113, v5
	v_sub_f32_e32 v5, v157, v148
	v_add_f32_e32 v3, 0, v100
	v_mul_f32_e32 v5, 0x3fb8aa3b, v5
	v_add_f32_e32 v3, v3, v101
	v_exp_f32_e32 v114, v5
	v_sub_f32_e32 v5, v158, v148
	v_add_f32_e32 v3, v3, v104
	v_mul_f32_e32 v5, 0x3fb8aa3b, v5
	v_add_f32_e32 v3, v3, v105
	v_exp_f32_e32 v115, v5
	v_sub_f32_e32 v5, v159, v148
	v_add_f32_e32 v3, v3, v102
	v_mul_f32_e32 v5, 0x3fb8aa3b, v5
	v_add_f32_e32 v3, v3, v103
	v_exp_f32_e32 v106, v5
	v_sub_f32_e32 v5, v160, v148
	v_add_f32_e32 v3, v3, v110
	v_mul_f32_e32 v5, 0x3fb8aa3b, v5
	v_add_f32_e32 v3, v3, v111
	v_exp_f32_e32 v107, v5
	v_sub_f32_e32 v5, v161, v148
	v_add_f32_e32 v3, v3, v112
	v_mul_f32_e32 v5, 0x3fb8aa3b, v5
	v_add_f32_e32 v3, v3, v113
	v_exp_f32_e32 v108, v5
	v_sub_f32_e32 v5, v162, v148
	v_add_f32_e32 v3, v3, v114
	v_mul_f32_e32 v5, 0x3fb8aa3b, v5
	v_add_f32_e32 v3, v3, v115
	v_exp_f32_e32 v109, v5
	v_add_f32_e32 v3, v3, v106
	v_add_f32_e32 v3, v3, v107
	v_add_f32_e32 v3, v3, v108
	v_add_f32_e32 v3, v3, v109
	v_div_scale_f32 v5, s[18:19], v3, v3, 1.0
	v_rcp_f32_e32 v6, v5
	v_ashrrev_i32_e32 v19, 31, v18
	s_lshl_b32 s52, s17, 6
	s_mov_b32 s17, 0x10000
	v_fma_f32 v17, -v5, v6, 1.0
	v_fmac_f32_e32 v6, v17, v6
	v_div_scale_f32 v17, vcc, 1.0, v3, 1.0
	v_mul_f32_e32 v20, v17, v6
	v_fma_f32 v21, -v5, v20, v17
	v_fmac_f32_e32 v20, v21, v6
	v_fma_f32 v5, -v5, v20, v17
	v_div_fmas_f32 v5, v5, v6, v20
	v_div_fixup_f32 v116, v5, v3, 1.0
	v_bfe_u32 v3, v162, 4, 4
	v_and_b32_e32 v2, 15, v162
	v_and_b32_e32 v17, 15, v154
	v_add_u32_e32 v3, v138, v3
	v_add_u32_e32 v2, v138, v2
	v_add_u32_e32 v17, v138, v17
	ds_read_u8 v3, v3
	ds_read_u8 v17, v17 offset:16
	ds_read_u8 v2, v2 offset:16
	v_and_b32_e32 v6, 15, v159
	v_add_u32_e32 v6, v138, v6
	ds_read_u8 v6, v6 offset:16
	v_lshlrev_b64 v[120:121], 9, v[18:19]
	s_waitcnt lgkmcnt(1)
	v_lshl_add_u32 v5, v3, 7, v2
	v_bfe_u32 v2, v161, 4, 4
	v_and_b32_e32 v3, 15, v161
	v_add_u32_e32 v2, v138, v2
	v_add_u32_e32 v3, v138, v3
	ds_read_u8 v2, v2
	ds_read_u8 v3, v3 offset:16
	v_lshl_add_u64 v[18:19], s[2:3], 0, v[120:121]
	v_lshl_add_u64 v[118:119], v[18:19], 0, s[52:53]
	v_lshl_add_u64 v[120:121], s[0:1], 0, v[120:121]
	v_lshl_add_u64 v[120:121], v[120:121], 0, s[52:53]
	s_waitcnt lgkmcnt(0)
	v_lshl_add_u32 v4, v2, 7, v3
	v_bfe_u32 v2, v160, 4, 4
	v_and_b32_e32 v3, 15, v160
	v_add_u32_e32 v2, v138, v2
	v_add_u32_e32 v3, v138, v3
	ds_read_u8 v2, v2
	ds_read_u8 v3, v3 offset:16
	v_and_b32_e32 v7, 15, v158
	v_add_u32_e32 v7, v138, v7
	ds_read_u8 v7, v7 offset:16
	s_waitcnt lgkmcnt(1)
	v_lshl_add_u32 v3, v2, 7, v3
	v_bfe_u32 v2, v159, 4, 4
	v_add_u32_e32 v2, v138, v2
	ds_read_u8 v2, v2
	s_waitcnt lgkmcnt(0)
	v_lshl_add_u32 v2, v2, 7, v6
	v_bfe_u32 v6, v158, 4, 4
	v_add_u32_e32 v6, v138, v6
	ds_read_u8 v6, v6
	s_waitcnt lgkmcnt(0)
	v_lshl_add_u32 v9, v6, 7, v7
	v_bfe_u32 v6, v157, 4, 4
	v_and_b32_e32 v7, 15, v157
	v_add_u32_e32 v6, v138, v6
	v_add_u32_e32 v7, v138, v7
	ds_read_u8 v6, v6
	ds_read_u8 v7, v7 offset:16
	s_waitcnt lgkmcnt(0)
	v_lshl_add_u32 v8, v6, 7, v7
	v_bfe_u32 v6, v156, 4, 4
	v_and_b32_e32 v7, 15, v156
	v_add_u32_e32 v6, v138, v6
	v_add_u32_e32 v7, v138, v7
	ds_read_u8 v6, v6
	ds_read_u8 v7, v7 offset:16
	s_waitcnt lgkmcnt(0)
	v_lshl_add_u32 v7, v6, 7, v7
	v_bfe_u32 v6, v155, 4, 4
	v_and_b32_e32 v13, 15, v155
	v_add_u32_e32 v6, v138, v6
	v_add_u32_e32 v13, v138, v13
	ds_read_u8 v6, v6
	ds_read_u8 v13, v13 offset:16
	s_waitcnt lgkmcnt(0)
	v_lshl_add_u32 v6, v6, 7, v13
	v_bfe_u32 v13, v154, 4, 4
	v_add_u32_e32 v13, v138, v13
	ds_read_u8 v13, v13
	s_waitcnt lgkmcnt(0)
	v_lshl_add_u32 v13, v13, 7, v17
	v_bfe_u32 v17, v153, 4, 4
	v_and_b32_e32 v12, 15, v153
	v_add_u32_e32 v17, v138, v17
	v_add_u32_e32 v12, v138, v12
	ds_read_u8 v17, v17
	ds_read_u8 v12, v12 offset:16
	s_waitcnt lgkmcnt(0)
	v_lshl_add_u32 v12, v17, 7, v12
	v_bfe_u32 v17, v152, 4, 4
	v_and_b32_e32 v11, 15, v152
	v_add_u32_e32 v17, v138, v17
	v_add_u32_e32 v11, v138, v11
	ds_read_u8 v17, v17
	ds_read_u8 v11, v11 offset:16
	s_waitcnt lgkmcnt(0)
	v_lshl_add_u32 v11, v17, 7, v11
	v_bfe_u32 v17, v151, 4, 4
	v_and_b32_e32 v10, 15, v151
	v_add_u32_e32 v17, v138, v17
	v_add_u32_e32 v10, v138, v10
	ds_read_u8 v17, v17
	ds_read_u8 v10, v10 offset:16
	s_waitcnt lgkmcnt(0)
	v_lshl_add_u32 v10, v17, 7, v10
	v_bfe_u32 v17, v150, 4, 4
	v_and_b32_e32 v16, 15, v150
	v_add_u32_e32 v17, v138, v17
	v_add_u32_e32 v16, v138, v16
	ds_read_u8 v17, v17
	ds_read_u8 v16, v16 offset:16
	s_waitcnt lgkmcnt(0)
	v_lshl_add_u32 v17, v17, 7, v16
	v_bfe_u32 v16, v149, 4, 4
	v_and_b32_e32 v15, 15, v149
	v_add_u32_e32 v16, v138, v16
	v_add_u32_e32 v15, v138, v15
	ds_read_u8 v16, v16
	ds_read_u8 v15, v15 offset:16
	s_waitcnt lgkmcnt(0)
; DEV void phase_peer_score(const Params& p, int layer, int M, char* smem) {
;     ...
;     int eid[16];
; #pragma unroll
;     for (int t = 0; t < 16; t++) {
;       unsigned code = __float_as_uint(R[t]) & 255u;
;       eid[t] = (int)tab[code >> 4] * 128 + (int)tab[16 + (code & 15u)];
;     }
;     if (quad == 0) {
;       int* eo = EIDX + (size_t)m * 128 + h * 16;
;       float* go = GATE + (size_t)m * 128 + h * 16;
;       float* uo = go + (size_t)MT * 128;
;       float us[16], vs[16];
; #pragma unroll
;       for (int t = 0; t < 16; t++) { us[t] = USC[eid[t]]; vs[t] = USC[16384 + eid[t]]; }
; #pragma unroll
;       for (int t = 0; t < 16; t += 4) {
;         *(int4*)(eo + t) = make_int4(eid[t], eid[t + 1], eid[t + 2], eid[t + 3]);
;         *(float4*)(go + t) = make_float4(ev[t] * inv * vs[t], ev[t + 1] * inv * vs[t + 1], ev[t + 2] * inv * vs[t + 2], ev[t + 3] * inv * vs[t + 3]);
;         *(float4*)(uo + t) = make_float4(us[t], us[t + 1], us[t + 2], us[t + 3]);
;       }
	v_lshl_add_u32 v16, v16, 7, v15
	v_bfe_u32 v15, v164, 4, 4
	v_and_b32_e32 v14, 15, v164
	v_add_u32_e32 v15, v138, v15
	v_add_u32_e32 v14, v138, v14
	ds_read_u8 v15, v15
	ds_read_u8 v14, v14 offset:16
	s_waitcnt lgkmcnt(0)
	v_lshl_add_u32 v15, v15, 7, v14
	v_bfe_u32 v14, v148, 4, 4
	v_and_b32_e32 v0, 15, v148
	v_add_u32_e32 v14, v138, v14
	v_add_u32_e32 v0, v138, v0
	ds_read_u8 v14, v14
	ds_read_u8 v0, v0 offset:16
	s_waitcnt lgkmcnt(0)
	v_lshl_add_u32 v14, v14, 7, v0
	v_lshlrev_b32_e32 v0, 2, v14
	v_lshl_add_u64 v[20:21], s[6:7], 0, v[0:1]
	v_add_co_u32_e32 v20, vcc, s17, v20
	global_load_dword v18, v0, s[6:7]
	s_nop 0
	v_addc_co_u32_e32 v21, vcc, 0, v21, vcc
	global_load_dword v122, v[20:21], off
	v_lshlrev_b32_e32 v0, 2, v15
	v_lshl_add_u64 v[20:21], s[6:7], 0, v[0:1]
	v_add_co_u32_e32 v20, vcc, s17, v20
	global_load_dword v19, v0, s[6:7]
	s_nop 0
	v_addc_co_u32_e32 v21, vcc, 0, v21, vcc
	global_load_dword v123, v[20:21], off
	v_lshlrev_b32_e32 v0, 2, v16
	v_lshl_add_u64 v[22:23], s[6:7], 0, v[0:1]
	v_add_co_u32_e32 v22, vcc, s17, v22
	global_load_dword v20, v0, s[6:7]
	s_nop 0
	v_addc_co_u32_e32 v23, vcc, 0, v23, vcc
	global_load_dword v126, v[22:23], off
	v_lshlrev_b32_e32 v0, 2, v17
	v_lshl_add_u64 v[22:23], s[6:7], 0, v[0:1]
	v_add_co_u32_e32 v22, vcc, s17, v22
	global_load_dword v21, v0, s[6:7]
	s_nop 0
	v_addc_co_u32_e32 v23, vcc, 0, v23, vcc
	global_load_dword v127, v[22:23], off
	v_lshlrev_b32_e32 v0, 2, v10
	v_lshl_add_u64 v[24:25], s[6:7], 0, v[0:1]
	v_add_co_u32_e32 v24, vcc, s17, v24
	global_load_dword v22, v0, s[6:7]
	s_nop 0
	v_addc_co_u32_e32 v25, vcc, 0, v25, vcc
	global_load_dword v124, v[24:25], off
	v_lshlrev_b32_e32 v0, 2, v11
	v_lshl_add_u64 v[24:25], s[6:7], 0, v[0:1]
	v_add_co_u32_e32 v24, vcc, s17, v24
	global_load_dword v23, v0, s[6:7]
	s_nop 0
	v_addc_co_u32_e32 v25, vcc, 0, v25, vcc
	global_load_dword v125, v[24:25], off
	v_lshlrev_b32_e32 v0, 2, v12
	v_lshl_add_u64 v[26:27], s[6:7], 0, v[0:1]
	v_add_co_u32_e32 v26, vcc, s17, v26
	global_load_dword v24, v0, s[6:7]
	s_nop 0
	v_addc_co_u32_e32 v27, vcc, 0, v27, vcc
	global_load_dword v128, v[26:27], off
	v_lshlrev_b32_e32 v0, 2, v13
	v_lshl_add_u64 v[26:27], s[6:7], 0, v[0:1]
	v_add_co_u32_e32 v26, vcc, s17, v26
	global_load_dword v25, v0, s[6:7]
	s_nop 0
	v_addc_co_u32_e32 v27, vcc, 0, v27, vcc
	global_load_dword v129, v[26:27], off
	v_lshlrev_b32_e32 v0, 2, v6
	v_lshl_add_u64 v[28:29], s[6:7], 0, v[0:1]
	v_add_co_u32_e32 v28, vcc, s17, v28
	global_load_dword v26, v0, s[6:7]
	s_nop 0
	v_addc_co_u32_e32 v29, vcc, 0, v29, vcc
	global_load_dword v130, v[28:29], off
	v_lshlrev_b32_e32 v0, 2, v7
	v_lshl_add_u64 v[28:29], s[6:7], 0, v[0:1]
	v_add_co_u32_e32 v28, vcc, s17, v28
	global_load_dword v27, v0, s[6:7]
	s_nop 0
	v_addc_co_u32_e32 v29, vcc, 0, v29, vcc
	global_load_dword v131, v[28:29], off
	v_lshlrev_b32_e32 v0, 2, v8
	v_lshl_add_u64 v[30:31], s[6:7], 0, v[0:1]
	v_add_co_u32_e32 v30, vcc, s17, v30
	global_load_dword v28, v0, s[6:7]
	s_nop 0
	v_addc_co_u32_e32 v31, vcc, 0, v31, vcc
	global_load_dword v132, v[30:31], off
	v_lshlrev_b32_e32 v0, 2, v9
	v_lshl_add_u64 v[30:31], s[6:7], 0, v[0:1]
	v_add_co_u32_e32 v30, vcc, s17, v30
	global_load_dword v29, v0, s[6:7]
	s_nop 0
	v_addc_co_u32_e32 v31, vcc, 0, v31, vcc
	global_load_dword v133, v[30:31], off
	v_lshlrev_b32_e32 v0, 2, v2
	v_lshl_add_u64 v[32:33], s[6:7], 0, v[0:1]
	v_add_co_u32_e32 v32, vcc, s17, v32
	global_load_dword v30, v0, s[6:7]
	s_nop 0
	v_addc_co_u32_e32 v33, vcc, 0, v33, vcc
	global_load_dword v134, v[32:33], off
	v_lshlrev_b32_e32 v0, 2, v3
	v_lshl_add_u64 v[32:33], s[6:7], 0, v[0:1]
	v_add_co_u32_e32 v32, vcc, s17, v32
	global_load_dword v31, v0, s[6:7]
	s_nop 0
	v_addc_co_u32_e32 v33, vcc, 0, v33, vcc
	global_load_dword v135, v[32:33], off
	v_lshlrev_b32_e32 v0, 2, v4
	v_lshl_add_u64 v[136:137], s[6:7], 0, v[0:1]
	v_add_co_u32_e32 v136, vcc, s17, v136
	global_load_dword v32, v0, s[6:7]
	s_nop 0
	v_addc_co_u32_e32 v137, vcc, 0, v137, vcc
	global_load_dword v136, v[136:137], off
	v_lshlrev_b32_e32 v0, 2, v5
	v_lshl_add_u64 v[140:141], s[6:7], 0, v[0:1]
	v_add_co_u32_e32 v140, vcc, s17, v140
	global_load_dword v33, v0, s[6:7]
	s_nop 0
	v_addc_co_u32_e32 v141, vcc, 0, v141, vcc
	global_load_dword v137, v[140:141], off
	s_mov_b32 s17, 0x840000
	global_store_dwordx4 v[120:121], v[14:17], off
	s_nop 1
	v_pk_mul_f32 v[14:15], v[100:101], v[116:117] op_sel_hi:[1,0]
	v_pk_mul_f32 v[16:17], v[104:105], v[116:117] op_sel_hi:[1,0]
	s_waitcnt vmcnt(29)
	v_pk_mul_f32 v[14:15], v[14:15], v[122:123]
	s_waitcnt vmcnt(25)
	v_pk_mul_f32 v[16:17], v[16:17], v[126:127]
	global_store_dwordx4 v[118:119], v[14:17], off
	s_nop 1
	v_add_co_u32_e32 v14, vcc, s17, v118
	s_nop 1
	v_addc_co_u32_e32 v15, vcc, 0, v119, vcc
	global_store_dwordx4 v[14:15], v[18:21], off
	global_store_dwordx4 v[120:121], v[10:13], off offset:16
	s_nop 1
	v_pk_mul_f32 v[10:11], v[102:103], v[116:117] op_sel_hi:[1,0]
	v_pk_mul_f32 v[12:13], v[110:111], v[116:117] op_sel_hi:[1,0]
	s_waitcnt vmcnt(24)
	v_pk_mul_f32 v[10:11], v[10:11], v[124:125]
	s_waitcnt vmcnt(20)
	v_pk_mul_f32 v[12:13], v[12:13], v[128:129]
	global_store_dwordx4 v[118:119], v[10:13], off offset:16
	global_store_dwordx4 v[14:15], v[22:25], off offset:16
	global_store_dwordx4 v[120:121], v[6:9], off offset:32
	s_nop 1
	v_pk_mul_f32 v[6:7], v[112:113], v[116:117] op_sel_hi:[1,0]
	v_pk_mul_f32 v[8:9], v[114:115], v[116:117] op_sel_hi:[1,0]
	s_waitcnt vmcnt(19)
	v_pk_mul_f32 v[6:7], v[6:7], v[130:131]
	s_waitcnt vmcnt(15)
	v_pk_mul_f32 v[8:9], v[8:9], v[132:133]
	global_store_dwordx4 v[118:119], v[6:9], off offset:32
	global_store_dwordx4 v[14:15], v[26:29], off offset:32
	global_store_dwordx4 v[120:121], v[2:5], off offset:48
	s_nop 1
	v_pk_mul_f32 v[2:3], v[106:107], v[116:117] op_sel_hi:[1,0]
	v_pk_mul_f32 v[4:5], v[108:109], v[116:117] op_sel_hi:[1,0]
	s_waitcnt vmcnt(14)
	v_pk_mul_f32 v[2:3], v[2:3], v[134:135]
	s_waitcnt vmcnt(10)
	v_pk_mul_f32 v[4:5], v[4:5], v[136:137]
	global_store_dwordx4 v[118:119], v[2:5], off offset:48
	global_store_dwordx4 v[14:15], v[30:33], off offset:48
	s_branch .LBB0_627
